# gemm_in and the 256x256 gemm_out: cross-tile prefetch of the next tile's first k-tile (A and B, 8 x 16 B per thread) into dead fragment registers during the epilogue
# speedup vs baseline: 1.0038x; 1.0038x over previous
.LBB0_235:
	s_and_b32 s1, 0xffff, s1
	s_lshr_b32 s1, 0x88, s1
	s_mul_i32 s6, s1, 11
	s_cmp_ge_i32 s4, s6
	s_cbranch_scc1 .LBB0_249
	v_readlane_b32 s82, v253, 38
	v_readlane_b32 s83, v253, 39
	s_mul_i32 s80, s74, 0x580000
	s_add_u32 s80, s50, s80
	s_addc_u32 s81, s51, 0
	s_mov_b32 s79, 0
	v_ashrrev_i32_e32 v1, 6, v0
	v_lshrrev_b32_e32 v3, 30, v1
	v_add_u32_e32 v3, v1, v3
	s_mul_i32 s7, s0, s1
	s_mul_i32 s0, s74, 0x580000
	v_ashrrev_i32_e32 v3, 2, v3
	s_add_u32 s0, s50, s0
	s_waitcnt vmcnt(6)
	v_and_b32_e32 v4, 7, v0
	v_mul_i32_i24_e32 v8, 4, v3
	s_addc_u32 s1, s51, 0
	v_and_b32_e32 v2, 31, v0
	v_lshlrev_b32_e32 v128, 4, v4
	v_sub_u32_e32 v9, v1, v8
	v_lshlrev_b32_e32 v153, 7, v3
	v_ashrrev_i32_e32 v152, 3, v0
	v_bfe_u32 v6, v0, 5, 1
	v_readlane_b32 s8, v253, 38
	v_lshl_add_u64 v[176:177], s[0:1], 0, v[128:129]
	s_movk_i32 s0, 0x90
	v_or_b32_e32 v3, v153, v2
	v_lshl_or_b32 v9, v9, 6, v2
	v_readlane_b32 s9, v253, 39
	v_mul_lo_u32 v7, v152, s0
	v_mul_lo_u32 v3, v3, s0
	v_lshlrev_b32_e32 v10, 4, v6
	v_mul_lo_u32 v9, v9, s0
	v_readlane_b32 s0, v255, 15
	v_readlane_b32 s1, v255, 16
	v_lshl_add_u64 v[250:251], s[8:9], 0, v[128:129]
	v_add3_u32 v154, 0, v3, v10
	v_add_u32_e32 v13, s1, v7
	v_readlane_b32 s8, v255, 17
	v_add3_u32 v155, s0, v3, v10
	v_add_u32_e32 v3, s1, v9
	s_movk_i32 s1, 0x1200
	v_add_u32_e32 v14, s8, v7
	v_readlane_b32 s8, v255, 18
	v_mul_lo_u32 v1, v1, s1
	v_lshlrev_b32_e32 v5, 3, v4
	v_add_u32_e32 v12, s0, v7
	v_add_u32_e32 v15, s8, v7
	v_readlane_b32 s8, v255, 19
	v_add_u32_e32 v1, s0, v1
	v_lshlrev_b32_e32 v2, 1, v2
	v_mul_u32_u24_e32 v6, 0x240, v6
	v_bfe_u32 v157, v0, 3, 3
	s_movk_i32 s0, 0xffc0
	v_add_u32_e32 v4, 0, v128
	v_add_u32_e32 v11, 0, v9
	s_waitcnt vmcnt(3)
	v_add_u32_e32 v16, s8, v7
	v_add_u32_e32 v9, 0, v7
	v_add_u32_e32 v17, v1, v128
	v_add3_u32 v156, v1, v2, v6
	v_mul_u32_u24_e32 v1, 0x90, v157
	v_and_or_b32 v0, v0, s0, v5
	v_lshlrev_b32_e32 v2, 6, v8
	v_mov_b32_e32 v180, 0x2000
	v_or_b32_e32 v171, 8, v157
	v_or_b32_e32 v252, 16, v157
	v_or_b32_e32 v181, 24, v157
	v_sub_u32_e32 v179, v0, v2
	s_lshl_b32 s8, s4, 8
	s_lshl_b32 s9, s5, 8
	v_add_u32_e32 v162, v4, v7
	v_add_u32_e32 v163, v11, v10
	v_add_u32_e32 v164, v12, v128
	v_add_u32_e32 v165, v13, v128
	v_add_u32_e32 v166, v14, v128
	v_add_u32_e32 v167, v15, v128
	v_add_u32_e32 v168, v16, v128
	v_add_u32_e32 v169, v3, v10
	v_add_u32_e32 v128, v9, v128
	v_add_u32_e32 v170, v17, v1
	s_branch .LBB0_239

.LBB0_239:
	s_mul_hi_i32 s0, s4, 0x2e8ba2e9
	s_lshr_b32 s1, s0, 31
	s_ashr_i32 s0, s0, 1
	s_add_i32 s1, s0, s1
	s_add_i32 s0, s1, s7
	s_cmpk_gt_i32 s0, 0x7f
	s_mul_i32 s12, s1, -11
	s_cselect_b64 s[10:11], -1, 0
	s_add_i32 s12, s4, s12
	s_and_b64 s[10:11], s[90:91], s[10:11]
	s_add_i32 s12, s12, -3
	s_cmp_lt_u32 s12, -2
	s_cselect_b64 s[12:13], -1, 0
	s_and_b64 s[10:11], s[10:11], s[12:13]
	s_and_b64 vcc, exec, s[10:11]
	s_cbranch_vccnz .LBB0_238
	s_cmp_eq_u32 s79, 0
	s_cbranch_scc1 .Lpfi_norm
	s_lshl_b32 s0, s0, 8
	v_add_u32_e32 v0, s0, v152
	v_ashrrev_i32_e32 v1, 31, v0
	v_lshlrev_b64 v[0:1], 11, v[0:1]
	s_mulk_i32 s1, 0xf500
	v_lshl_add_u64 v[148:149], v[250:251], 0, v[0:1]
	s_add_i32 s1, s1, s8
	v_add_co_u32_e32 v150, vcc, 0x20000, v148
	v_add_u32_e32 v2, s1, v152
	s_nop 0
	v_addc_co_u32_e32 v151, vcc, 0, v149, vcc
	v_ashrrev_i32_e32 v3, 31, v2
	v_add_co_u32_e32 v144, vcc, 0x40000, v148
	v_lshlrev_b64 v[16:17], 11, v[2:3]
	s_nop 0
	v_addc_co_u32_e32 v145, vcc, 0, v149, vcc
	v_add_co_u32_e32 v146, vcc, 0x60000, v148
	v_lshl_add_u64 v[140:141], v[176:177], 0, v[16:17]
	v_addc_co_u32_e32 v147, vcc, 0, v149, vcc
	v_add_co_u32_e32 v138, vcc, s94, v140
	s_nop 0
	v_addc_co_u32_e32 v139, vcc, 0, v141, vcc
	v_add_co_u32_e32 v134, vcc, 0x40000, v140
	s_nop 0
	v_addc_co_u32_e32 v135, vcc, 0, v141, vcc
	v_add_co_u32_e32 v136, vcc, s95, v140
	s_nop 1
	v_addc_co_u32_e32 v137, vcc, 0, v141, vcc
	global_load_dwordx4 v[172:175], v[148:149], off offset:128
	global_load_dwordx4 v[182:185], v[150:151], off offset:128
	global_load_dwordx4 v[186:189], v[144:145], off offset:128
	global_load_dwordx4 v[190:193], v[146:147], off offset:128
	global_load_dwordx4 v[194:197], v[140:141], off offset:128
	global_load_dwordx4 v[198:201], v[138:139], off offset:128
	global_load_dwordx4 v[202:205], v[134:135], off offset:128
	global_load_dwordx4 v[206:209], v[136:137], off offset:128
	s_waitcnt vmcnt(8)
	v_mov_b32_e32 v0, v210
	v_mov_b32_e32 v1, v211
	v_mov_b32_e32 v2, v212
	v_mov_b32_e32 v3, v213
	v_mov_b32_e32 v4, v214
	v_mov_b32_e32 v5, v215
	v_mov_b32_e32 v6, v216
	v_mov_b32_e32 v7, v217
	v_mov_b32_e32 v8, v218
	v_mov_b32_e32 v9, v219
	v_mov_b32_e32 v10, v220
	v_mov_b32_e32 v11, v221
	v_mov_b32_e32 v12, v222
	v_mov_b32_e32 v13, v223
	v_mov_b32_e32 v14, v224
	v_mov_b32_e32 v15, v225
	v_mov_b32_e32 v16, v226
	v_mov_b32_e32 v17, v227
	v_mov_b32_e32 v18, v228
	v_mov_b32_e32 v19, v229
	v_mov_b32_e32 v20, v238
	v_mov_b32_e32 v21, v239
	v_mov_b32_e32 v22, v240
	v_mov_b32_e32 v23, v241
	v_mov_b32_e32 v24, v242
	v_mov_b32_e32 v25, v243
	v_mov_b32_e32 v26, v244
	v_mov_b32_e32 v27, v245
	v_mov_b32_e32 v28, v246
	v_mov_b32_e32 v29, v247
	v_mov_b32_e32 v30, v248
	v_mov_b32_e32 v31, v249
	s_branch .Lpfi_join
.Lpfi_norm:
	s_lshl_b32 s0, s0, 8
	v_add_u32_e32 v0, s0, v152
	v_ashrrev_i32_e32 v1, 31, v0
	v_lshlrev_b64 v[0:1], 11, v[0:1]
	s_mulk_i32 s1, 0xf500
	v_lshl_add_u64 v[148:149], v[250:251], 0, v[0:1]
	s_add_i32 s1, s1, s8
	v_add_co_u32_e32 v150, vcc, 0x20000, v148
	v_add_u32_e32 v2, s1, v152
	s_nop 0
	v_addc_co_u32_e32 v151, vcc, 0, v149, vcc
	v_ashrrev_i32_e32 v3, 31, v2
	v_add_co_u32_e32 v144, vcc, 0x40000, v148
	v_lshlrev_b64 v[16:17], 11, v[2:3]
	s_nop 0
	v_addc_co_u32_e32 v145, vcc, 0, v149, vcc
	global_load_dwordx4 v[0:3], v[148:149], off
	v_add_co_u32_e32 v146, vcc, 0x60000, v148
	v_lshl_add_u64 v[140:141], v[176:177], 0, v[16:17]
	global_load_dwordx4 v[8:11], v[144:145], off
	global_load_dwordx4 v[16:19], v[140:141], off
	v_addc_co_u32_e32 v147, vcc, 0, v149, vcc
	global_load_dwordx4 v[4:7], v[150:151], off
	v_add_co_u32_e32 v138, vcc, s94, v140
	global_load_dwordx4 v[12:15], v[146:147], off
	s_nop 0
	v_addc_co_u32_e32 v139, vcc, 0, v141, vcc
	v_add_co_u32_e32 v134, vcc, 0x40000, v140
	global_load_dwordx4 v[20:23], v[138:139], off
	s_nop 0
	v_addc_co_u32_e32 v135, vcc, 0, v141, vcc
	global_load_dwordx4 v[24:27], v[134:135], off
	v_add_co_u32_e32 v136, vcc, s95, v140
	s_nop 1
	v_addc_co_u32_e32 v137, vcc, 0, v141, vcc
	global_load_dwordx4 v[28:31], v[136:137], off
	global_load_dwordx4 v[172:175], v[148:149], off offset:128
	global_load_dwordx4 v[182:185], v[150:151], off offset:128
	global_load_dwordx4 v[186:189], v[144:145], off offset:128
	global_load_dwordx4 v[190:193], v[146:147], off offset:128
	global_load_dwordx4 v[194:197], v[140:141], off offset:128
	global_load_dwordx4 v[198:201], v[138:139], off offset:128
	global_load_dwordx4 v[202:205], v[134:135], off offset:128
	global_load_dwordx4 v[206:209], v[136:137], off offset:128
.Lpfi_join:
	s_waitcnt vmcnt(15)
	ds_write_b128 v162, v[0:3]
	s_waitcnt vmcnt(13)
	ds_write_b128 v162, v[16:19] offset:36864
	s_waitcnt vmcnt(12)
	ds_write_b128 v162, v[4:7] offset:9216
	ds_write_b128 v162, v[8:11] offset:18432
	s_waitcnt vmcnt(11)
	ds_write_b128 v162, v[12:15] offset:27648
	s_waitcnt vmcnt(10)
	ds_write_b128 v162, v[20:23] offset:46080
	s_waitcnt vmcnt(9)
	ds_write_b128 v162, v[24:27] offset:55296
	s_waitcnt vmcnt(8)
	ds_write_b128 v162, v[28:31] offset:64512
	s_waitcnt lgkmcnt(0)
	s_barrier
	ds_read_b128 v[0:3], v163 offset:36864
	ds_read_b128 v[210:213], v163 offset:36896
	ds_read_b128 v[4:7], v163 offset:41472
	ds_read_b128 v[214:217], v163 offset:41504
	ds_read_b128 v[8:11], v154
	ds_read_b128 v[218:221], v154 offset:32
	ds_read_b128 v[12:15], v154 offset:4608
	ds_read_b128 v[222:225], v154 offset:4640
	ds_read_b128 v[16:19], v154 offset:9216
	ds_read_b128 v[226:229], v154 offset:9248
	ds_read_b128 v[230:233], v154 offset:13824
	ds_read_b128 v[234:237], v154 offset:13856
	s_waitcnt lgkmcnt(7)
	v_mfma_f32_32x32x16_bf16 v[112:127], v[8:11], v[0:3], 0
	v_mfma_f32_32x32x16_bf16 v[96:111], v[8:11], v[4:7], 0
	s_waitcnt lgkmcnt(5)
	v_mfma_f32_32x32x16_bf16 v[80:95], v[12:15], v[0:3], 0
	v_mfma_f32_32x32x16_bf16 v[64:79], v[12:15], v[4:7], 0
	s_waitcnt lgkmcnt(3)
	v_mfma_f32_32x32x16_bf16 v[48:63], v[16:19], v[0:3], 0
	v_mfma_f32_32x32x16_bf16 v[32:47], v[16:19], v[4:7], 0
	s_waitcnt lgkmcnt(1)
	v_mfma_f32_32x32x16_bf16 v[16:31], v[230:233], v[0:3], 0
	v_mfma_f32_32x32x16_bf16 v[0:15], v[230:233], v[4:7], 0
	global_load_dwordx4 v[230:233], v[148:149], off offset:256
	global_load_dwordx4 v[238:241], v[150:151], off offset:256
	s_waitcnt vmcnt(9)
	ds_write_b128 v164, v[172:175]
	s_waitcnt vmcnt(8)
	ds_write_b128 v164, v[182:185] offset:9216
	ds_read_b128 v[172:175], v163 offset:36928
	ds_read_b128 v[182:185], v163 offset:41536
	ds_read_b128 v[242:245], v154 offset:64
	ds_read_b128 v[246:249], v154 offset:4672
	ds_read_b128 v[130:133], v154 offset:9280
	ds_read_b128 v[158:161], v154 offset:13888
	v_mfma_f32_32x32x16_bf16 v[80:95], v[222:225], v[210:213], v[80:95]
	v_mfma_f32_32x32x16_bf16 v[64:79], v[222:225], v[214:217], v[64:79]
	v_mfma_f32_32x32x16_bf16 v[48:63], v[226:229], v[210:213], v[48:63]
	v_mfma_f32_32x32x16_bf16 v[32:47], v[226:229], v[214:217], v[32:47]
	s_waitcnt lgkmcnt(8)
	v_mfma_f32_32x32x16_bf16 v[16:31], v[234:237], v[210:213], v[16:31]
	v_mfma_f32_32x32x16_bf16 v[0:15], v[234:237], v[214:217], v[0:15]
	v_mfma_f32_32x32x16_bf16 v[112:127], v[218:221], v[210:213], v[112:127]
	v_mfma_f32_32x32x16_bf16 v[96:111], v[218:221], v[214:217], v[96:111]
	global_load_dwordx4 v[210:213], v[144:145], off offset:256
	global_load_dwordx4 v[214:217], v[146:147], off offset:256
	s_waitcnt vmcnt(9)
	ds_write_b128 v164, v[186:189] offset:18432
	s_waitcnt vmcnt(8)
	ds_write_b128 v164, v[190:193] offset:27648
	ds_read_b128 v[186:189], v163 offset:36960
	ds_read_b128 v[190:193], v163 offset:41568
	ds_read_b128 v[218:221], v154 offset:96
	ds_read_b128 v[222:225], v154 offset:4704
	ds_read_b128 v[226:229], v154 offset:9312
	ds_read_b128 v[234:237], v154 offset:13920
	s_waitcnt lgkmcnt(10)
	v_mfma_f32_32x32x16_bf16 v[80:95], v[246:249], v[172:175], v[80:95]
	v_mfma_f32_32x32x16_bf16 v[64:79], v[246:249], v[182:185], v[64:79]
	s_waitcnt lgkmcnt(9)
	v_mfma_f32_32x32x16_bf16 v[48:63], v[130:133], v[172:175], v[48:63]
	v_mfma_f32_32x32x16_bf16 v[32:47], v[130:133], v[182:185], v[32:47]
	s_waitcnt lgkmcnt(8)
	v_mfma_f32_32x32x16_bf16 v[16:31], v[158:161], v[172:175], v[16:31]
	v_mfma_f32_32x32x16_bf16 v[0:15], v[158:161], v[182:185], v[0:15]
	v_mfma_f32_32x32x16_bf16 v[112:127], v[242:245], v[172:175], v[112:127]
	v_mfma_f32_32x32x16_bf16 v[96:111], v[242:245], v[182:185], v[96:111]
	global_load_dwordx4 v[130:133], v[140:141], off offset:256
	global_load_dwordx4 v[158:161], v[138:139], off offset:256
	s_waitcnt vmcnt(9)
	ds_write_b128 v165, v[194:197]
	s_waitcnt vmcnt(8)
	ds_write_b128 v166, v[198:201]
	s_waitcnt lgkmcnt(4)
	v_mfma_f32_32x32x16_bf16 v[80:95], v[222:225], v[186:189], v[80:95]
	v_mfma_f32_32x32x16_bf16 v[64:79], v[222:225], v[190:193], v[64:79]
	s_waitcnt lgkmcnt(3)
	v_mfma_f32_32x32x16_bf16 v[48:63], v[226:229], v[186:189], v[48:63]
	v_mfma_f32_32x32x16_bf16 v[32:47], v[226:229], v[190:193], v[32:47]
	s_waitcnt lgkmcnt(2)
	v_mfma_f32_32x32x16_bf16 v[16:31], v[234:237], v[186:189], v[16:31]
	v_mfma_f32_32x32x16_bf16 v[0:15], v[234:237], v[190:193], v[0:15]
	v_mfma_f32_32x32x16_bf16 v[112:127], v[218:221], v[186:189], v[112:127]
	v_mfma_f32_32x32x16_bf16 v[96:111], v[218:221], v[190:193], v[96:111]
	global_load_dwordx4 v[172:175], v[134:135], off offset:256
	global_load_dwordx4 v[182:185], v[136:137], off offset:256
	s_waitcnt vmcnt(9)
	ds_write_b128 v167, v[202:205]
	s_waitcnt vmcnt(8)
	ds_write_b128 v168, v[206:209]
	s_waitcnt lgkmcnt(0)
	s_barrier
	ds_read_b128 v[186:189], v169
	ds_read_b128 v[190:193], v169 offset:32
	ds_read_b128 v[194:197], v169 offset:4608
	ds_read_b128 v[198:201], v169 offset:4640
	ds_read_b128 v[202:205], v155
	ds_read_b128 v[206:209], v155 offset:32
	ds_read_b128 v[218:221], v155 offset:4608
	ds_read_b128 v[222:225], v155 offset:4640
	ds_read_b128 v[226:229], v155 offset:9216
	ds_read_b128 v[234:237], v155 offset:9248
	ds_read_b128 v[242:245], v155 offset:13824
	ds_read_b128 v[246:249], v155 offset:13856
	s_waitcnt lgkmcnt(5)
	v_mfma_f32_32x32x16_bf16 v[80:95], v[218:221], v[186:189], v[80:95]
	v_mfma_f32_32x32x16_bf16 v[64:79], v[218:221], v[194:197], v[64:79]
	s_waitcnt lgkmcnt(3)
	v_mfma_f32_32x32x16_bf16 v[48:63], v[226:229], v[186:189], v[48:63]
	v_mfma_f32_32x32x16_bf16 v[32:47], v[226:229], v[194:197], v[32:47]
	s_waitcnt lgkmcnt(1)
	v_mfma_f32_32x32x16_bf16 v[16:31], v[242:245], v[186:189], v[16:31]
	v_mfma_f32_32x32x16_bf16 v[0:15], v[242:245], v[194:197], v[0:15]
	v_mfma_f32_32x32x16_bf16 v[112:127], v[202:205], v[186:189], v[112:127]
	v_mfma_f32_32x32x16_bf16 v[96:111], v[202:205], v[194:197], v[96:111]
	global_load_dwordx4 v[186:189], v[148:149], off offset:384
	global_load_dwordx4 v[194:197], v[150:151], off offset:384
	s_waitcnt vmcnt(9)
	ds_write_b128 v128, v[230:233]
	s_waitcnt vmcnt(8)
	ds_write_b128 v128, v[238:241] offset:9216
	ds_read_b128 v[202:205], v169 offset:64
	ds_read_b128 v[218:221], v169 offset:4672
	ds_read_b128 v[226:229], v155 offset:64
	ds_read_b128 v[230:233], v155 offset:4672
	ds_read_b128 v[238:241], v155 offset:9280
	ds_read_b128 v[242:245], v155 offset:13888
	v_mfma_f32_32x32x16_bf16 v[80:95], v[222:225], v[190:193], v[80:95]
	v_mfma_f32_32x32x16_bf16 v[64:79], v[222:225], v[198:201], v[64:79]
	v_mfma_f32_32x32x16_bf16 v[48:63], v[234:237], v[190:193], v[48:63]
	v_mfma_f32_32x32x16_bf16 v[32:47], v[234:237], v[198:201], v[32:47]
	s_waitcnt lgkmcnt(8)
	v_mfma_f32_32x32x16_bf16 v[16:31], v[246:249], v[190:193], v[16:31]
	v_mfma_f32_32x32x16_bf16 v[0:15], v[246:249], v[198:201], v[0:15]
	v_mfma_f32_32x32x16_bf16 v[112:127], v[206:209], v[190:193], v[112:127]
	v_mfma_f32_32x32x16_bf16 v[96:111], v[206:209], v[198:201], v[96:111]
	global_load_dwordx4 v[190:193], v[144:145], off offset:384
	global_load_dwordx4 v[198:201], v[146:147], off offset:384
	s_waitcnt vmcnt(9)
	ds_write_b128 v128, v[210:213] offset:18432
	s_waitcnt vmcnt(8)
	ds_write_b128 v128, v[214:217] offset:27648
	ds_read_b128 v[206:209], v169 offset:96
	ds_read_b128 v[210:213], v169 offset:4704
	ds_read_b128 v[214:217], v155 offset:96
	ds_read_b128 v[222:225], v155 offset:4704
	ds_read_b128 v[234:237], v155 offset:9312
	ds_read_b128 v[246:249], v155 offset:13920
	s_waitcnt lgkmcnt(10)
	v_mfma_f32_32x32x16_bf16 v[80:95], v[230:233], v[202:205], v[80:95]
	v_mfma_f32_32x32x16_bf16 v[64:79], v[230:233], v[218:221], v[64:79]
	s_waitcnt lgkmcnt(9)
	v_mfma_f32_32x32x16_bf16 v[48:63], v[238:241], v[202:205], v[48:63]
	v_mfma_f32_32x32x16_bf16 v[32:47], v[238:241], v[218:221], v[32:47]
	s_waitcnt lgkmcnt(8)
	v_mfma_f32_32x32x16_bf16 v[16:31], v[242:245], v[202:205], v[16:31]
	v_mfma_f32_32x32x16_bf16 v[0:15], v[242:245], v[218:221], v[0:15]
	v_mfma_f32_32x32x16_bf16 v[112:127], v[226:229], v[202:205], v[112:127]
	v_mfma_f32_32x32x16_bf16 v[96:111], v[226:229], v[218:221], v[96:111]
	s_waitcnt vmcnt(7)
	ds_write_b128 v128, v[130:133] offset:36864
	global_load_dwordx4 v[130:133], v[140:141], off offset:384
	s_waitcnt vmcnt(7)
	ds_write_b128 v128, v[158:161] offset:46080
	global_load_dwordx4 v[158:161], v[138:139], off offset:384
	s_waitcnt lgkmcnt(4)
	v_mfma_f32_32x32x16_bf16 v[80:95], v[222:225], v[206:209], v[80:95]
	v_mfma_f32_32x32x16_bf16 v[64:79], v[222:225], v[210:213], v[64:79]
	s_waitcnt lgkmcnt(3)
	v_mfma_f32_32x32x16_bf16 v[48:63], v[234:237], v[206:209], v[48:63]
	v_mfma_f32_32x32x16_bf16 v[32:47], v[234:237], v[210:213], v[32:47]
	s_waitcnt lgkmcnt(2)
	v_mfma_f32_32x32x16_bf16 v[16:31], v[246:249], v[206:209], v[16:31]
	v_mfma_f32_32x32x16_bf16 v[0:15], v[246:249], v[210:213], v[0:15]
	v_mfma_f32_32x32x16_bf16 v[112:127], v[214:217], v[206:209], v[112:127]
	v_mfma_f32_32x32x16_bf16 v[96:111], v[214:217], v[210:213], v[96:111]
	global_load_dwordx4 v[202:205], v[134:135], off offset:384
	global_load_dwordx4 v[206:209], v[136:137], off offset:384
	s_waitcnt vmcnt(9)
	ds_write_b128 v128, v[172:175] offset:55296
	s_waitcnt vmcnt(8)
	ds_write_b128 v128, v[182:185] offset:64512
	s_waitcnt lgkmcnt(0)
	s_barrier
	ds_read_b128 v[172:175], v163 offset:36864
	ds_read_b128 v[182:185], v163 offset:36896
	ds_read_b128 v[210:213], v163 offset:41472
	ds_read_b128 v[214:217], v163 offset:41504
	ds_read_b128 v[218:221], v154
	ds_read_b128 v[222:225], v154 offset:32
	ds_read_b128 v[226:229], v154 offset:4608
	ds_read_b128 v[230:233], v154 offset:4640
	ds_read_b128 v[234:237], v154 offset:9216
	ds_read_b128 v[238:241], v154 offset:9248
	ds_read_b128 v[242:245], v154 offset:13824
	ds_read_b128 v[246:249], v154 offset:13856
	s_waitcnt lgkmcnt(5)
	v_mfma_f32_32x32x16_bf16 v[80:95], v[226:229], v[172:175], v[80:95]
	v_mfma_f32_32x32x16_bf16 v[64:79], v[226:229], v[210:213], v[64:79]
	s_waitcnt lgkmcnt(3)
	v_mfma_f32_32x32x16_bf16 v[48:63], v[234:237], v[172:175], v[48:63]
	v_mfma_f32_32x32x16_bf16 v[32:47], v[234:237], v[210:213], v[32:47]
	s_waitcnt lgkmcnt(1)
	v_mfma_f32_32x32x16_bf16 v[16:31], v[242:245], v[172:175], v[16:31]
	v_mfma_f32_32x32x16_bf16 v[0:15], v[242:245], v[210:213], v[0:15]
	v_mfma_f32_32x32x16_bf16 v[112:127], v[218:221], v[172:175], v[112:127]
	v_mfma_f32_32x32x16_bf16 v[96:111], v[218:221], v[210:213], v[96:111]
	global_load_dwordx4 v[172:175], v[148:149], off offset:512
	global_load_dwordx4 v[210:213], v[150:151], off offset:512
	s_waitcnt vmcnt(9)
	ds_write_b128 v164, v[186:189]
	s_waitcnt vmcnt(8)
	ds_write_b128 v164, v[194:197] offset:9216
	ds_read_b128 v[186:189], v163 offset:36928
	ds_read_b128 v[194:197], v163 offset:41536
	ds_read_b128 v[218:221], v154 offset:64
	ds_read_b128 v[226:229], v154 offset:4672
	ds_read_b128 v[234:237], v154 offset:9280
	ds_read_b128 v[242:245], v154 offset:13888
	v_mfma_f32_32x32x16_bf16 v[80:95], v[230:233], v[182:185], v[80:95]
	v_mfma_f32_32x32x16_bf16 v[64:79], v[230:233], v[214:217], v[64:79]
	v_mfma_f32_32x32x16_bf16 v[48:63], v[238:241], v[182:185], v[48:63]
	v_mfma_f32_32x32x16_bf16 v[32:47], v[238:241], v[214:217], v[32:47]
	s_waitcnt lgkmcnt(8)
	v_mfma_f32_32x32x16_bf16 v[16:31], v[246:249], v[182:185], v[16:31]
	v_mfma_f32_32x32x16_bf16 v[0:15], v[246:249], v[214:217], v[0:15]
	v_mfma_f32_32x32x16_bf16 v[112:127], v[222:225], v[182:185], v[112:127]
	v_mfma_f32_32x32x16_bf16 v[96:111], v[222:225], v[214:217], v[96:111]
	global_load_dwordx4 v[182:185], v[144:145], off offset:512
	global_load_dwordx4 v[214:217], v[146:147], off offset:512
	s_waitcnt vmcnt(9)
	ds_write_b128 v164, v[190:193] offset:18432
	s_waitcnt vmcnt(8)
	ds_write_b128 v164, v[198:201] offset:27648
	ds_read_b128 v[190:193], v163 offset:36960
	ds_read_b128 v[198:201], v163 offset:41568
	ds_read_b128 v[222:225], v154 offset:96
	ds_read_b128 v[230:233], v154 offset:4704
	ds_read_b128 v[238:241], v154 offset:9312
	ds_read_b128 v[246:249], v154 offset:13920
	s_waitcnt lgkmcnt(10)
	v_mfma_f32_32x32x16_bf16 v[80:95], v[226:229], v[186:189], v[80:95]
	v_mfma_f32_32x32x16_bf16 v[64:79], v[226:229], v[194:197], v[64:79]
	s_waitcnt lgkmcnt(9)
	v_mfma_f32_32x32x16_bf16 v[48:63], v[234:237], v[186:189], v[48:63]
	v_mfma_f32_32x32x16_bf16 v[32:47], v[234:237], v[194:197], v[32:47]
	s_waitcnt lgkmcnt(8)
	v_mfma_f32_32x32x16_bf16 v[16:31], v[242:245], v[186:189], v[16:31]
	v_mfma_f32_32x32x16_bf16 v[0:15], v[242:245], v[194:197], v[0:15]
	v_mfma_f32_32x32x16_bf16 v[112:127], v[218:221], v[186:189], v[112:127]
	v_mfma_f32_32x32x16_bf16 v[96:111], v[218:221], v[194:197], v[96:111]
	s_waitcnt vmcnt(7)
	ds_write_b128 v165, v[130:133]
	global_load_dwordx4 v[130:133], v[140:141], off offset:512
	s_waitcnt vmcnt(7)
	ds_write_b128 v166, v[158:161]
	global_load_dwordx4 v[158:161], v[138:139], off offset:512
	s_waitcnt lgkmcnt(4)
	v_mfma_f32_32x32x16_bf16 v[80:95], v[230:233], v[190:193], v[80:95]
	v_mfma_f32_32x32x16_bf16 v[64:79], v[230:233], v[198:201], v[64:79]
	s_waitcnt lgkmcnt(3)
	v_mfma_f32_32x32x16_bf16 v[48:63], v[238:241], v[190:193], v[48:63]
	v_mfma_f32_32x32x16_bf16 v[32:47], v[238:241], v[198:201], v[32:47]
	s_waitcnt lgkmcnt(2)
	v_mfma_f32_32x32x16_bf16 v[16:31], v[246:249], v[190:193], v[16:31]
	v_mfma_f32_32x32x16_bf16 v[0:15], v[246:249], v[198:201], v[0:15]
	v_mfma_f32_32x32x16_bf16 v[112:127], v[222:225], v[190:193], v[112:127]
	v_mfma_f32_32x32x16_bf16 v[96:111], v[222:225], v[198:201], v[96:111]
	global_load_dwordx4 v[186:189], v[134:135], off offset:512
	global_load_dwordx4 v[190:193], v[136:137], off offset:512
	s_waitcnt vmcnt(9)
	ds_write_b128 v167, v[202:205]
	s_waitcnt vmcnt(8)
	ds_write_b128 v168, v[206:209]
	s_waitcnt lgkmcnt(0)
	s_barrier
	ds_read_b128 v[194:197], v169
	ds_read_b128 v[198:201], v169 offset:32
	ds_read_b128 v[202:205], v169 offset:4608
	ds_read_b128 v[206:209], v169 offset:4640
	ds_read_b128 v[218:221], v155
	ds_read_b128 v[222:225], v155 offset:32
	ds_read_b128 v[226:229], v155 offset:4608
	ds_read_b128 v[230:233], v155 offset:4640
	ds_read_b128 v[234:237], v155 offset:9216
	ds_read_b128 v[238:241], v155 offset:9248
	ds_read_b128 v[242:245], v155 offset:13824
	ds_read_b128 v[246:249], v155 offset:13856
	s_waitcnt lgkmcnt(5)
	v_mfma_f32_32x32x16_bf16 v[80:95], v[226:229], v[194:197], v[80:95]
	v_mfma_f32_32x32x16_bf16 v[64:79], v[226:229], v[202:205], v[64:79]
	s_waitcnt lgkmcnt(3)
	v_mfma_f32_32x32x16_bf16 v[48:63], v[234:237], v[194:197], v[48:63]
	v_mfma_f32_32x32x16_bf16 v[32:47], v[234:237], v[202:205], v[32:47]
	s_waitcnt lgkmcnt(1)
	v_mfma_f32_32x32x16_bf16 v[16:31], v[242:245], v[194:197], v[16:31]
	v_mfma_f32_32x32x16_bf16 v[0:15], v[242:245], v[202:205], v[0:15]
	v_mfma_f32_32x32x16_bf16 v[112:127], v[218:221], v[194:197], v[112:127]
	v_mfma_f32_32x32x16_bf16 v[96:111], v[218:221], v[202:205], v[96:111]
	global_load_dwordx4 v[194:197], v[148:149], off offset:640
	global_load_dwordx4 v[202:205], v[150:151], off offset:640
	s_waitcnt vmcnt(9)
	ds_write_b128 v128, v[172:175]
	s_waitcnt vmcnt(8)
	ds_write_b128 v128, v[210:213] offset:9216
	ds_read_b128 v[172:175], v169 offset:64
	ds_read_b128 v[210:213], v169 offset:4672
	ds_read_b128 v[218:221], v155 offset:64
	ds_read_b128 v[226:229], v155 offset:4672
	ds_read_b128 v[234:237], v155 offset:9280
	ds_read_b128 v[242:245], v155 offset:13888
	v_mfma_f32_32x32x16_bf16 v[80:95], v[230:233], v[198:201], v[80:95]
	v_mfma_f32_32x32x16_bf16 v[64:79], v[230:233], v[206:209], v[64:79]
	v_mfma_f32_32x32x16_bf16 v[48:63], v[238:241], v[198:201], v[48:63]
	v_mfma_f32_32x32x16_bf16 v[32:47], v[238:241], v[206:209], v[32:47]
	s_waitcnt lgkmcnt(8)
	v_mfma_f32_32x32x16_bf16 v[16:31], v[246:249], v[198:201], v[16:31]
	v_mfma_f32_32x32x16_bf16 v[0:15], v[246:249], v[206:209], v[0:15]
	v_mfma_f32_32x32x16_bf16 v[112:127], v[222:225], v[198:201], v[112:127]
	v_mfma_f32_32x32x16_bf16 v[96:111], v[222:225], v[206:209], v[96:111]
	global_load_dwordx4 v[198:201], v[144:145], off offset:640
	global_load_dwordx4 v[206:209], v[146:147], off offset:640
	s_waitcnt vmcnt(9)
	ds_write_b128 v128, v[182:185] offset:18432
	s_waitcnt vmcnt(8)
	ds_write_b128 v128, v[214:217] offset:27648
	ds_read_b128 v[182:185], v169 offset:96
	ds_read_b128 v[214:217], v169 offset:4704
	ds_read_b128 v[222:225], v155 offset:96
	ds_read_b128 v[230:233], v155 offset:4704
	ds_read_b128 v[238:241], v155 offset:9312
	ds_read_b128 v[246:249], v155 offset:13920
	s_waitcnt lgkmcnt(10)
	v_mfma_f32_32x32x16_bf16 v[80:95], v[226:229], v[172:175], v[80:95]
	v_mfma_f32_32x32x16_bf16 v[64:79], v[226:229], v[210:213], v[64:79]
	s_waitcnt lgkmcnt(9)
	v_mfma_f32_32x32x16_bf16 v[48:63], v[234:237], v[172:175], v[48:63]
	v_mfma_f32_32x32x16_bf16 v[32:47], v[234:237], v[210:213], v[32:47]
	s_waitcnt lgkmcnt(8)
	v_mfma_f32_32x32x16_bf16 v[16:31], v[242:245], v[172:175], v[16:31]
	v_mfma_f32_32x32x16_bf16 v[0:15], v[242:245], v[210:213], v[0:15]
	v_mfma_f32_32x32x16_bf16 v[112:127], v[218:221], v[172:175], v[112:127]
	v_mfma_f32_32x32x16_bf16 v[96:111], v[218:221], v[210:213], v[96:111]
	s_waitcnt vmcnt(7)
	ds_write_b128 v128, v[130:133] offset:36864
	global_load_dwordx4 v[130:133], v[140:141], off offset:640
	s_waitcnt vmcnt(7)
	ds_write_b128 v128, v[158:161] offset:46080
	global_load_dwordx4 v[158:161], v[138:139], off offset:640
	s_waitcnt lgkmcnt(4)
	v_mfma_f32_32x32x16_bf16 v[80:95], v[230:233], v[182:185], v[80:95]
	v_mfma_f32_32x32x16_bf16 v[64:79], v[230:233], v[214:217], v[64:79]
	s_waitcnt lgkmcnt(3)
	v_mfma_f32_32x32x16_bf16 v[48:63], v[238:241], v[182:185], v[48:63]
	v_mfma_f32_32x32x16_bf16 v[32:47], v[238:241], v[214:217], v[32:47]
	s_waitcnt lgkmcnt(2)
	v_mfma_f32_32x32x16_bf16 v[16:31], v[246:249], v[182:185], v[16:31]
	v_mfma_f32_32x32x16_bf16 v[0:15], v[246:249], v[214:217], v[0:15]
	v_mfma_f32_32x32x16_bf16 v[112:127], v[222:225], v[182:185], v[112:127]
	v_mfma_f32_32x32x16_bf16 v[96:111], v[222:225], v[214:217], v[96:111]
	global_load_dwordx4 v[172:175], v[134:135], off offset:640
	global_load_dwordx4 v[182:185], v[136:137], off offset:640
	s_waitcnt vmcnt(9)
	ds_write_b128 v128, v[186:189] offset:55296
	s_waitcnt vmcnt(8)
	ds_write_b128 v128, v[190:193] offset:64512
	s_waitcnt lgkmcnt(0)
	s_barrier
	ds_read_b128 v[186:189], v163 offset:36864
	ds_read_b128 v[190:193], v163 offset:36896
	ds_read_b128 v[210:213], v163 offset:41472
	ds_read_b128 v[214:217], v163 offset:41504
	ds_read_b128 v[218:221], v154
	ds_read_b128 v[222:225], v154 offset:32
	ds_read_b128 v[226:229], v154 offset:4608
	ds_read_b128 v[230:233], v154 offset:4640
	ds_read_b128 v[234:237], v154 offset:9216
	ds_read_b128 v[238:241], v154 offset:9248
	ds_read_b128 v[242:245], v154 offset:13824
	ds_read_b128 v[246:249], v154 offset:13856
	s_waitcnt lgkmcnt(5)
	v_mfma_f32_32x32x16_bf16 v[80:95], v[226:229], v[186:189], v[80:95]
	v_mfma_f32_32x32x16_bf16 v[64:79], v[226:229], v[210:213], v[64:79]
	s_waitcnt lgkmcnt(3)
	v_mfma_f32_32x32x16_bf16 v[48:63], v[234:237], v[186:189], v[48:63]
	v_mfma_f32_32x32x16_bf16 v[32:47], v[234:237], v[210:213], v[32:47]
	s_waitcnt lgkmcnt(1)
	v_mfma_f32_32x32x16_bf16 v[16:31], v[242:245], v[186:189], v[16:31]
	v_mfma_f32_32x32x16_bf16 v[0:15], v[242:245], v[210:213], v[0:15]
	v_mfma_f32_32x32x16_bf16 v[112:127], v[218:221], v[186:189], v[112:127]
	v_mfma_f32_32x32x16_bf16 v[96:111], v[218:221], v[210:213], v[96:111]
	global_load_dwordx4 v[186:189], v[148:149], off offset:768
	global_load_dwordx4 v[210:213], v[150:151], off offset:768
	s_waitcnt vmcnt(9)
	ds_write_b128 v164, v[194:197]
	s_waitcnt vmcnt(8)
	ds_write_b128 v164, v[202:205] offset:9216
	ds_read_b128 v[194:197], v163 offset:36928
	ds_read_b128 v[202:205], v163 offset:41536
	ds_read_b128 v[218:221], v154 offset:64
	ds_read_b128 v[226:229], v154 offset:4672
	ds_read_b128 v[234:237], v154 offset:9280
	ds_read_b128 v[242:245], v154 offset:13888
	v_mfma_f32_32x32x16_bf16 v[80:95], v[230:233], v[190:193], v[80:95]
	v_mfma_f32_32x32x16_bf16 v[64:79], v[230:233], v[214:217], v[64:79]
	v_mfma_f32_32x32x16_bf16 v[48:63], v[238:241], v[190:193], v[48:63]
	v_mfma_f32_32x32x16_bf16 v[32:47], v[238:241], v[214:217], v[32:47]
	s_waitcnt lgkmcnt(8)
	v_mfma_f32_32x32x16_bf16 v[16:31], v[246:249], v[190:193], v[16:31]
	v_mfma_f32_32x32x16_bf16 v[0:15], v[246:249], v[214:217], v[0:15]
	v_mfma_f32_32x32x16_bf16 v[112:127], v[222:225], v[190:193], v[112:127]
	v_mfma_f32_32x32x16_bf16 v[96:111], v[222:225], v[214:217], v[96:111]
	global_load_dwordx4 v[190:193], v[144:145], off offset:768
	global_load_dwordx4 v[214:217], v[146:147], off offset:768
	s_waitcnt vmcnt(9)
	ds_write_b128 v164, v[198:201] offset:18432
	s_waitcnt vmcnt(8)
	ds_write_b128 v164, v[206:209] offset:27648
	ds_read_b128 v[198:201], v163 offset:36960
	ds_read_b128 v[206:209], v163 offset:41568
	ds_read_b128 v[222:225], v154 offset:96
	ds_read_b128 v[230:233], v154 offset:4704
	ds_read_b128 v[238:241], v154 offset:9312
	ds_read_b128 v[246:249], v154 offset:13920
	s_waitcnt lgkmcnt(10)
	v_mfma_f32_32x32x16_bf16 v[80:95], v[226:229], v[194:197], v[80:95]
	v_mfma_f32_32x32x16_bf16 v[64:79], v[226:229], v[202:205], v[64:79]
	s_waitcnt lgkmcnt(9)
	v_mfma_f32_32x32x16_bf16 v[48:63], v[234:237], v[194:197], v[48:63]
	v_mfma_f32_32x32x16_bf16 v[32:47], v[234:237], v[202:205], v[32:47]
	s_waitcnt lgkmcnt(8)
	v_mfma_f32_32x32x16_bf16 v[16:31], v[242:245], v[194:197], v[16:31]
	v_mfma_f32_32x32x16_bf16 v[0:15], v[242:245], v[202:205], v[0:15]
	v_mfma_f32_32x32x16_bf16 v[112:127], v[218:221], v[194:197], v[112:127]
	v_mfma_f32_32x32x16_bf16 v[96:111], v[218:221], v[202:205], v[96:111]
	s_waitcnt vmcnt(7)
	ds_write_b128 v165, v[130:133]
	global_load_dwordx4 v[130:133], v[140:141], off offset:768
	s_waitcnt vmcnt(7)
	ds_write_b128 v166, v[158:161]
	global_load_dwordx4 v[158:161], v[138:139], off offset:768
	s_waitcnt lgkmcnt(4)
	v_mfma_f32_32x32x16_bf16 v[80:95], v[230:233], v[198:201], v[80:95]
	v_mfma_f32_32x32x16_bf16 v[64:79], v[230:233], v[206:209], v[64:79]
	s_waitcnt lgkmcnt(3)
	v_mfma_f32_32x32x16_bf16 v[48:63], v[238:241], v[198:201], v[48:63]
	v_mfma_f32_32x32x16_bf16 v[32:47], v[238:241], v[206:209], v[32:47]
	s_waitcnt lgkmcnt(2)
	v_mfma_f32_32x32x16_bf16 v[16:31], v[246:249], v[198:201], v[16:31]
	v_mfma_f32_32x32x16_bf16 v[0:15], v[246:249], v[206:209], v[0:15]
	v_mfma_f32_32x32x16_bf16 v[112:127], v[222:225], v[198:201], v[112:127]
	v_mfma_f32_32x32x16_bf16 v[96:111], v[222:225], v[206:209], v[96:111]
	global_load_dwordx4 v[194:197], v[134:135], off offset:768
	global_load_dwordx4 v[198:201], v[136:137], off offset:768
	s_waitcnt vmcnt(9)
	ds_write_b128 v167, v[172:175]
	s_waitcnt vmcnt(8)
	ds_write_b128 v168, v[182:185]
	s_waitcnt lgkmcnt(0)
	s_barrier
	ds_read_b128 v[172:175], v169
	ds_read_b128 v[182:185], v169 offset:32
	ds_read_b128 v[202:205], v169 offset:4608
	ds_read_b128 v[206:209], v169 offset:4640
	ds_read_b128 v[218:221], v155
	ds_read_b128 v[222:225], v155 offset:32
	ds_read_b128 v[226:229], v155 offset:4608
	ds_read_b128 v[230:233], v155 offset:4640
	ds_read_b128 v[234:237], v155 offset:9216
	ds_read_b128 v[238:241], v155 offset:9248
	ds_read_b128 v[242:245], v155 offset:13824
	ds_read_b128 v[246:249], v155 offset:13856
	s_waitcnt lgkmcnt(5)
	v_mfma_f32_32x32x16_bf16 v[80:95], v[226:229], v[172:175], v[80:95]
	v_mfma_f32_32x32x16_bf16 v[64:79], v[226:229], v[202:205], v[64:79]
	s_waitcnt lgkmcnt(3)
	v_mfma_f32_32x32x16_bf16 v[48:63], v[234:237], v[172:175], v[48:63]
	v_mfma_f32_32x32x16_bf16 v[32:47], v[234:237], v[202:205], v[32:47]
	s_waitcnt lgkmcnt(1)
	v_mfma_f32_32x32x16_bf16 v[16:31], v[242:245], v[172:175], v[16:31]
	v_mfma_f32_32x32x16_bf16 v[0:15], v[242:245], v[202:205], v[0:15]
	v_mfma_f32_32x32x16_bf16 v[112:127], v[218:221], v[172:175], v[112:127]
	v_mfma_f32_32x32x16_bf16 v[96:111], v[218:221], v[202:205], v[96:111]
	global_load_dwordx4 v[172:175], v[148:149], off offset:896
	global_load_dwordx4 v[202:205], v[150:151], off offset:896
	s_waitcnt vmcnt(9)
	ds_write_b128 v128, v[186:189]
	s_waitcnt vmcnt(8)
	ds_write_b128 v128, v[210:213] offset:9216
	ds_read_b128 v[186:189], v169 offset:64
	ds_read_b128 v[210:213], v169 offset:4672
	ds_read_b128 v[218:221], v155 offset:64
	ds_read_b128 v[226:229], v155 offset:4672
	ds_read_b128 v[234:237], v155 offset:9280
	ds_read_b128 v[242:245], v155 offset:13888
	v_mfma_f32_32x32x16_bf16 v[80:95], v[230:233], v[182:185], v[80:95]
	v_mfma_f32_32x32x16_bf16 v[64:79], v[230:233], v[206:209], v[64:79]
	v_mfma_f32_32x32x16_bf16 v[48:63], v[238:241], v[182:185], v[48:63]
	v_mfma_f32_32x32x16_bf16 v[32:47], v[238:241], v[206:209], v[32:47]
	s_waitcnt lgkmcnt(8)
	v_mfma_f32_32x32x16_bf16 v[16:31], v[246:249], v[182:185], v[16:31]
	v_mfma_f32_32x32x16_bf16 v[0:15], v[246:249], v[206:209], v[0:15]
	v_mfma_f32_32x32x16_bf16 v[112:127], v[222:225], v[182:185], v[112:127]
	v_mfma_f32_32x32x16_bf16 v[96:111], v[222:225], v[206:209], v[96:111]
	global_load_dwordx4 v[182:185], v[144:145], off offset:896
	global_load_dwordx4 v[206:209], v[146:147], off offset:896
	s_waitcnt vmcnt(9)
	ds_write_b128 v128, v[190:193] offset:18432
	s_waitcnt vmcnt(8)
	ds_write_b128 v128, v[214:217] offset:27648
	ds_read_b128 v[190:193], v169 offset:96
	ds_read_b128 v[214:217], v169 offset:4704
	ds_read_b128 v[222:225], v155 offset:96
	ds_read_b128 v[230:233], v155 offset:4704
	ds_read_b128 v[238:241], v155 offset:9312
	ds_read_b128 v[246:249], v155 offset:13920
	s_waitcnt lgkmcnt(10)
	v_mfma_f32_32x32x16_bf16 v[80:95], v[226:229], v[186:189], v[80:95]
	v_mfma_f32_32x32x16_bf16 v[64:79], v[226:229], v[210:213], v[64:79]
	s_waitcnt lgkmcnt(9)
	v_mfma_f32_32x32x16_bf16 v[48:63], v[234:237], v[186:189], v[48:63]
	v_mfma_f32_32x32x16_bf16 v[32:47], v[234:237], v[210:213], v[32:47]
	s_waitcnt lgkmcnt(8)
	v_mfma_f32_32x32x16_bf16 v[16:31], v[242:245], v[186:189], v[16:31]
	v_mfma_f32_32x32x16_bf16 v[0:15], v[242:245], v[210:213], v[0:15]
	v_mfma_f32_32x32x16_bf16 v[112:127], v[218:221], v[186:189], v[112:127]
	v_mfma_f32_32x32x16_bf16 v[96:111], v[218:221], v[210:213], v[96:111]
	s_waitcnt vmcnt(7)
	ds_write_b128 v128, v[130:133] offset:36864
	global_load_dwordx4 v[130:133], v[140:141], off offset:896
	s_waitcnt vmcnt(7)
	ds_write_b128 v128, v[158:161] offset:46080
	global_load_dwordx4 v[158:161], v[138:139], off offset:896
	s_waitcnt lgkmcnt(4)
	v_mfma_f32_32x32x16_bf16 v[80:95], v[230:233], v[190:193], v[80:95]
	v_mfma_f32_32x32x16_bf16 v[64:79], v[230:233], v[214:217], v[64:79]
	s_waitcnt lgkmcnt(3)
	v_mfma_f32_32x32x16_bf16 v[48:63], v[238:241], v[190:193], v[48:63]
	v_mfma_f32_32x32x16_bf16 v[32:47], v[238:241], v[214:217], v[32:47]
	s_waitcnt lgkmcnt(2)
	v_mfma_f32_32x32x16_bf16 v[16:31], v[246:249], v[190:193], v[16:31]
	v_mfma_f32_32x32x16_bf16 v[0:15], v[246:249], v[214:217], v[0:15]
	v_mfma_f32_32x32x16_bf16 v[112:127], v[222:225], v[190:193], v[112:127]
	v_mfma_f32_32x32x16_bf16 v[96:111], v[222:225], v[214:217], v[96:111]
	global_load_dwordx4 v[186:189], v[134:135], off offset:896
	global_load_dwordx4 v[190:193], v[136:137], off offset:896
	s_waitcnt vmcnt(9)
	ds_write_b128 v128, v[194:197] offset:55296
	s_waitcnt vmcnt(8)
	ds_write_b128 v128, v[198:201] offset:64512
	s_waitcnt lgkmcnt(0)
	s_barrier
	ds_read_b128 v[194:197], v163 offset:36864
	ds_read_b128 v[198:201], v163 offset:36896
	ds_read_b128 v[210:213], v163 offset:41472
	ds_read_b128 v[214:217], v163 offset:41504
	ds_read_b128 v[218:221], v154
	ds_read_b128 v[222:225], v154 offset:32
	ds_read_b128 v[226:229], v154 offset:4608
	ds_read_b128 v[230:233], v154 offset:4640
	ds_read_b128 v[234:237], v154 offset:9216
	ds_read_b128 v[238:241], v154 offset:9248
	ds_read_b128 v[242:245], v154 offset:13824
	ds_read_b128 v[246:249], v154 offset:13856
	s_waitcnt lgkmcnt(5)
	v_mfma_f32_32x32x16_bf16 v[80:95], v[226:229], v[194:197], v[80:95]
	v_mfma_f32_32x32x16_bf16 v[64:79], v[226:229], v[210:213], v[64:79]
	s_waitcnt lgkmcnt(3)
	v_mfma_f32_32x32x16_bf16 v[48:63], v[234:237], v[194:197], v[48:63]
	v_mfma_f32_32x32x16_bf16 v[32:47], v[234:237], v[210:213], v[32:47]
	s_waitcnt lgkmcnt(1)
	v_mfma_f32_32x32x16_bf16 v[16:31], v[242:245], v[194:197], v[16:31]
	v_mfma_f32_32x32x16_bf16 v[0:15], v[242:245], v[210:213], v[0:15]
	v_mfma_f32_32x32x16_bf16 v[112:127], v[218:221], v[194:197], v[112:127]
	v_mfma_f32_32x32x16_bf16 v[96:111], v[218:221], v[210:213], v[96:111]
	global_load_dwordx4 v[194:197], v[148:149], off offset:1024
	global_load_dwordx4 v[210:213], v[150:151], off offset:1024
	s_waitcnt vmcnt(9)
	ds_write_b128 v164, v[172:175]
	s_waitcnt vmcnt(8)
	ds_write_b128 v164, v[202:205] offset:9216
	ds_read_b128 v[172:175], v163 offset:36928
	ds_read_b128 v[202:205], v163 offset:41536
	ds_read_b128 v[218:221], v154 offset:64
	ds_read_b128 v[226:229], v154 offset:4672
	ds_read_b128 v[234:237], v154 offset:9280
	ds_read_b128 v[242:245], v154 offset:13888
	v_mfma_f32_32x32x16_bf16 v[80:95], v[230:233], v[198:201], v[80:95]
	v_mfma_f32_32x32x16_bf16 v[64:79], v[230:233], v[214:217], v[64:79]
	v_mfma_f32_32x32x16_bf16 v[48:63], v[238:241], v[198:201], v[48:63]
	v_mfma_f32_32x32x16_bf16 v[32:47], v[238:241], v[214:217], v[32:47]
	s_waitcnt lgkmcnt(8)
	v_mfma_f32_32x32x16_bf16 v[16:31], v[246:249], v[198:201], v[16:31]
	v_mfma_f32_32x32x16_bf16 v[0:15], v[246:249], v[214:217], v[0:15]
	v_mfma_f32_32x32x16_bf16 v[112:127], v[222:225], v[198:201], v[112:127]
	v_mfma_f32_32x32x16_bf16 v[96:111], v[222:225], v[214:217], v[96:111]
	global_load_dwordx4 v[198:201], v[144:145], off offset:1024
	global_load_dwordx4 v[214:217], v[146:147], off offset:1024
	s_waitcnt vmcnt(9)
	ds_write_b128 v164, v[182:185] offset:18432
	s_waitcnt vmcnt(8)
	ds_write_b128 v164, v[206:209] offset:27648
	ds_read_b128 v[182:185], v163 offset:36960
	ds_read_b128 v[206:209], v163 offset:41568
	ds_read_b128 v[222:225], v154 offset:96
	ds_read_b128 v[230:233], v154 offset:4704
	ds_read_b128 v[238:241], v154 offset:9312
	ds_read_b128 v[246:249], v154 offset:13920
	s_waitcnt lgkmcnt(10)
	v_mfma_f32_32x32x16_bf16 v[80:95], v[226:229], v[172:175], v[80:95]
	v_mfma_f32_32x32x16_bf16 v[64:79], v[226:229], v[202:205], v[64:79]
	s_waitcnt lgkmcnt(9)
	v_mfma_f32_32x32x16_bf16 v[48:63], v[234:237], v[172:175], v[48:63]
	v_mfma_f32_32x32x16_bf16 v[32:47], v[234:237], v[202:205], v[32:47]
	s_waitcnt lgkmcnt(8)
	v_mfma_f32_32x32x16_bf16 v[16:31], v[242:245], v[172:175], v[16:31]
	v_mfma_f32_32x32x16_bf16 v[0:15], v[242:245], v[202:205], v[0:15]
	v_mfma_f32_32x32x16_bf16 v[112:127], v[218:221], v[172:175], v[112:127]
	v_mfma_f32_32x32x16_bf16 v[96:111], v[218:221], v[202:205], v[96:111]
	s_waitcnt vmcnt(7)
	ds_write_b128 v165, v[130:133]
	global_load_dwordx4 v[130:133], v[140:141], off offset:1024
	s_waitcnt vmcnt(7)
	ds_write_b128 v166, v[158:161]
	global_load_dwordx4 v[158:161], v[138:139], off offset:1024
	s_waitcnt lgkmcnt(4)
	v_mfma_f32_32x32x16_bf16 v[80:95], v[230:233], v[182:185], v[80:95]
	v_mfma_f32_32x32x16_bf16 v[64:79], v[230:233], v[206:209], v[64:79]
	s_waitcnt lgkmcnt(3)
	v_mfma_f32_32x32x16_bf16 v[48:63], v[238:241], v[182:185], v[48:63]
	v_mfma_f32_32x32x16_bf16 v[32:47], v[238:241], v[206:209], v[32:47]
	s_waitcnt lgkmcnt(2)
	v_mfma_f32_32x32x16_bf16 v[16:31], v[246:249], v[182:185], v[16:31]
	v_mfma_f32_32x32x16_bf16 v[0:15], v[246:249], v[206:209], v[0:15]
	v_mfma_f32_32x32x16_bf16 v[112:127], v[222:225], v[182:185], v[112:127]
	v_mfma_f32_32x32x16_bf16 v[96:111], v[222:225], v[206:209], v[96:111]
	global_load_dwordx4 v[172:175], v[134:135], off offset:1024
	global_load_dwordx4 v[182:185], v[136:137], off offset:1024
	s_waitcnt vmcnt(9)
	ds_write_b128 v167, v[186:189]
	s_waitcnt vmcnt(8)
	ds_write_b128 v168, v[190:193]
	s_waitcnt lgkmcnt(0)
	s_barrier
	ds_read_b128 v[186:189], v169
	ds_read_b128 v[190:193], v169 offset:32
	ds_read_b128 v[202:205], v169 offset:4608
	ds_read_b128 v[206:209], v169 offset:4640
	ds_read_b128 v[218:221], v155
	ds_read_b128 v[222:225], v155 offset:32
	ds_read_b128 v[226:229], v155 offset:4608
	ds_read_b128 v[230:233], v155 offset:4640
	ds_read_b128 v[234:237], v155 offset:9216
	ds_read_b128 v[238:241], v155 offset:9248
	ds_read_b128 v[242:245], v155 offset:13824
	ds_read_b128 v[246:249], v155 offset:13856
	s_waitcnt lgkmcnt(5)
	v_mfma_f32_32x32x16_bf16 v[80:95], v[226:229], v[186:189], v[80:95]
	v_mfma_f32_32x32x16_bf16 v[64:79], v[226:229], v[202:205], v[64:79]
	s_waitcnt lgkmcnt(3)
	v_mfma_f32_32x32x16_bf16 v[48:63], v[234:237], v[186:189], v[48:63]
	v_mfma_f32_32x32x16_bf16 v[32:47], v[234:237], v[202:205], v[32:47]
	s_waitcnt lgkmcnt(1)
	v_mfma_f32_32x32x16_bf16 v[16:31], v[242:245], v[186:189], v[16:31]
	v_mfma_f32_32x32x16_bf16 v[0:15], v[242:245], v[202:205], v[0:15]
	v_mfma_f32_32x32x16_bf16 v[112:127], v[218:221], v[186:189], v[112:127]
	v_mfma_f32_32x32x16_bf16 v[96:111], v[218:221], v[202:205], v[96:111]
	global_load_dwordx4 v[186:189], v[148:149], off offset:1152
	global_load_dwordx4 v[202:205], v[150:151], off offset:1152
	s_waitcnt vmcnt(9)
	ds_write_b128 v128, v[194:197]
	s_waitcnt vmcnt(8)
	ds_write_b128 v128, v[210:213] offset:9216
	ds_read_b128 v[194:197], v169 offset:64
	ds_read_b128 v[210:213], v169 offset:4672
	ds_read_b128 v[218:221], v155 offset:64
	ds_read_b128 v[226:229], v155 offset:4672
	ds_read_b128 v[234:237], v155 offset:9280
	ds_read_b128 v[242:245], v155 offset:13888
	v_mfma_f32_32x32x16_bf16 v[80:95], v[230:233], v[190:193], v[80:95]
	v_mfma_f32_32x32x16_bf16 v[64:79], v[230:233], v[206:209], v[64:79]
	v_mfma_f32_32x32x16_bf16 v[48:63], v[238:241], v[190:193], v[48:63]
	v_mfma_f32_32x32x16_bf16 v[32:47], v[238:241], v[206:209], v[32:47]
	s_waitcnt lgkmcnt(8)
	v_mfma_f32_32x32x16_bf16 v[16:31], v[246:249], v[190:193], v[16:31]
	v_mfma_f32_32x32x16_bf16 v[0:15], v[246:249], v[206:209], v[0:15]
	v_mfma_f32_32x32x16_bf16 v[112:127], v[222:225], v[190:193], v[112:127]
	v_mfma_f32_32x32x16_bf16 v[96:111], v[222:225], v[206:209], v[96:111]
	global_load_dwordx4 v[190:193], v[144:145], off offset:1152
	global_load_dwordx4 v[206:209], v[146:147], off offset:1152
	s_waitcnt vmcnt(9)
	ds_write_b128 v128, v[198:201] offset:18432
	s_waitcnt vmcnt(8)
	ds_write_b128 v128, v[214:217] offset:27648
	ds_read_b128 v[198:201], v169 offset:96
	ds_read_b128 v[214:217], v169 offset:4704
	ds_read_b128 v[222:225], v155 offset:96
	ds_read_b128 v[230:233], v155 offset:4704
	ds_read_b128 v[238:241], v155 offset:9312
	ds_read_b128 v[246:249], v155 offset:13920
	s_waitcnt lgkmcnt(10)
	v_mfma_f32_32x32x16_bf16 v[80:95], v[226:229], v[194:197], v[80:95]
	v_mfma_f32_32x32x16_bf16 v[64:79], v[226:229], v[210:213], v[64:79]
	s_waitcnt lgkmcnt(9)
	v_mfma_f32_32x32x16_bf16 v[48:63], v[234:237], v[194:197], v[48:63]
	v_mfma_f32_32x32x16_bf16 v[32:47], v[234:237], v[210:213], v[32:47]
	s_waitcnt lgkmcnt(8)
	v_mfma_f32_32x32x16_bf16 v[16:31], v[242:245], v[194:197], v[16:31]
	v_mfma_f32_32x32x16_bf16 v[0:15], v[242:245], v[210:213], v[0:15]
	v_mfma_f32_32x32x16_bf16 v[112:127], v[218:221], v[194:197], v[112:127]
	v_mfma_f32_32x32x16_bf16 v[96:111], v[218:221], v[210:213], v[96:111]
	s_waitcnt vmcnt(7)
	ds_write_b128 v128, v[130:133] offset:36864
	global_load_dwordx4 v[130:133], v[140:141], off offset:1152
	s_waitcnt vmcnt(7)
	ds_write_b128 v128, v[158:161] offset:46080
	global_load_dwordx4 v[158:161], v[138:139], off offset:1152
	s_waitcnt lgkmcnt(4)
	v_mfma_f32_32x32x16_bf16 v[80:95], v[230:233], v[198:201], v[80:95]
	v_mfma_f32_32x32x16_bf16 v[64:79], v[230:233], v[214:217], v[64:79]
	s_waitcnt lgkmcnt(3)
	v_mfma_f32_32x32x16_bf16 v[48:63], v[238:241], v[198:201], v[48:63]
	v_mfma_f32_32x32x16_bf16 v[32:47], v[238:241], v[214:217], v[32:47]
	s_waitcnt lgkmcnt(2)
	v_mfma_f32_32x32x16_bf16 v[16:31], v[246:249], v[198:201], v[16:31]
	v_mfma_f32_32x32x16_bf16 v[0:15], v[246:249], v[214:217], v[0:15]
	v_mfma_f32_32x32x16_bf16 v[112:127], v[222:225], v[198:201], v[112:127]
	v_mfma_f32_32x32x16_bf16 v[96:111], v[222:225], v[214:217], v[96:111]
	global_load_dwordx4 v[194:197], v[134:135], off offset:1152
	global_load_dwordx4 v[198:201], v[136:137], off offset:1152
	s_waitcnt vmcnt(9)
	ds_write_b128 v128, v[172:175] offset:55296
	s_waitcnt vmcnt(8)
	ds_write_b128 v128, v[182:185] offset:64512
	s_waitcnt lgkmcnt(0)
	s_barrier
	ds_read_b128 v[172:175], v163 offset:36864
	ds_read_b128 v[182:185], v163 offset:36896
	ds_read_b128 v[210:213], v163 offset:41472
	ds_read_b128 v[214:217], v163 offset:41504
	ds_read_b128 v[218:221], v154
	ds_read_b128 v[222:225], v154 offset:32
	ds_read_b128 v[226:229], v154 offset:4608
	ds_read_b128 v[230:233], v154 offset:4640
	ds_read_b128 v[234:237], v154 offset:9216
	ds_read_b128 v[238:241], v154 offset:9248
	ds_read_b128 v[242:245], v154 offset:13824
	ds_read_b128 v[246:249], v154 offset:13856
	s_waitcnt lgkmcnt(5)
	v_mfma_f32_32x32x16_bf16 v[80:95], v[226:229], v[172:175], v[80:95]
	v_mfma_f32_32x32x16_bf16 v[64:79], v[226:229], v[210:213], v[64:79]
	s_waitcnt lgkmcnt(3)
	v_mfma_f32_32x32x16_bf16 v[48:63], v[234:237], v[172:175], v[48:63]
	v_mfma_f32_32x32x16_bf16 v[32:47], v[234:237], v[210:213], v[32:47]
	s_waitcnt lgkmcnt(1)
	v_mfma_f32_32x32x16_bf16 v[16:31], v[242:245], v[172:175], v[16:31]
	v_mfma_f32_32x32x16_bf16 v[0:15], v[242:245], v[210:213], v[0:15]
	v_mfma_f32_32x32x16_bf16 v[112:127], v[218:221], v[172:175], v[112:127]
	v_mfma_f32_32x32x16_bf16 v[96:111], v[218:221], v[210:213], v[96:111]
	global_load_dwordx4 v[172:175], v[148:149], off offset:1280
	global_load_dwordx4 v[210:213], v[150:151], off offset:1280
	s_waitcnt vmcnt(9)
	ds_write_b128 v164, v[186:189]
	s_waitcnt vmcnt(8)
	ds_write_b128 v164, v[202:205] offset:9216
	ds_read_b128 v[186:189], v163 offset:36928
	ds_read_b128 v[202:205], v163 offset:41536
	ds_read_b128 v[218:221], v154 offset:64
	ds_read_b128 v[226:229], v154 offset:4672
	ds_read_b128 v[234:237], v154 offset:9280
	ds_read_b128 v[242:245], v154 offset:13888
	v_mfma_f32_32x32x16_bf16 v[80:95], v[230:233], v[182:185], v[80:95]
	v_mfma_f32_32x32x16_bf16 v[64:79], v[230:233], v[214:217], v[64:79]
	v_mfma_f32_32x32x16_bf16 v[48:63], v[238:241], v[182:185], v[48:63]
	v_mfma_f32_32x32x16_bf16 v[32:47], v[238:241], v[214:217], v[32:47]
	s_waitcnt lgkmcnt(8)
	v_mfma_f32_32x32x16_bf16 v[16:31], v[246:249], v[182:185], v[16:31]
	v_mfma_f32_32x32x16_bf16 v[0:15], v[246:249], v[214:217], v[0:15]
	v_mfma_f32_32x32x16_bf16 v[112:127], v[222:225], v[182:185], v[112:127]
	v_mfma_f32_32x32x16_bf16 v[96:111], v[222:225], v[214:217], v[96:111]
	global_load_dwordx4 v[182:185], v[144:145], off offset:1280
	global_load_dwordx4 v[214:217], v[146:147], off offset:1280
	s_waitcnt vmcnt(9)
	ds_write_b128 v164, v[190:193] offset:18432
	s_waitcnt vmcnt(8)
	ds_write_b128 v164, v[206:209] offset:27648
	ds_read_b128 v[190:193], v163 offset:36960
	ds_read_b128 v[206:209], v163 offset:41568
	ds_read_b128 v[222:225], v154 offset:96
	ds_read_b128 v[230:233], v154 offset:4704
	ds_read_b128 v[238:241], v154 offset:9312
	ds_read_b128 v[246:249], v154 offset:13920
	s_waitcnt lgkmcnt(10)
	v_mfma_f32_32x32x16_bf16 v[80:95], v[226:229], v[186:189], v[80:95]
	v_mfma_f32_32x32x16_bf16 v[64:79], v[226:229], v[202:205], v[64:79]
	s_waitcnt lgkmcnt(9)
	v_mfma_f32_32x32x16_bf16 v[48:63], v[234:237], v[186:189], v[48:63]
	v_mfma_f32_32x32x16_bf16 v[32:47], v[234:237], v[202:205], v[32:47]
	s_waitcnt lgkmcnt(8)
	v_mfma_f32_32x32x16_bf16 v[16:31], v[242:245], v[186:189], v[16:31]
	v_mfma_f32_32x32x16_bf16 v[0:15], v[242:245], v[202:205], v[0:15]
	v_mfma_f32_32x32x16_bf16 v[112:127], v[218:221], v[186:189], v[112:127]
	v_mfma_f32_32x32x16_bf16 v[96:111], v[218:221], v[202:205], v[96:111]
	s_waitcnt vmcnt(7)
	ds_write_b128 v165, v[130:133]
	global_load_dwordx4 v[130:133], v[140:141], off offset:1280
	s_waitcnt vmcnt(7)
	ds_write_b128 v166, v[158:161]
	global_load_dwordx4 v[158:161], v[138:139], off offset:1280
	s_waitcnt lgkmcnt(4)
	v_mfma_f32_32x32x16_bf16 v[80:95], v[230:233], v[190:193], v[80:95]
	v_mfma_f32_32x32x16_bf16 v[64:79], v[230:233], v[206:209], v[64:79]
	s_waitcnt lgkmcnt(3)
	v_mfma_f32_32x32x16_bf16 v[48:63], v[238:241], v[190:193], v[48:63]
	v_mfma_f32_32x32x16_bf16 v[32:47], v[238:241], v[206:209], v[32:47]
	s_waitcnt lgkmcnt(2)
	v_mfma_f32_32x32x16_bf16 v[16:31], v[246:249], v[190:193], v[16:31]
	v_mfma_f32_32x32x16_bf16 v[0:15], v[246:249], v[206:209], v[0:15]
	v_mfma_f32_32x32x16_bf16 v[112:127], v[222:225], v[190:193], v[112:127]
	v_mfma_f32_32x32x16_bf16 v[96:111], v[222:225], v[206:209], v[96:111]
	global_load_dwordx4 v[186:189], v[134:135], off offset:1280
	global_load_dwordx4 v[190:193], v[136:137], off offset:1280
	s_waitcnt vmcnt(9)
	ds_write_b128 v167, v[194:197]
	s_waitcnt vmcnt(8)
	ds_write_b128 v168, v[198:201]
	s_waitcnt lgkmcnt(0)
	s_barrier
	ds_read_b128 v[194:197], v169
	ds_read_b128 v[198:201], v169 offset:32
	ds_read_b128 v[202:205], v169 offset:4608
	ds_read_b128 v[206:209], v169 offset:4640
	ds_read_b128 v[218:221], v155
	ds_read_b128 v[222:225], v155 offset:32
	ds_read_b128 v[226:229], v155 offset:4608
	ds_read_b128 v[230:233], v155 offset:4640
	ds_read_b128 v[234:237], v155 offset:9216
	ds_read_b128 v[238:241], v155 offset:9248
	ds_read_b128 v[242:245], v155 offset:13824
	ds_read_b128 v[246:249], v155 offset:13856
	s_waitcnt lgkmcnt(5)
	v_mfma_f32_32x32x16_bf16 v[80:95], v[226:229], v[194:197], v[80:95]
	v_mfma_f32_32x32x16_bf16 v[64:79], v[226:229], v[202:205], v[64:79]
	s_waitcnt lgkmcnt(3)
	v_mfma_f32_32x32x16_bf16 v[48:63], v[234:237], v[194:197], v[48:63]
	v_mfma_f32_32x32x16_bf16 v[32:47], v[234:237], v[202:205], v[32:47]
	s_waitcnt lgkmcnt(1)
	v_mfma_f32_32x32x16_bf16 v[16:31], v[242:245], v[194:197], v[16:31]
	v_mfma_f32_32x32x16_bf16 v[0:15], v[242:245], v[202:205], v[0:15]
	v_mfma_f32_32x32x16_bf16 v[112:127], v[218:221], v[194:197], v[112:127]
	v_mfma_f32_32x32x16_bf16 v[96:111], v[218:221], v[202:205], v[96:111]
	global_load_dwordx4 v[194:197], v[148:149], off offset:1408
	global_load_dwordx4 v[202:205], v[150:151], off offset:1408
	s_waitcnt vmcnt(9)
	ds_write_b128 v128, v[172:175]
	s_waitcnt vmcnt(8)
	ds_write_b128 v128, v[210:213] offset:9216
	ds_read_b128 v[172:175], v169 offset:64
	ds_read_b128 v[210:213], v169 offset:4672
	ds_read_b128 v[218:221], v155 offset:64
	ds_read_b128 v[226:229], v155 offset:4672
	ds_read_b128 v[234:237], v155 offset:9280
	ds_read_b128 v[242:245], v155 offset:13888
	v_mfma_f32_32x32x16_bf16 v[80:95], v[230:233], v[198:201], v[80:95]
	v_mfma_f32_32x32x16_bf16 v[64:79], v[230:233], v[206:209], v[64:79]
	v_mfma_f32_32x32x16_bf16 v[48:63], v[238:241], v[198:201], v[48:63]
	v_mfma_f32_32x32x16_bf16 v[32:47], v[238:241], v[206:209], v[32:47]
	s_waitcnt lgkmcnt(8)
	v_mfma_f32_32x32x16_bf16 v[16:31], v[246:249], v[198:201], v[16:31]
	v_mfma_f32_32x32x16_bf16 v[0:15], v[246:249], v[206:209], v[0:15]
	v_mfma_f32_32x32x16_bf16 v[112:127], v[222:225], v[198:201], v[112:127]
	v_mfma_f32_32x32x16_bf16 v[96:111], v[222:225], v[206:209], v[96:111]
	global_load_dwordx4 v[198:201], v[144:145], off offset:1408
	global_load_dwordx4 v[206:209], v[146:147], off offset:1408
	s_waitcnt vmcnt(9)
	ds_write_b128 v128, v[182:185] offset:18432
	s_waitcnt vmcnt(8)
	ds_write_b128 v128, v[214:217] offset:27648
	ds_read_b128 v[182:185], v169 offset:96
	ds_read_b128 v[214:217], v169 offset:4704
	ds_read_b128 v[222:225], v155 offset:96
	ds_read_b128 v[230:233], v155 offset:4704
	ds_read_b128 v[238:241], v155 offset:9312
	ds_read_b128 v[246:249], v155 offset:13920
	s_waitcnt lgkmcnt(10)
	v_mfma_f32_32x32x16_bf16 v[80:95], v[226:229], v[172:175], v[80:95]
	v_mfma_f32_32x32x16_bf16 v[64:79], v[226:229], v[210:213], v[64:79]
	s_waitcnt lgkmcnt(9)
	v_mfma_f32_32x32x16_bf16 v[48:63], v[234:237], v[172:175], v[48:63]
	v_mfma_f32_32x32x16_bf16 v[32:47], v[234:237], v[210:213], v[32:47]
	s_waitcnt lgkmcnt(8)
	v_mfma_f32_32x32x16_bf16 v[16:31], v[242:245], v[172:175], v[16:31]
	v_mfma_f32_32x32x16_bf16 v[0:15], v[242:245], v[210:213], v[0:15]
	v_mfma_f32_32x32x16_bf16 v[112:127], v[218:221], v[172:175], v[112:127]
	v_mfma_f32_32x32x16_bf16 v[96:111], v[218:221], v[210:213], v[96:111]
	s_waitcnt vmcnt(7)
	ds_write_b128 v128, v[130:133] offset:36864
	global_load_dwordx4 v[130:133], v[140:141], off offset:1408
	s_waitcnt vmcnt(7)
	ds_write_b128 v128, v[158:161] offset:46080
	global_load_dwordx4 v[158:161], v[138:139], off offset:1408
	s_waitcnt lgkmcnt(4)
	v_mfma_f32_32x32x16_bf16 v[80:95], v[230:233], v[182:185], v[80:95]
	v_mfma_f32_32x32x16_bf16 v[64:79], v[230:233], v[214:217], v[64:79]
	s_waitcnt lgkmcnt(3)
	v_mfma_f32_32x32x16_bf16 v[48:63], v[238:241], v[182:185], v[48:63]
	v_mfma_f32_32x32x16_bf16 v[32:47], v[238:241], v[214:217], v[32:47]
	s_waitcnt lgkmcnt(2)
	v_mfma_f32_32x32x16_bf16 v[16:31], v[246:249], v[182:185], v[16:31]
	v_mfma_f32_32x32x16_bf16 v[0:15], v[246:249], v[214:217], v[0:15]
	v_mfma_f32_32x32x16_bf16 v[112:127], v[222:225], v[182:185], v[112:127]
	v_mfma_f32_32x32x16_bf16 v[96:111], v[222:225], v[214:217], v[96:111]
	global_load_dwordx4 v[172:175], v[134:135], off offset:1408
	global_load_dwordx4 v[182:185], v[136:137], off offset:1408
	s_waitcnt vmcnt(9)
	ds_write_b128 v128, v[186:189] offset:55296
	s_waitcnt vmcnt(8)
	ds_write_b128 v128, v[190:193] offset:64512
	s_waitcnt lgkmcnt(0)
	s_barrier
	ds_read_b128 v[186:189], v163 offset:36864
	ds_read_b128 v[190:193], v163 offset:36896
	ds_read_b128 v[210:213], v163 offset:41472
	ds_read_b128 v[214:217], v163 offset:41504
	ds_read_b128 v[218:221], v154
	ds_read_b128 v[222:225], v154 offset:32
	ds_read_b128 v[226:229], v154 offset:4608
	ds_read_b128 v[230:233], v154 offset:4640
	ds_read_b128 v[234:237], v154 offset:9216
	ds_read_b128 v[238:241], v154 offset:9248
	ds_read_b128 v[242:245], v154 offset:13824
	ds_read_b128 v[246:249], v154 offset:13856
	s_waitcnt lgkmcnt(5)
	v_mfma_f32_32x32x16_bf16 v[80:95], v[226:229], v[186:189], v[80:95]
	v_mfma_f32_32x32x16_bf16 v[64:79], v[226:229], v[210:213], v[64:79]
	s_waitcnt lgkmcnt(3)
	v_mfma_f32_32x32x16_bf16 v[48:63], v[234:237], v[186:189], v[48:63]
	v_mfma_f32_32x32x16_bf16 v[32:47], v[234:237], v[210:213], v[32:47]
	s_waitcnt lgkmcnt(1)
	v_mfma_f32_32x32x16_bf16 v[16:31], v[242:245], v[186:189], v[16:31]
	v_mfma_f32_32x32x16_bf16 v[0:15], v[242:245], v[210:213], v[0:15]
	v_mfma_f32_32x32x16_bf16 v[112:127], v[218:221], v[186:189], v[112:127]
	v_mfma_f32_32x32x16_bf16 v[96:111], v[218:221], v[210:213], v[96:111]
	global_load_dwordx4 v[186:189], v[148:149], off offset:1536
	global_load_dwordx4 v[210:213], v[150:151], off offset:1536
	s_waitcnt vmcnt(9)
	ds_write_b128 v164, v[194:197]
	s_waitcnt vmcnt(8)
	ds_write_b128 v164, v[202:205] offset:9216
	ds_read_b128 v[194:197], v163 offset:36928
	ds_read_b128 v[202:205], v163 offset:41536
	ds_read_b128 v[218:221], v154 offset:64
	ds_read_b128 v[226:229], v154 offset:4672
	ds_read_b128 v[234:237], v154 offset:9280
	ds_read_b128 v[242:245], v154 offset:13888
	v_mfma_f32_32x32x16_bf16 v[80:95], v[230:233], v[190:193], v[80:95]
	v_mfma_f32_32x32x16_bf16 v[64:79], v[230:233], v[214:217], v[64:79]
	v_mfma_f32_32x32x16_bf16 v[48:63], v[238:241], v[190:193], v[48:63]
	v_mfma_f32_32x32x16_bf16 v[32:47], v[238:241], v[214:217], v[32:47]
	s_waitcnt lgkmcnt(8)
	v_mfma_f32_32x32x16_bf16 v[16:31], v[246:249], v[190:193], v[16:31]
	v_mfma_f32_32x32x16_bf16 v[0:15], v[246:249], v[214:217], v[0:15]
	v_mfma_f32_32x32x16_bf16 v[112:127], v[222:225], v[190:193], v[112:127]
	v_mfma_f32_32x32x16_bf16 v[96:111], v[222:225], v[214:217], v[96:111]
	global_load_dwordx4 v[190:193], v[144:145], off offset:1536
	global_load_dwordx4 v[214:217], v[146:147], off offset:1536
	s_waitcnt vmcnt(9)
	ds_write_b128 v164, v[198:201] offset:18432
	s_waitcnt vmcnt(8)
	ds_write_b128 v164, v[206:209] offset:27648
	ds_read_b128 v[198:201], v163 offset:36960
	ds_read_b128 v[206:209], v163 offset:41568
	ds_read_b128 v[222:225], v154 offset:96
	ds_read_b128 v[230:233], v154 offset:4704
	ds_read_b128 v[238:241], v154 offset:9312
	ds_read_b128 v[246:249], v154 offset:13920
	s_waitcnt lgkmcnt(10)
	v_mfma_f32_32x32x16_bf16 v[80:95], v[226:229], v[194:197], v[80:95]
	v_mfma_f32_32x32x16_bf16 v[64:79], v[226:229], v[202:205], v[64:79]
	s_waitcnt lgkmcnt(9)
	v_mfma_f32_32x32x16_bf16 v[48:63], v[234:237], v[194:197], v[48:63]
	v_mfma_f32_32x32x16_bf16 v[32:47], v[234:237], v[202:205], v[32:47]
	s_waitcnt lgkmcnt(8)
	v_mfma_f32_32x32x16_bf16 v[16:31], v[242:245], v[194:197], v[16:31]
	v_mfma_f32_32x32x16_bf16 v[0:15], v[242:245], v[202:205], v[0:15]
	v_mfma_f32_32x32x16_bf16 v[112:127], v[218:221], v[194:197], v[112:127]
	v_mfma_f32_32x32x16_bf16 v[96:111], v[218:221], v[202:205], v[96:111]
	s_waitcnt vmcnt(7)
	ds_write_b128 v165, v[130:133]
	global_load_dwordx4 v[130:133], v[140:141], off offset:1536
	s_waitcnt vmcnt(7)
	ds_write_b128 v166, v[158:161]
	global_load_dwordx4 v[158:161], v[138:139], off offset:1536
	s_waitcnt lgkmcnt(4)
	v_mfma_f32_32x32x16_bf16 v[80:95], v[230:233], v[198:201], v[80:95]
	v_mfma_f32_32x32x16_bf16 v[64:79], v[230:233], v[206:209], v[64:79]
	s_waitcnt lgkmcnt(3)
	v_mfma_f32_32x32x16_bf16 v[48:63], v[238:241], v[198:201], v[48:63]
	v_mfma_f32_32x32x16_bf16 v[32:47], v[238:241], v[206:209], v[32:47]
	s_waitcnt lgkmcnt(2)
	v_mfma_f32_32x32x16_bf16 v[16:31], v[246:249], v[198:201], v[16:31]
	v_mfma_f32_32x32x16_bf16 v[0:15], v[246:249], v[206:209], v[0:15]
	v_mfma_f32_32x32x16_bf16 v[112:127], v[222:225], v[198:201], v[112:127]
	v_mfma_f32_32x32x16_bf16 v[96:111], v[222:225], v[206:209], v[96:111]
	global_load_dwordx4 v[194:197], v[134:135], off offset:1536
	global_load_dwordx4 v[198:201], v[136:137], off offset:1536
	s_waitcnt vmcnt(9)
	ds_write_b128 v167, v[172:175]
	s_waitcnt vmcnt(8)
	ds_write_b128 v168, v[182:185]
	s_waitcnt lgkmcnt(0)
	s_barrier
	ds_read_b128 v[172:175], v169
	ds_read_b128 v[182:185], v169 offset:32
	ds_read_b128 v[202:205], v169 offset:4608
	ds_read_b128 v[206:209], v169 offset:4640
	ds_read_b128 v[218:221], v155
	ds_read_b128 v[222:225], v155 offset:32
	ds_read_b128 v[226:229], v155 offset:4608
	ds_read_b128 v[230:233], v155 offset:4640
	ds_read_b128 v[234:237], v155 offset:9216
	ds_read_b128 v[238:241], v155 offset:9248
	ds_read_b128 v[242:245], v155 offset:13824
	ds_read_b128 v[246:249], v155 offset:13856
	s_waitcnt lgkmcnt(5)
	v_mfma_f32_32x32x16_bf16 v[80:95], v[226:229], v[172:175], v[80:95]
	v_mfma_f32_32x32x16_bf16 v[64:79], v[226:229], v[202:205], v[64:79]
	s_waitcnt lgkmcnt(3)
	v_mfma_f32_32x32x16_bf16 v[48:63], v[234:237], v[172:175], v[48:63]
	v_mfma_f32_32x32x16_bf16 v[32:47], v[234:237], v[202:205], v[32:47]
	s_waitcnt lgkmcnt(1)
	v_mfma_f32_32x32x16_bf16 v[16:31], v[242:245], v[172:175], v[16:31]
	v_mfma_f32_32x32x16_bf16 v[0:15], v[242:245], v[202:205], v[0:15]
	v_mfma_f32_32x32x16_bf16 v[112:127], v[218:221], v[172:175], v[112:127]
	v_mfma_f32_32x32x16_bf16 v[96:111], v[218:221], v[202:205], v[96:111]
	global_load_dwordx4 v[172:175], v[148:149], off offset:1664
	global_load_dwordx4 v[202:205], v[150:151], off offset:1664
	s_waitcnt vmcnt(9)
	ds_write_b128 v128, v[186:189]
	s_waitcnt vmcnt(8)
	ds_write_b128 v128, v[210:213] offset:9216
	ds_read_b128 v[186:189], v169 offset:64
	ds_read_b128 v[210:213], v169 offset:4672
	ds_read_b128 v[218:221], v155 offset:64
	ds_read_b128 v[226:229], v155 offset:4672
	ds_read_b128 v[234:237], v155 offset:9280
	ds_read_b128 v[242:245], v155 offset:13888
	v_mfma_f32_32x32x16_bf16 v[80:95], v[230:233], v[182:185], v[80:95]
	v_mfma_f32_32x32x16_bf16 v[64:79], v[230:233], v[206:209], v[64:79]
	v_mfma_f32_32x32x16_bf16 v[48:63], v[238:241], v[182:185], v[48:63]
	v_mfma_f32_32x32x16_bf16 v[32:47], v[238:241], v[206:209], v[32:47]
	s_waitcnt lgkmcnt(8)
	v_mfma_f32_32x32x16_bf16 v[16:31], v[246:249], v[182:185], v[16:31]
	v_mfma_f32_32x32x16_bf16 v[0:15], v[246:249], v[206:209], v[0:15]
	v_mfma_f32_32x32x16_bf16 v[112:127], v[222:225], v[182:185], v[112:127]
	v_mfma_f32_32x32x16_bf16 v[96:111], v[222:225], v[206:209], v[96:111]
	global_load_dwordx4 v[182:185], v[144:145], off offset:1664
	global_load_dwordx4 v[206:209], v[146:147], off offset:1664
	s_waitcnt vmcnt(9)
	ds_write_b128 v128, v[190:193] offset:18432
	s_waitcnt vmcnt(8)
	ds_write_b128 v128, v[214:217] offset:27648
	ds_read_b128 v[190:193], v169 offset:96
	ds_read_b128 v[214:217], v169 offset:4704
	ds_read_b128 v[222:225], v155 offset:96
	ds_read_b128 v[230:233], v155 offset:4704
	ds_read_b128 v[238:241], v155 offset:9312
	ds_read_b128 v[246:249], v155 offset:13920
	s_waitcnt lgkmcnt(10)
	v_mfma_f32_32x32x16_bf16 v[80:95], v[226:229], v[186:189], v[80:95]
	v_mfma_f32_32x32x16_bf16 v[64:79], v[226:229], v[210:213], v[64:79]
	s_waitcnt lgkmcnt(9)
	v_mfma_f32_32x32x16_bf16 v[48:63], v[234:237], v[186:189], v[48:63]
	v_mfma_f32_32x32x16_bf16 v[32:47], v[234:237], v[210:213], v[32:47]
	s_waitcnt lgkmcnt(8)
	v_mfma_f32_32x32x16_bf16 v[16:31], v[242:245], v[186:189], v[16:31]
	v_mfma_f32_32x32x16_bf16 v[0:15], v[242:245], v[210:213], v[0:15]
	v_mfma_f32_32x32x16_bf16 v[112:127], v[218:221], v[186:189], v[112:127]
	v_mfma_f32_32x32x16_bf16 v[96:111], v[218:221], v[210:213], v[96:111]
	s_waitcnt vmcnt(7)
	ds_write_b128 v128, v[130:133] offset:36864
	global_load_dwordx4 v[130:133], v[140:141], off offset:1664
	s_waitcnt vmcnt(7)
	ds_write_b128 v128, v[158:161] offset:46080
	global_load_dwordx4 v[158:161], v[138:139], off offset:1664
	s_waitcnt lgkmcnt(4)
	v_mfma_f32_32x32x16_bf16 v[80:95], v[230:233], v[190:193], v[80:95]
	v_mfma_f32_32x32x16_bf16 v[64:79], v[230:233], v[214:217], v[64:79]
	s_waitcnt lgkmcnt(3)
	v_mfma_f32_32x32x16_bf16 v[48:63], v[238:241], v[190:193], v[48:63]
	v_mfma_f32_32x32x16_bf16 v[32:47], v[238:241], v[214:217], v[32:47]
	s_waitcnt lgkmcnt(2)
	v_mfma_f32_32x32x16_bf16 v[16:31], v[246:249], v[190:193], v[16:31]
	v_mfma_f32_32x32x16_bf16 v[0:15], v[246:249], v[214:217], v[0:15]
	v_mfma_f32_32x32x16_bf16 v[112:127], v[222:225], v[190:193], v[112:127]
	v_mfma_f32_32x32x16_bf16 v[96:111], v[222:225], v[214:217], v[96:111]
	global_load_dwordx4 v[186:189], v[134:135], off offset:1664
	global_load_dwordx4 v[190:193], v[136:137], off offset:1664
	s_waitcnt vmcnt(9)
	ds_write_b128 v128, v[194:197] offset:55296
	s_waitcnt vmcnt(8)
	ds_write_b128 v128, v[198:201] offset:64512
	s_waitcnt lgkmcnt(0)
	s_barrier
	ds_read_b128 v[194:197], v163 offset:36864
	ds_read_b128 v[198:201], v163 offset:36896
	ds_read_b128 v[210:213], v163 offset:41472
	ds_read_b128 v[214:217], v163 offset:41504
	ds_read_b128 v[218:221], v154
	ds_read_b128 v[222:225], v154 offset:32
	ds_read_b128 v[226:229], v154 offset:4608
	ds_read_b128 v[230:233], v154 offset:4640
	ds_read_b128 v[234:237], v154 offset:9216
	ds_read_b128 v[238:241], v154 offset:9248
	ds_read_b128 v[242:245], v154 offset:13824
	ds_read_b128 v[246:249], v154 offset:13856
	s_waitcnt lgkmcnt(5)
	v_mfma_f32_32x32x16_bf16 v[80:95], v[226:229], v[194:197], v[80:95]
	v_mfma_f32_32x32x16_bf16 v[64:79], v[226:229], v[210:213], v[64:79]
	s_waitcnt lgkmcnt(3)
	v_mfma_f32_32x32x16_bf16 v[48:63], v[234:237], v[194:197], v[48:63]
	v_mfma_f32_32x32x16_bf16 v[32:47], v[234:237], v[210:213], v[32:47]
	s_waitcnt lgkmcnt(1)
	v_mfma_f32_32x32x16_bf16 v[16:31], v[242:245], v[194:197], v[16:31]
	v_mfma_f32_32x32x16_bf16 v[0:15], v[242:245], v[210:213], v[0:15]
	v_mfma_f32_32x32x16_bf16 v[112:127], v[218:221], v[194:197], v[112:127]
	v_mfma_f32_32x32x16_bf16 v[96:111], v[218:221], v[210:213], v[96:111]
	global_load_dwordx4 v[194:197], v[148:149], off offset:1792
	global_load_dwordx4 v[210:213], v[150:151], off offset:1792
	s_waitcnt vmcnt(9)
	ds_write_b128 v164, v[172:175]
	s_waitcnt vmcnt(8)
	ds_write_b128 v164, v[202:205] offset:9216
	ds_read_b128 v[172:175], v163 offset:36928
	ds_read_b128 v[202:205], v163 offset:41536
	ds_read_b128 v[218:221], v154 offset:64
	ds_read_b128 v[226:229], v154 offset:4672
	ds_read_b128 v[234:237], v154 offset:9280
	ds_read_b128 v[242:245], v154 offset:13888
	v_mfma_f32_32x32x16_bf16 v[80:95], v[230:233], v[198:201], v[80:95]
	v_mfma_f32_32x32x16_bf16 v[64:79], v[230:233], v[214:217], v[64:79]
	v_mfma_f32_32x32x16_bf16 v[48:63], v[238:241], v[198:201], v[48:63]
	v_mfma_f32_32x32x16_bf16 v[32:47], v[238:241], v[214:217], v[32:47]
	s_waitcnt lgkmcnt(8)
	v_mfma_f32_32x32x16_bf16 v[16:31], v[246:249], v[198:201], v[16:31]
	v_mfma_f32_32x32x16_bf16 v[0:15], v[246:249], v[214:217], v[0:15]
	v_mfma_f32_32x32x16_bf16 v[112:127], v[222:225], v[198:201], v[112:127]
	v_mfma_f32_32x32x16_bf16 v[96:111], v[222:225], v[214:217], v[96:111]
	global_load_dwordx4 v[198:201], v[144:145], off offset:1792
	global_load_dwordx4 v[214:217], v[146:147], off offset:1792
	s_waitcnt vmcnt(9)
	ds_write_b128 v164, v[182:185] offset:18432
	s_waitcnt vmcnt(8)
	ds_write_b128 v164, v[206:209] offset:27648
	ds_read_b128 v[182:185], v163 offset:36960
	ds_read_b128 v[206:209], v163 offset:41568
	ds_read_b128 v[222:225], v154 offset:96
	ds_read_b128 v[230:233], v154 offset:4704
	ds_read_b128 v[238:241], v154 offset:9312
	ds_read_b128 v[246:249], v154 offset:13920
	s_waitcnt lgkmcnt(10)
	v_mfma_f32_32x32x16_bf16 v[80:95], v[226:229], v[172:175], v[80:95]
	v_mfma_f32_32x32x16_bf16 v[64:79], v[226:229], v[202:205], v[64:79]
	s_waitcnt lgkmcnt(9)
	v_mfma_f32_32x32x16_bf16 v[48:63], v[234:237], v[172:175], v[48:63]
	v_mfma_f32_32x32x16_bf16 v[32:47], v[234:237], v[202:205], v[32:47]
	s_waitcnt lgkmcnt(8)
	v_mfma_f32_32x32x16_bf16 v[16:31], v[242:245], v[172:175], v[16:31]
	v_mfma_f32_32x32x16_bf16 v[0:15], v[242:245], v[202:205], v[0:15]
	v_mfma_f32_32x32x16_bf16 v[112:127], v[218:221], v[172:175], v[112:127]
	v_mfma_f32_32x32x16_bf16 v[96:111], v[218:221], v[202:205], v[96:111]
	s_waitcnt vmcnt(7)
	ds_write_b128 v165, v[130:133]
	global_load_dwordx4 v[130:133], v[140:141], off offset:1792
	s_waitcnt vmcnt(7)
	ds_write_b128 v166, v[158:161]
	global_load_dwordx4 v[158:161], v[138:139], off offset:1792
	s_waitcnt lgkmcnt(4)
	v_mfma_f32_32x32x16_bf16 v[80:95], v[230:233], v[182:185], v[80:95]
	v_mfma_f32_32x32x16_bf16 v[64:79], v[230:233], v[206:209], v[64:79]
	s_waitcnt lgkmcnt(3)
	v_mfma_f32_32x32x16_bf16 v[48:63], v[238:241], v[182:185], v[48:63]
	v_mfma_f32_32x32x16_bf16 v[32:47], v[238:241], v[206:209], v[32:47]
	s_waitcnt lgkmcnt(2)
	v_mfma_f32_32x32x16_bf16 v[16:31], v[246:249], v[182:185], v[16:31]
	v_mfma_f32_32x32x16_bf16 v[0:15], v[246:249], v[206:209], v[0:15]
	v_mfma_f32_32x32x16_bf16 v[112:127], v[222:225], v[182:185], v[112:127]
	v_mfma_f32_32x32x16_bf16 v[96:111], v[222:225], v[206:209], v[96:111]
	global_load_dwordx4 v[172:175], v[134:135], off offset:1792
	global_load_dwordx4 v[182:185], v[136:137], off offset:1792
	s_waitcnt vmcnt(9)
	ds_write_b128 v167, v[186:189]
	s_waitcnt vmcnt(8)
	ds_write_b128 v168, v[190:193]
	s_waitcnt lgkmcnt(0)
	s_barrier
	ds_read_b128 v[186:189], v169
	ds_read_b128 v[190:193], v169 offset:32
	ds_read_b128 v[202:205], v169 offset:4608
	ds_read_b128 v[206:209], v169 offset:4640
	ds_read_b128 v[218:221], v155
	ds_read_b128 v[222:225], v155 offset:32
	ds_read_b128 v[226:229], v155 offset:4608
	ds_read_b128 v[230:233], v155 offset:4640
	ds_read_b128 v[234:237], v155 offset:9216
	ds_read_b128 v[238:241], v155 offset:9248
	ds_read_b128 v[242:245], v155 offset:13824
	ds_read_b128 v[246:249], v155 offset:13856
	s_waitcnt lgkmcnt(5)
	v_mfma_f32_32x32x16_bf16 v[80:95], v[226:229], v[186:189], v[80:95]
	v_mfma_f32_32x32x16_bf16 v[64:79], v[226:229], v[202:205], v[64:79]
	s_waitcnt lgkmcnt(3)
	v_mfma_f32_32x32x16_bf16 v[48:63], v[234:237], v[186:189], v[48:63]
	v_mfma_f32_32x32x16_bf16 v[32:47], v[234:237], v[202:205], v[32:47]
	s_waitcnt lgkmcnt(1)
	v_mfma_f32_32x32x16_bf16 v[16:31], v[242:245], v[186:189], v[16:31]
	v_mfma_f32_32x32x16_bf16 v[0:15], v[242:245], v[202:205], v[0:15]
	v_mfma_f32_32x32x16_bf16 v[112:127], v[218:221], v[186:189], v[112:127]
	v_mfma_f32_32x32x16_bf16 v[96:111], v[218:221], v[202:205], v[96:111]
	global_load_dwordx4 v[186:189], v[148:149], off offset:1920
	s_nop 0
	global_load_dwordx4 v[148:151], v[150:151], off offset:1920
	s_waitcnt vmcnt(9)
	ds_write_b128 v128, v[194:197]
	s_waitcnt vmcnt(8)
	ds_write_b128 v128, v[210:213] offset:9216
	ds_read_b128 v[194:197], v169 offset:64
	ds_read_b128 v[202:205], v169 offset:4672
	ds_read_b128 v[210:213], v155 offset:64
	ds_read_b128 v[218:221], v155 offset:4672
	ds_read_b128 v[226:229], v155 offset:9280
	ds_read_b128 v[234:237], v155 offset:13888
	v_mfma_f32_32x32x16_bf16 v[80:95], v[230:233], v[190:193], v[80:95]
	v_mfma_f32_32x32x16_bf16 v[64:79], v[230:233], v[206:209], v[64:79]
	v_mfma_f32_32x32x16_bf16 v[48:63], v[238:241], v[190:193], v[48:63]
	v_mfma_f32_32x32x16_bf16 v[32:47], v[238:241], v[206:209], v[32:47]
	s_waitcnt lgkmcnt(8)
	v_mfma_f32_32x32x16_bf16 v[16:31], v[246:249], v[190:193], v[16:31]
	v_mfma_f32_32x32x16_bf16 v[0:15], v[246:249], v[206:209], v[0:15]
	v_mfma_f32_32x32x16_bf16 v[112:127], v[222:225], v[190:193], v[112:127]
	v_mfma_f32_32x32x16_bf16 v[96:111], v[222:225], v[206:209], v[96:111]
	global_load_dwordx4 v[190:193], v[144:145], off offset:1920
	s_nop 0
	global_load_dwordx4 v[144:147], v[146:147], off offset:1920
	s_waitcnt vmcnt(9)
	ds_write_b128 v128, v[198:201] offset:18432
	s_waitcnt vmcnt(8)
	ds_write_b128 v128, v[214:217] offset:27648
	ds_read_b128 v[198:201], v169 offset:96
	ds_read_b128 v[206:209], v169 offset:4704
	ds_read_b128 v[214:217], v155 offset:96
	ds_read_b128 v[222:225], v155 offset:4704
	ds_read_b128 v[230:233], v155 offset:9312
	ds_read_b128 v[238:241], v155 offset:13920
	s_waitcnt lgkmcnt(10)
	v_mfma_f32_32x32x16_bf16 v[80:95], v[218:221], v[194:197], v[80:95]
	v_mfma_f32_32x32x16_bf16 v[64:79], v[218:221], v[202:205], v[64:79]
	s_waitcnt lgkmcnt(9)
	v_mfma_f32_32x32x16_bf16 v[48:63], v[226:229], v[194:197], v[48:63]
	v_mfma_f32_32x32x16_bf16 v[32:47], v[226:229], v[202:205], v[32:47]
	s_waitcnt lgkmcnt(8)
	v_mfma_f32_32x32x16_bf16 v[16:31], v[234:237], v[194:197], v[16:31]
	v_mfma_f32_32x32x16_bf16 v[0:15], v[234:237], v[202:205], v[0:15]
	v_mfma_f32_32x32x16_bf16 v[112:127], v[210:213], v[194:197], v[112:127]
	v_mfma_f32_32x32x16_bf16 v[96:111], v[210:213], v[202:205], v[96:111]
	s_waitcnt vmcnt(7)
	ds_write_b128 v128, v[130:133] offset:36864
	global_load_dwordx4 v[130:133], v[140:141], off offset:1920
	s_waitcnt vmcnt(7)
	ds_write_b128 v128, v[158:161] offset:46080
	global_load_dwordx4 v[138:141], v[138:139], off offset:1920
	s_waitcnt lgkmcnt(4)
	v_mfma_f32_32x32x16_bf16 v[80:95], v[222:225], v[198:201], v[80:95]
	v_mfma_f32_32x32x16_bf16 v[64:79], v[222:225], v[206:209], v[64:79]
	s_waitcnt lgkmcnt(3)
	v_mfma_f32_32x32x16_bf16 v[48:63], v[230:233], v[198:201], v[48:63]
	v_mfma_f32_32x32x16_bf16 v[32:47], v[230:233], v[206:209], v[32:47]
	s_waitcnt lgkmcnt(2)
	v_mfma_f32_32x32x16_bf16 v[16:31], v[238:241], v[198:201], v[16:31]
	v_mfma_f32_32x32x16_bf16 v[0:15], v[238:241], v[206:209], v[0:15]
	v_mfma_f32_32x32x16_bf16 v[112:127], v[214:217], v[198:201], v[112:127]
	v_mfma_f32_32x32x16_bf16 v[96:111], v[214:217], v[206:209], v[96:111]
	global_load_dwordx4 v[158:161], v[134:135], off offset:1920
	s_nop 0
	global_load_dwordx4 v[134:137], v[136:137], off offset:1920
	s_waitcnt vmcnt(9)
	ds_write_b128 v128, v[172:175] offset:55296
	s_waitcnt vmcnt(8)
	ds_write_b128 v128, v[182:185] offset:64512
	s_waitcnt lgkmcnt(0)
	s_barrier
	ds_read_b128 v[172:175], v163 offset:36864
	ds_read_b128 v[182:185], v163 offset:36896
	ds_read_b128 v[194:197], v163 offset:41472
	ds_read_b128 v[198:201], v163 offset:41504
	ds_read_b128 v[202:205], v154
	ds_read_b128 v[206:209], v154 offset:32
	ds_read_b128 v[210:213], v154 offset:4608
	ds_read_b128 v[214:217], v154 offset:4640
	ds_read_b128 v[218:221], v154 offset:9216
	ds_read_b128 v[222:225], v154 offset:9248
	ds_read_b128 v[226:229], v154 offset:13824
	ds_read_b128 v[230:233], v154 offset:13856
	s_waitcnt lgkmcnt(5)
	v_mfma_f32_32x32x16_bf16 v[80:95], v[210:213], v[172:175], v[80:95]
	v_mfma_f32_32x32x16_bf16 v[64:79], v[210:213], v[194:197], v[64:79]
	s_waitcnt lgkmcnt(3)
	v_mfma_f32_32x32x16_bf16 v[48:63], v[218:221], v[172:175], v[48:63]
	v_mfma_f32_32x32x16_bf16 v[32:47], v[218:221], v[194:197], v[32:47]
	s_waitcnt lgkmcnt(1)
	v_mfma_f32_32x32x16_bf16 v[16:31], v[226:229], v[172:175], v[16:31]
	v_mfma_f32_32x32x16_bf16 v[0:15], v[226:229], v[194:197], v[0:15]
	v_mfma_f32_32x32x16_bf16 v[112:127], v[202:205], v[172:175], v[112:127]
	v_mfma_f32_32x32x16_bf16 v[96:111], v[202:205], v[194:197], v[96:111]
	s_waitcnt vmcnt(7)
	ds_write_b128 v164, v[186:189]
	s_waitcnt vmcnt(6)
	ds_write_b128 v164, v[148:151] offset:9216
	ds_read_b128 v[148:151], v163 offset:36928
	ds_read_b128 v[172:175], v163 offset:41536
	ds_read_b128 v[186:189], v154 offset:64
	ds_read_b128 v[194:197], v154 offset:4672
	ds_read_b128 v[202:205], v154 offset:9280
	ds_read_b128 v[210:213], v154 offset:13888
	v_mfma_f32_32x32x16_bf16 v[80:95], v[214:217], v[182:185], v[80:95]
	v_mfma_f32_32x32x16_bf16 v[64:79], v[214:217], v[198:201], v[64:79]
	v_mfma_f32_32x32x16_bf16 v[48:63], v[222:225], v[182:185], v[48:63]
	v_mfma_f32_32x32x16_bf16 v[32:47], v[222:225], v[198:201], v[32:47]
	s_waitcnt lgkmcnt(8)
	v_mfma_f32_32x32x16_bf16 v[16:31], v[230:233], v[182:185], v[16:31]
	v_mfma_f32_32x32x16_bf16 v[0:15], v[230:233], v[198:201], v[0:15]
	v_mfma_f32_32x32x16_bf16 v[112:127], v[206:209], v[182:185], v[112:127]
	v_mfma_f32_32x32x16_bf16 v[96:111], v[206:209], v[198:201], v[96:111]
	s_waitcnt vmcnt(5)
	ds_write_b128 v164, v[190:193] offset:18432
	s_waitcnt vmcnt(4)
	ds_write_b128 v164, v[144:147] offset:27648
	ds_read_b128 v[144:147], v163 offset:36960
	ds_read_b128 v[182:185], v163 offset:41568
	ds_read_b128 v[190:193], v154 offset:96
	ds_read_b128 v[198:201], v154 offset:4704
	ds_read_b128 v[206:209], v154 offset:9312
	ds_read_b128 v[214:217], v154 offset:13920
	s_waitcnt lgkmcnt(10)
	v_mfma_f32_32x32x16_bf16 v[80:95], v[194:197], v[148:151], v[80:95]
	v_mfma_f32_32x32x16_bf16 v[64:79], v[194:197], v[172:175], v[64:79]
	s_waitcnt lgkmcnt(9)
	v_mfma_f32_32x32x16_bf16 v[48:63], v[202:205], v[148:151], v[48:63]
	v_mfma_f32_32x32x16_bf16 v[32:47], v[202:205], v[172:175], v[32:47]
	s_waitcnt lgkmcnt(8)
	v_mfma_f32_32x32x16_bf16 v[16:31], v[210:213], v[148:151], v[16:31]
	v_mfma_f32_32x32x16_bf16 v[0:15], v[210:213], v[172:175], v[0:15]
	v_mfma_f32_32x32x16_bf16 v[112:127], v[186:189], v[148:151], v[112:127]
	v_mfma_f32_32x32x16_bf16 v[96:111], v[186:189], v[172:175], v[96:111]
	s_waitcnt vmcnt(3)
	ds_write_b128 v165, v[130:133]
	s_waitcnt vmcnt(2)
	ds_write_b128 v166, v[138:141]
	s_waitcnt lgkmcnt(4)
	v_mfma_f32_32x32x16_bf16 v[80:95], v[198:201], v[144:147], v[80:95]
	v_mfma_f32_32x32x16_bf16 v[64:79], v[198:201], v[182:185], v[64:79]
	s_waitcnt lgkmcnt(3)
	v_mfma_f32_32x32x16_bf16 v[48:63], v[206:209], v[144:147], v[48:63]
	v_mfma_f32_32x32x16_bf16 v[32:47], v[206:209], v[182:185], v[32:47]
	s_waitcnt lgkmcnt(2)
	v_mfma_f32_32x32x16_bf16 v[16:31], v[214:217], v[144:147], v[16:31]
	v_mfma_f32_32x32x16_bf16 v[0:15], v[214:217], v[182:185], v[0:15]
	v_mfma_f32_32x32x16_bf16 v[112:127], v[190:193], v[144:147], v[112:127]
	v_mfma_f32_32x32x16_bf16 v[96:111], v[190:193], v[182:185], v[96:111]
	s_waitcnt vmcnt(1)
	ds_write_b128 v167, v[158:161]
	s_waitcnt vmcnt(0)
	ds_write_b128 v168, v[134:137]
	s_waitcnt lgkmcnt(0)
	s_barrier
	ds_read_b128 v[130:133], v169
	ds_read_b128 v[134:137], v169 offset:32
	ds_read_b128 v[138:141], v169 offset:4608
	ds_read_b128 v[144:147], v169 offset:4640
	ds_read_b128 v[148:151], v155
	ds_read_b128 v[158:161], v155 offset:32
	ds_read_b128 v[172:175], v155 offset:4608
	ds_read_b128 v[182:185], v155 offset:4640
	ds_read_b128 v[186:189], v155 offset:9216
	ds_read_b128 v[190:193], v155 offset:9248
	ds_read_b128 v[194:197], v155 offset:13824
	ds_read_b128 v[198:201], v155 offset:13856
	s_waitcnt lgkmcnt(5)
	v_mfma_f32_32x32x16_bf16 v[80:95], v[172:175], v[130:133], v[80:95]
	v_mfma_f32_32x32x16_bf16 v[64:79], v[172:175], v[138:141], v[64:79]
	s_waitcnt lgkmcnt(3)
	v_mfma_f32_32x32x16_bf16 v[48:63], v[186:189], v[130:133], v[48:63]
	v_mfma_f32_32x32x16_bf16 v[32:47], v[186:189], v[138:141], v[32:47]
	s_waitcnt lgkmcnt(1)
	v_mfma_f32_32x32x16_bf16 v[16:31], v[194:197], v[130:133], v[16:31]
	v_mfma_f32_32x32x16_bf16 v[0:15], v[194:197], v[138:141], v[0:15]
	v_mfma_f32_32x32x16_bf16 v[112:127], v[148:151], v[130:133], v[112:127]
	v_mfma_f32_32x32x16_bf16 v[96:111], v[148:151], v[138:141], v[96:111]
	ds_read_b128 v[130:133], v169 offset:64
	ds_read_b128 v[138:141], v169 offset:4672
	ds_read_b128 v[148:151], v155 offset:64
	ds_read_b128 v[172:175], v155 offset:4672
	ds_read_b128 v[186:189], v155 offset:9280
	ds_read_b128 v[194:197], v155 offset:13888
	v_mfma_f32_32x32x16_bf16 v[80:95], v[182:185], v[134:137], v[80:95]
	v_mfma_f32_32x32x16_bf16 v[64:79], v[182:185], v[144:147], v[64:79]
	v_mfma_f32_32x32x16_bf16 v[48:63], v[190:193], v[134:137], v[48:63]
	v_mfma_f32_32x32x16_bf16 v[32:47], v[190:193], v[144:147], v[32:47]
	s_waitcnt lgkmcnt(6)
	v_mfma_f32_32x32x16_bf16 v[16:31], v[198:201], v[134:137], v[16:31]
	v_mfma_f32_32x32x16_bf16 v[0:15], v[198:201], v[144:147], v[0:15]
	v_mfma_f32_32x32x16_bf16 v[112:127], v[158:161], v[134:137], v[112:127]
	v_mfma_f32_32x32x16_bf16 v[96:111], v[158:161], v[144:147], v[96:111]
	ds_read_b128 v[134:137], v169 offset:96
	ds_read_b128 v[144:147], v169 offset:4704
	ds_read_b128 v[158:161], v155 offset:96
	ds_read_b128 v[182:185], v155 offset:4704
	ds_read_b128 v[190:193], v155 offset:9312
	ds_read_b128 v[198:201], v155 offset:13920
	s_waitcnt lgkmcnt(8)
	v_mfma_f32_32x32x16_bf16 v[80:95], v[172:175], v[130:133], v[80:95]
	v_mfma_f32_32x32x16_bf16 v[64:79], v[172:175], v[138:141], v[64:79]
	s_waitcnt lgkmcnt(7)
	v_mfma_f32_32x32x16_bf16 v[48:63], v[186:189], v[130:133], v[48:63]
	v_mfma_f32_32x32x16_bf16 v[32:47], v[186:189], v[138:141], v[32:47]
	s_waitcnt lgkmcnt(6)
	v_mfma_f32_32x32x16_bf16 v[16:31], v[194:197], v[130:133], v[16:31]
	v_mfma_f32_32x32x16_bf16 v[0:15], v[194:197], v[138:141], v[0:15]
	v_mfma_f32_32x32x16_bf16 v[112:127], v[148:151], v[130:133], v[112:127]
	v_mfma_f32_32x32x16_bf16 v[96:111], v[148:151], v[138:141], v[96:111]
	s_waitcnt lgkmcnt(2)
	v_mfma_f32_32x32x16_bf16 v[80:95], v[182:185], v[134:137], v[80:95]
	v_mfma_f32_32x32x16_bf16 v[64:79], v[182:185], v[144:147], v[64:79]
	s_waitcnt lgkmcnt(1)
	v_mfma_f32_32x32x16_bf16 v[48:63], v[190:193], v[134:137], v[48:63]
	v_mfma_f32_32x32x16_bf16 v[32:47], v[190:193], v[144:147], v[32:47]
	s_waitcnt lgkmcnt(0)
	v_mfma_f32_32x32x16_bf16 v[16:31], v[198:201], v[134:137], v[16:31]
	v_mfma_f32_32x32x16_bf16 v[0:15], v[198:201], v[144:147], v[0:15]
	v_mfma_f32_32x32x16_bf16 v[112:127], v[158:161], v[134:137], v[112:127]
	v_mfma_f32_32x32x16_bf16 v[96:111], v[158:161], v[144:147], v[96:111]
	s_mov_b32 s79, 0
	s_add_i32 s14, s4, s5
	s_cmp_lt_i32 s14, s6
	s_cbranch_scc0 .Lpfi_skip
	s_mul_hi_i32 s15, s14, 0x2e8ba2e9
	s_lshr_b32 s16, s15, 31
	s_ashr_i32 s15, s15, 1
	s_add_i32 s15, s15, s16
	s_mul_i32 s16, s15, -11
	s_add_i32 s16, s14, s16
	s_add_i32 s15, s15, s7
	s_cmp_eq_u64 s[90:91], 0
	s_cbranch_scc1 .Lpfi_ok
	s_cmpk_gt_i32 s15, 0x7f
	s_cbranch_scc0 .Lpfi_ok
	s_add_i32 s17, s16, -3
	s_cmp_lt_u32 s17, -2
	s_cbranch_scc1 .Lpfi_skip
.Lpfi_ok:
	s_lshl_b32 s15, s15, 19
	s_add_u32 s18, s82, s15
	s_addc_u32 s19, s83, 0
	s_lshl_b32 s16, s16, 19
	s_add_u32 s20, s80, s16
	s_addc_u32 s21, s81, 0
	v_lshrrev_b32_e32 v132, 3, v143
	v_lshlrev_b32_e32 v132, 11, v132
	v_and_b32_e32 v133, 7, v143
	v_lshl_add_u32 v132, v133, 4, v132
	global_load_dwordx4 v[210:213], v132, s[18:19]
	s_add_u32 s18, s18, 0x20000
	s_addc_u32 s19, s19, 0
	global_load_dwordx4 v[214:217], v132, s[18:19]
	s_add_u32 s18, s18, 0x20000
	s_addc_u32 s19, s19, 0
	global_load_dwordx4 v[218:221], v132, s[18:19]
	s_add_u32 s18, s18, 0x20000
	s_addc_u32 s19, s19, 0
	global_load_dwordx4 v[222:225], v132, s[18:19]
	global_load_dwordx4 v[226:229], v132, s[20:21]
	s_add_u32 s20, s20, 0x20000
	s_addc_u32 s21, s21, 0
	global_load_dwordx4 v[238:241], v132, s[20:21]
	s_add_u32 s20, s20, 0x20000
	s_addc_u32 s21, s21, 0
	global_load_dwordx4 v[242:245], v132, s[20:21]
	s_add_u32 s20, s20, 0x20000
	s_addc_u32 s21, s21, 0
	global_load_dwordx4 v[246:249], v132, s[20:21]
	s_mov_b32 s79, 1
.Lpfi_skip:
	v_add_u32_e32 v130, s1, v179
	s_movk_i32 s1, 0xa20
	v_ashrrev_i32_e32 v131, 31, v130
	v_cmp_gt_i32_e32 vcc, s1, v130
	v_lshl_add_u64 v[134:135], v[130:131], 1, s[60:61]
	s_nop 5
	v_bfe_u32 v130, v112, 16, 1
	v_add3_u32 v112, v112, v130, s24
	s_barrier
	ds_write_b16_d16_hi v156, v112
	v_bfe_u32 v112, v113, 16, 1
	v_add3_u32 v112, v113, v112, s24
	ds_write_b16_d16_hi v156, v112 offset:144
	v_bfe_u32 v112, v114, 16, 1
	v_add3_u32 v112, v114, v112, s24
	ds_write_b16_d16_hi v156, v112 offset:288
	v_bfe_u32 v112, v115, 16, 1
	v_add3_u32 v112, v115, v112, s24
	ds_write_b16_d16_hi v156, v112 offset:432
	v_bfe_u32 v112, v116, 16, 1
	v_add3_u32 v112, v116, v112, s24
	ds_write_b16_d16_hi v156, v112 offset:1152
	v_bfe_u32 v112, v117, 16, 1
	v_add3_u32 v112, v117, v112, s24
	ds_write_b16_d16_hi v156, v112 offset:1296
	v_bfe_u32 v112, v118, 16, 1
	v_add3_u32 v112, v118, v112, s24
	ds_write_b16_d16_hi v156, v112 offset:1440
	v_bfe_u32 v112, v119, 16, 1
	v_add3_u32 v112, v119, v112, s24
	ds_write_b16_d16_hi v156, v112 offset:1584
	v_bfe_u32 v112, v120, 16, 1
	v_add3_u32 v112, v120, v112, s24
	ds_write_b16_d16_hi v156, v112 offset:2304
	v_bfe_u32 v112, v121, 16, 1
	v_add3_u32 v112, v121, v112, s24
	ds_write_b16_d16_hi v156, v112 offset:2448
	v_bfe_u32 v112, v122, 16, 1
	v_add3_u32 v112, v122, v112, s24
	ds_write_b16_d16_hi v156, v112 offset:2592
	v_bfe_u32 v112, v123, 16, 1
	v_add3_u32 v112, v123, v112, s24
	ds_write_b16_d16_hi v156, v112 offset:2736
	v_bfe_u32 v112, v124, 16, 1
	v_add3_u32 v112, v124, v112, s24
	ds_write_b16_d16_hi v156, v112 offset:3456
	v_bfe_u32 v112, v125, 16, 1
	v_add3_u32 v112, v125, v112, s24
	ds_write_b16_d16_hi v156, v112 offset:3600
	v_bfe_u32 v112, v126, 16, 1
	v_add3_u32 v112, v126, v112, s24
	ds_write_b16_d16_hi v156, v112 offset:3744
	v_bfe_u32 v112, v127, 16, 1
	v_add3_u32 v112, v127, v112, s24
	ds_write_b16_d16_hi v156, v112 offset:3888
	v_bfe_u32 v112, v96, 16, 1
	v_add3_u32 v96, v96, v112, s24
	ds_write_b16_d16_hi v156, v96 offset:64
	v_bfe_u32 v96, v97, 16, 1
	v_add3_u32 v96, v97, v96, s24
	ds_write_b16_d16_hi v156, v96 offset:208
	v_bfe_u32 v96, v98, 16, 1
	v_add3_u32 v96, v98, v96, s24
	ds_write_b16_d16_hi v156, v96 offset:352
	v_bfe_u32 v96, v99, 16, 1
	v_add3_u32 v96, v99, v96, s24
	ds_write_b16_d16_hi v156, v96 offset:496
	v_bfe_u32 v96, v100, 16, 1
	v_add3_u32 v96, v100, v96, s24
	ds_write_b16_d16_hi v156, v96 offset:1216
	v_bfe_u32 v96, v101, 16, 1
	v_add3_u32 v96, v101, v96, s24
	ds_write_b16_d16_hi v156, v96 offset:1360
	v_bfe_u32 v96, v102, 16, 1
	v_add3_u32 v96, v102, v96, s24
	ds_write_b16_d16_hi v156, v96 offset:1504
	v_bfe_u32 v96, v103, 16, 1
	v_add3_u32 v96, v103, v96, s24
	ds_write_b16_d16_hi v156, v96 offset:1648
	v_bfe_u32 v96, v104, 16, 1
	v_add3_u32 v96, v104, v96, s24
	ds_write_b16_d16_hi v156, v96 offset:2368
	v_bfe_u32 v96, v105, 16, 1
	v_add3_u32 v96, v105, v96, s24
	ds_write_b16_d16_hi v156, v96 offset:2512
	v_bfe_u32 v96, v106, 16, 1
	v_add3_u32 v96, v106, v96, s24
	ds_write_b16_d16_hi v156, v96 offset:2656
	v_bfe_u32 v96, v107, 16, 1
	v_add3_u32 v96, v107, v96, s24
	ds_write_b16_d16_hi v156, v96 offset:2800
	v_bfe_u32 v96, v108, 16, 1
	v_add3_u32 v96, v108, v96, s24
	ds_write_b16_d16_hi v156, v96 offset:3520
	v_bfe_u32 v96, v109, 16, 1
	v_add3_u32 v96, v109, v96, s24
	ds_write_b16_d16_hi v156, v96 offset:3664
	v_bfe_u32 v96, v110, 16, 1
	v_add3_u32 v96, v110, v96, s24
	ds_write_b16_d16_hi v156, v96 offset:3808
	v_bfe_u32 v96, v111, 16, 1
	v_add_u32_e32 v136, s0, v153
	v_add3_u32 v96, v111, v96, s24
	ds_write_b16_d16_hi v156, v96 offset:3952
	s_and_saveexec_b64 s[0:1], vcc
	s_cbranch_execz .LBB0_242
	ds_read_b128 v[96:99], v170
	v_or_b32_e32 v100, v136, v157
	v_mad_i64_i32 v[100:101], s[10:11], v100, s33, v[134:135]
	s_waitcnt lgkmcnt(0)
	global_store_dwordx4 v[100:101], v[96:99], off
	ds_read_b128 v[96:99], v170 offset:1152
	v_or_b32_e32 v100, v136, v171
	v_mad_i64_i32 v[100:101], s[10:11], v100, s33, v[134:135]
	s_waitcnt lgkmcnt(0)
	global_store_dwordx4 v[100:101], v[96:99], off
	ds_read_b128 v[96:99], v170 offset:2304
	v_or_b32_e32 v100, v136, v252
	v_mad_i64_i32 v[100:101], s[10:11], v100, s33, v[134:135]
	s_waitcnt lgkmcnt(0)
	global_store_dwordx4 v[100:101], v[96:99], off
	ds_read_b128 v[96:99], v170 offset:3456
	v_or_b32_e32 v100, v136, v181
	v_mad_i64_i32 v[100:101], s[10:11], v100, s33, v[134:135]
	s_waitcnt lgkmcnt(0)
	global_store_dwordx4 v[100:101], v[96:99], off

.Lgo_235:
	s_and_b32 s1, 0xffff, s1
	s_and_b64 s[6:7], s[90:91], exec
	s_movk_i32 s6, 0x80
	s_cselect_b32 s6, s6, 0x88
	s_lshr_b32 s1, s6, s1
	s_lshl_b32 s6, s1, 2
	s_cmp_ge_i32 s4, s6
	s_cbranch_scc1 .Lgo_end
	v_readlane_b32 s82, v253, 38
	v_readlane_b32 s83, v253, 39
	s_lshl_b32 s80, s74, 21
	s_add_u32 s80, s80, 0xc40000
	s_add_u32 s80, s50, s80
	s_addc_u32 s81, s51, 0
	s_mov_b32 s79, 0
	v_ashrrev_i32_e32 v1, 6, v0
	v_lshrrev_b32_e32 v3, 30, v1
	v_add_u32_e32 v3, v1, v3
	s_mul_i32 s7, s0, s1
	s_lshl_b32 s0, s74, 21
	s_add_u32 s0, s0, 0xc40000
	v_ashrrev_i32_e32 v3, 2, v3
	s_add_u32 s0, s50, s0
	s_waitcnt vmcnt(6)
	v_and_b32_e32 v4, 7, v0
	v_mul_i32_i24_e32 v8, 4, v3
	s_addc_u32 s1, s51, 0
	v_and_b32_e32 v2, 31, v0
	v_lshlrev_b32_e32 v128, 4, v4
	v_sub_u32_e32 v9, v1, v8
	v_lshlrev_b32_e32 v153, 7, v3
	v_ashrrev_i32_e32 v152, 3, v0
	v_bfe_u32 v6, v0, 5, 1
	v_readlane_b32 s8, v253, 38
	v_lshl_add_u64 v[176:177], s[0:1], 0, v[128:129]
	s_movk_i32 s0, 0x90
	v_or_b32_e32 v3, v153, v2
	v_lshl_or_b32 v9, v9, 6, v2
	v_readlane_b32 s9, v253, 39
	v_mul_lo_u32 v7, v152, s0
	v_mul_lo_u32 v3, v3, s0
	v_lshlrev_b32_e32 v10, 4, v6
	v_mul_lo_u32 v9, v9, s0
	v_readlane_b32 s0, v255, 15
	v_readlane_b32 s1, v255, 16
	v_lshl_add_u64 v[250:251], s[8:9], 0, v[128:129]
	v_add3_u32 v154, 0, v3, v10
	v_add_u32_e32 v13, s1, v7
	v_readlane_b32 s8, v255, 17
	v_add3_u32 v155, s0, v3, v10
	v_add_u32_e32 v3, s1, v9
	s_movk_i32 s1, 0x1200
	v_add_u32_e32 v14, s8, v7
	v_readlane_b32 s8, v255, 18
	v_mul_lo_u32 v1, v1, s1
	v_lshlrev_b32_e32 v5, 3, v4
	v_add_u32_e32 v12, s0, v7
	v_add_u32_e32 v15, s8, v7
	v_readlane_b32 s8, v255, 19
	v_add_u32_e32 v1, s0, v1
	v_lshlrev_b32_e32 v2, 1, v2
	v_mul_u32_u24_e32 v6, 0x240, v6
	v_bfe_u32 v157, v0, 3, 3
	s_movk_i32 s0, 0xffc0
	v_add_u32_e32 v4, 0, v128
	v_add_u32_e32 v11, 0, v9
	s_waitcnt vmcnt(3)
	v_add_u32_e32 v16, s8, v7
	v_add_u32_e32 v9, 0, v7
	v_add_u32_e32 v17, v1, v128
	v_add3_u32 v156, v1, v2, v6
	v_mul_u32_u24_e32 v1, 0x90, v157
	v_and_or_b32 v0, v0, s0, v5
	v_lshlrev_b32_e32 v2, 6, v8
	v_mov_b32_e32 v180, 0x2000
	v_or_b32_e32 v171, 8, v157
	v_or_b32_e32 v252, 16, v157
	v_or_b32_e32 v181, 24, v157
	v_sub_u32_e32 v179, v0, v2
	s_lshl_b32 s8, s4, 8
	s_lshl_b32 s9, s5, 8
	v_add_u32_e32 v162, v4, v7
	v_add_u32_e32 v163, v11, v10
	v_add_u32_e32 v164, v12, v128
	v_add_u32_e32 v165, v13, v128
	v_add_u32_e32 v166, v14, v128
	v_add_u32_e32 v167, v15, v128
	v_add_u32_e32 v168, v16, v128
	v_add_u32_e32 v169, v3, v10
	v_add_u32_e32 v128, v9, v128
	v_add_u32_e32 v170, v17, v1
	s_branch .Lgo_239

.Lgo_239:
	s_ashr_i32 s1, s4, 2
	s_add_i32 s0, s1, s7
	s_cmp_eq_u32 s79, 0
	s_cbranch_scc1 .Lpfg_norm
	s_lshl_b32 s0, s0, 8
	v_add_u32_e32 v0, s0, v152
	v_ashrrev_i32_e32 v1, 31, v0
	v_lshlrev_b64 v[0:1], 11, v[0:1]
	s_mulk_i32 s1, 0xfc00
	v_lshl_add_u64 v[148:149], v[250:251], 0, v[0:1]
	s_add_i32 s1, s1, s8
	v_add_co_u32_e32 v150, vcc, 0x20000, v148
	v_add_u32_e32 v2, s1, v152
	s_nop 0
	v_addc_co_u32_e32 v151, vcc, 0, v149, vcc
	v_ashrrev_i32_e32 v3, 31, v2
	v_add_co_u32_e32 v144, vcc, 0x40000, v148
	v_lshlrev_b64 v[16:17], 11, v[2:3]
	s_nop 0
	v_addc_co_u32_e32 v145, vcc, 0, v149, vcc
	v_add_co_u32_e32 v146, vcc, 0x60000, v148
	v_lshl_add_u64 v[140:141], v[176:177], 0, v[16:17]
	v_addc_co_u32_e32 v147, vcc, 0, v149, vcc
	v_add_co_u32_e32 v138, vcc, s94, v140
	s_nop 0
	v_addc_co_u32_e32 v139, vcc, 0, v141, vcc
	v_add_co_u32_e32 v134, vcc, 0x40000, v140
	s_nop 0
	v_addc_co_u32_e32 v135, vcc, 0, v141, vcc
	v_add_co_u32_e32 v136, vcc, s95, v140
	s_nop 1
	v_addc_co_u32_e32 v137, vcc, 0, v141, vcc
	global_load_dwordx4 v[172:175], v[148:149], off offset:128
	global_load_dwordx4 v[182:185], v[150:151], off offset:128
	global_load_dwordx4 v[186:189], v[144:145], off offset:128
	global_load_dwordx4 v[190:193], v[146:147], off offset:128
	global_load_dwordx4 v[194:197], v[140:141], off offset:128
	global_load_dwordx4 v[198:201], v[138:139], off offset:128
	global_load_dwordx4 v[202:205], v[134:135], off offset:128
	global_load_dwordx4 v[206:209], v[136:137], off offset:128
	s_waitcnt vmcnt(8)
	v_mov_b32_e32 v0, v210
	v_mov_b32_e32 v1, v211
	v_mov_b32_e32 v2, v212
	v_mov_b32_e32 v3, v213
	v_mov_b32_e32 v4, v214
	v_mov_b32_e32 v5, v215
	v_mov_b32_e32 v6, v216
	v_mov_b32_e32 v7, v217
	v_mov_b32_e32 v8, v218
	v_mov_b32_e32 v9, v219
	v_mov_b32_e32 v10, v220
	v_mov_b32_e32 v11, v221
	v_mov_b32_e32 v12, v222
	v_mov_b32_e32 v13, v223
	v_mov_b32_e32 v14, v224
	v_mov_b32_e32 v15, v225
	v_mov_b32_e32 v16, v226
	v_mov_b32_e32 v17, v227
	v_mov_b32_e32 v18, v228
	v_mov_b32_e32 v19, v229
	v_mov_b32_e32 v20, v238
	v_mov_b32_e32 v21, v239
	v_mov_b32_e32 v22, v240
	v_mov_b32_e32 v23, v241
	v_mov_b32_e32 v24, v242
	v_mov_b32_e32 v25, v243
	v_mov_b32_e32 v26, v244
	v_mov_b32_e32 v27, v245
	v_mov_b32_e32 v28, v246
	v_mov_b32_e32 v29, v247
	v_mov_b32_e32 v30, v248
	v_mov_b32_e32 v31, v249
	s_branch .Lpfg_join
.Lpfg_norm:
	s_lshl_b32 s0, s0, 8
	v_add_u32_e32 v0, s0, v152
	v_ashrrev_i32_e32 v1, 31, v0
	v_lshlrev_b64 v[0:1], 11, v[0:1]
	s_mulk_i32 s1, 0xfc00
	v_lshl_add_u64 v[148:149], v[250:251], 0, v[0:1]
	s_add_i32 s1, s1, s8
	v_add_co_u32_e32 v150, vcc, 0x20000, v148
	v_add_u32_e32 v2, s1, v152
	s_nop 0
	v_addc_co_u32_e32 v151, vcc, 0, v149, vcc
	v_ashrrev_i32_e32 v3, 31, v2
	v_add_co_u32_e32 v144, vcc, 0x40000, v148
	v_lshlrev_b64 v[16:17], 11, v[2:3]
	s_nop 0
	v_addc_co_u32_e32 v145, vcc, 0, v149, vcc
	global_load_dwordx4 v[0:3], v[148:149], off
	v_add_co_u32_e32 v146, vcc, 0x60000, v148
	v_lshl_add_u64 v[140:141], v[176:177], 0, v[16:17]
	global_load_dwordx4 v[8:11], v[144:145], off
	global_load_dwordx4 v[16:19], v[140:141], off
	v_addc_co_u32_e32 v147, vcc, 0, v149, vcc
	global_load_dwordx4 v[4:7], v[150:151], off
	v_add_co_u32_e32 v138, vcc, s94, v140
	global_load_dwordx4 v[12:15], v[146:147], off
	s_nop 0
	v_addc_co_u32_e32 v139, vcc, 0, v141, vcc
	v_add_co_u32_e32 v134, vcc, 0x40000, v140
	global_load_dwordx4 v[20:23], v[138:139], off
	s_nop 0
	v_addc_co_u32_e32 v135, vcc, 0, v141, vcc
	global_load_dwordx4 v[24:27], v[134:135], off
	v_add_co_u32_e32 v136, vcc, s95, v140
	s_nop 1
	v_addc_co_u32_e32 v137, vcc, 0, v141, vcc
	global_load_dwordx4 v[28:31], v[136:137], off
	global_load_dwordx4 v[172:175], v[148:149], off offset:128
	global_load_dwordx4 v[182:185], v[150:151], off offset:128
	global_load_dwordx4 v[186:189], v[144:145], off offset:128
	global_load_dwordx4 v[190:193], v[146:147], off offset:128
	global_load_dwordx4 v[194:197], v[140:141], off offset:128
	global_load_dwordx4 v[198:201], v[138:139], off offset:128
	global_load_dwordx4 v[202:205], v[134:135], off offset:128
	global_load_dwordx4 v[206:209], v[136:137], off offset:128
.Lpfg_join:
	s_waitcnt vmcnt(15)
	ds_write_b128 v162, v[0:3]
	s_waitcnt vmcnt(13)
	ds_write_b128 v162, v[16:19] offset:36864
	s_waitcnt vmcnt(12)
	ds_write_b128 v162, v[4:7] offset:9216
	ds_write_b128 v162, v[8:11] offset:18432
	s_waitcnt vmcnt(11)
	ds_write_b128 v162, v[12:15] offset:27648
	s_waitcnt vmcnt(10)
	ds_write_b128 v162, v[20:23] offset:46080
	s_waitcnt vmcnt(9)
	ds_write_b128 v162, v[24:27] offset:55296
	s_waitcnt vmcnt(8)
	ds_write_b128 v162, v[28:31] offset:64512
	s_waitcnt lgkmcnt(0)
	s_barrier
	ds_read_b128 v[0:3], v163 offset:36864
	ds_read_b128 v[210:213], v163 offset:36896
	ds_read_b128 v[4:7], v163 offset:41472
	ds_read_b128 v[214:217], v163 offset:41504
	ds_read_b128 v[8:11], v154
	ds_read_b128 v[218:221], v154 offset:32
	ds_read_b128 v[12:15], v154 offset:4608
	ds_read_b128 v[222:225], v154 offset:4640
	ds_read_b128 v[16:19], v154 offset:9216
	ds_read_b128 v[226:229], v154 offset:9248
	ds_read_b128 v[230:233], v154 offset:13824
	ds_read_b128 v[234:237], v154 offset:13856
	s_waitcnt lgkmcnt(7)
	v_mfma_f32_32x32x16_bf16 v[112:127], v[8:11], v[0:3], 0
	v_mfma_f32_32x32x16_bf16 v[96:111], v[8:11], v[4:7], 0
	s_waitcnt lgkmcnt(5)
	v_mfma_f32_32x32x16_bf16 v[80:95], v[12:15], v[0:3], 0
	v_mfma_f32_32x32x16_bf16 v[64:79], v[12:15], v[4:7], 0
	s_waitcnt lgkmcnt(3)
	v_mfma_f32_32x32x16_bf16 v[48:63], v[16:19], v[0:3], 0
	v_mfma_f32_32x32x16_bf16 v[32:47], v[16:19], v[4:7], 0
	s_waitcnt lgkmcnt(1)
	v_mfma_f32_32x32x16_bf16 v[16:31], v[230:233], v[0:3], 0
	v_mfma_f32_32x32x16_bf16 v[0:15], v[230:233], v[4:7], 0
	global_load_dwordx4 v[230:233], v[148:149], off offset:256
	global_load_dwordx4 v[238:241], v[150:151], off offset:256
	s_waitcnt vmcnt(9)
	ds_write_b128 v164, v[172:175]
	s_waitcnt vmcnt(8)
	ds_write_b128 v164, v[182:185] offset:9216
	ds_read_b128 v[172:175], v163 offset:36928
	ds_read_b128 v[182:185], v163 offset:41536
	ds_read_b128 v[242:245], v154 offset:64
	ds_read_b128 v[246:249], v154 offset:4672
	ds_read_b128 v[130:133], v154 offset:9280
	ds_read_b128 v[158:161], v154 offset:13888
	v_mfma_f32_32x32x16_bf16 v[80:95], v[222:225], v[210:213], v[80:95]
	v_mfma_f32_32x32x16_bf16 v[64:79], v[222:225], v[214:217], v[64:79]
	v_mfma_f32_32x32x16_bf16 v[48:63], v[226:229], v[210:213], v[48:63]
	v_mfma_f32_32x32x16_bf16 v[32:47], v[226:229], v[214:217], v[32:47]
	s_waitcnt lgkmcnt(8)
	v_mfma_f32_32x32x16_bf16 v[16:31], v[234:237], v[210:213], v[16:31]
	v_mfma_f32_32x32x16_bf16 v[0:15], v[234:237], v[214:217], v[0:15]
	v_mfma_f32_32x32x16_bf16 v[112:127], v[218:221], v[210:213], v[112:127]
	v_mfma_f32_32x32x16_bf16 v[96:111], v[218:221], v[214:217], v[96:111]
	global_load_dwordx4 v[210:213], v[144:145], off offset:256
	global_load_dwordx4 v[214:217], v[146:147], off offset:256
	s_waitcnt vmcnt(9)
	ds_write_b128 v164, v[186:189] offset:18432
	s_waitcnt vmcnt(8)
	ds_write_b128 v164, v[190:193] offset:27648
	ds_read_b128 v[186:189], v163 offset:36960
	ds_read_b128 v[190:193], v163 offset:41568
	ds_read_b128 v[218:221], v154 offset:96
	ds_read_b128 v[222:225], v154 offset:4704
	ds_read_b128 v[226:229], v154 offset:9312
	ds_read_b128 v[234:237], v154 offset:13920
	s_waitcnt lgkmcnt(10)
	v_mfma_f32_32x32x16_bf16 v[80:95], v[246:249], v[172:175], v[80:95]
	v_mfma_f32_32x32x16_bf16 v[64:79], v[246:249], v[182:185], v[64:79]
	s_waitcnt lgkmcnt(9)
	v_mfma_f32_32x32x16_bf16 v[48:63], v[130:133], v[172:175], v[48:63]
	v_mfma_f32_32x32x16_bf16 v[32:47], v[130:133], v[182:185], v[32:47]
	s_waitcnt lgkmcnt(8)
	v_mfma_f32_32x32x16_bf16 v[16:31], v[158:161], v[172:175], v[16:31]
	v_mfma_f32_32x32x16_bf16 v[0:15], v[158:161], v[182:185], v[0:15]
	v_mfma_f32_32x32x16_bf16 v[112:127], v[242:245], v[172:175], v[112:127]
	v_mfma_f32_32x32x16_bf16 v[96:111], v[242:245], v[182:185], v[96:111]
	global_load_dwordx4 v[130:133], v[140:141], off offset:256
	global_load_dwordx4 v[158:161], v[138:139], off offset:256
	s_waitcnt vmcnt(9)
	ds_write_b128 v165, v[194:197]
	s_waitcnt vmcnt(8)
	ds_write_b128 v166, v[198:201]
	s_waitcnt lgkmcnt(4)
	v_mfma_f32_32x32x16_bf16 v[80:95], v[222:225], v[186:189], v[80:95]
	v_mfma_f32_32x32x16_bf16 v[64:79], v[222:225], v[190:193], v[64:79]
	s_waitcnt lgkmcnt(3)
	v_mfma_f32_32x32x16_bf16 v[48:63], v[226:229], v[186:189], v[48:63]
	v_mfma_f32_32x32x16_bf16 v[32:47], v[226:229], v[190:193], v[32:47]
	s_waitcnt lgkmcnt(2)
	v_mfma_f32_32x32x16_bf16 v[16:31], v[234:237], v[186:189], v[16:31]
	v_mfma_f32_32x32x16_bf16 v[0:15], v[234:237], v[190:193], v[0:15]
	v_mfma_f32_32x32x16_bf16 v[112:127], v[218:221], v[186:189], v[112:127]
	v_mfma_f32_32x32x16_bf16 v[96:111], v[218:221], v[190:193], v[96:111]
	global_load_dwordx4 v[172:175], v[134:135], off offset:256
	global_load_dwordx4 v[182:185], v[136:137], off offset:256
	s_waitcnt vmcnt(9)
	ds_write_b128 v167, v[202:205]
	s_waitcnt vmcnt(8)
	ds_write_b128 v168, v[206:209]
	s_waitcnt lgkmcnt(0)
	s_barrier
	ds_read_b128 v[186:189], v169
	ds_read_b128 v[190:193], v169 offset:32
	ds_read_b128 v[194:197], v169 offset:4608
	ds_read_b128 v[198:201], v169 offset:4640
	ds_read_b128 v[202:205], v155
	ds_read_b128 v[206:209], v155 offset:32
	ds_read_b128 v[218:221], v155 offset:4608
	ds_read_b128 v[222:225], v155 offset:4640
	ds_read_b128 v[226:229], v155 offset:9216
	ds_read_b128 v[234:237], v155 offset:9248
	ds_read_b128 v[242:245], v155 offset:13824
	ds_read_b128 v[246:249], v155 offset:13856
	s_waitcnt lgkmcnt(5)
	v_mfma_f32_32x32x16_bf16 v[80:95], v[218:221], v[186:189], v[80:95]
	v_mfma_f32_32x32x16_bf16 v[64:79], v[218:221], v[194:197], v[64:79]
	s_waitcnt lgkmcnt(3)
	v_mfma_f32_32x32x16_bf16 v[48:63], v[226:229], v[186:189], v[48:63]
	v_mfma_f32_32x32x16_bf16 v[32:47], v[226:229], v[194:197], v[32:47]
	s_waitcnt lgkmcnt(1)
	v_mfma_f32_32x32x16_bf16 v[16:31], v[242:245], v[186:189], v[16:31]
	v_mfma_f32_32x32x16_bf16 v[0:15], v[242:245], v[194:197], v[0:15]
	v_mfma_f32_32x32x16_bf16 v[112:127], v[202:205], v[186:189], v[112:127]
	v_mfma_f32_32x32x16_bf16 v[96:111], v[202:205], v[194:197], v[96:111]
	global_load_dwordx4 v[186:189], v[148:149], off offset:384
	global_load_dwordx4 v[194:197], v[150:151], off offset:384
	s_waitcnt vmcnt(9)
	ds_write_b128 v128, v[230:233]
	s_waitcnt vmcnt(8)
	ds_write_b128 v128, v[238:241] offset:9216
	ds_read_b128 v[202:205], v169 offset:64
	ds_read_b128 v[218:221], v169 offset:4672
	ds_read_b128 v[226:229], v155 offset:64
	ds_read_b128 v[230:233], v155 offset:4672
	ds_read_b128 v[238:241], v155 offset:9280
	ds_read_b128 v[242:245], v155 offset:13888
	v_mfma_f32_32x32x16_bf16 v[80:95], v[222:225], v[190:193], v[80:95]
	v_mfma_f32_32x32x16_bf16 v[64:79], v[222:225], v[198:201], v[64:79]
	v_mfma_f32_32x32x16_bf16 v[48:63], v[234:237], v[190:193], v[48:63]
	v_mfma_f32_32x32x16_bf16 v[32:47], v[234:237], v[198:201], v[32:47]
	s_waitcnt lgkmcnt(8)
	v_mfma_f32_32x32x16_bf16 v[16:31], v[246:249], v[190:193], v[16:31]
	v_mfma_f32_32x32x16_bf16 v[0:15], v[246:249], v[198:201], v[0:15]
	v_mfma_f32_32x32x16_bf16 v[112:127], v[206:209], v[190:193], v[112:127]
	v_mfma_f32_32x32x16_bf16 v[96:111], v[206:209], v[198:201], v[96:111]
	global_load_dwordx4 v[190:193], v[144:145], off offset:384
	global_load_dwordx4 v[198:201], v[146:147], off offset:384
	s_waitcnt vmcnt(9)
	ds_write_b128 v128, v[210:213] offset:18432
	s_waitcnt vmcnt(8)
	ds_write_b128 v128, v[214:217] offset:27648
	ds_read_b128 v[206:209], v169 offset:96
	ds_read_b128 v[210:213], v169 offset:4704
	ds_read_b128 v[214:217], v155 offset:96
	ds_read_b128 v[222:225], v155 offset:4704
	ds_read_b128 v[234:237], v155 offset:9312
	ds_read_b128 v[246:249], v155 offset:13920
	s_waitcnt lgkmcnt(10)
	v_mfma_f32_32x32x16_bf16 v[80:95], v[230:233], v[202:205], v[80:95]
	v_mfma_f32_32x32x16_bf16 v[64:79], v[230:233], v[218:221], v[64:79]
	s_waitcnt lgkmcnt(9)
	v_mfma_f32_32x32x16_bf16 v[48:63], v[238:241], v[202:205], v[48:63]
	v_mfma_f32_32x32x16_bf16 v[32:47], v[238:241], v[218:221], v[32:47]
	s_waitcnt lgkmcnt(8)
	v_mfma_f32_32x32x16_bf16 v[16:31], v[242:245], v[202:205], v[16:31]
	v_mfma_f32_32x32x16_bf16 v[0:15], v[242:245], v[218:221], v[0:15]
	v_mfma_f32_32x32x16_bf16 v[112:127], v[226:229], v[202:205], v[112:127]
	v_mfma_f32_32x32x16_bf16 v[96:111], v[226:229], v[218:221], v[96:111]
	s_waitcnt vmcnt(7)
	ds_write_b128 v128, v[130:133] offset:36864
	global_load_dwordx4 v[130:133], v[140:141], off offset:384
	s_waitcnt vmcnt(7)
	ds_write_b128 v128, v[158:161] offset:46080
	global_load_dwordx4 v[158:161], v[138:139], off offset:384
	s_waitcnt lgkmcnt(4)
	v_mfma_f32_32x32x16_bf16 v[80:95], v[222:225], v[206:209], v[80:95]
	v_mfma_f32_32x32x16_bf16 v[64:79], v[222:225], v[210:213], v[64:79]
	s_waitcnt lgkmcnt(3)
	v_mfma_f32_32x32x16_bf16 v[48:63], v[234:237], v[206:209], v[48:63]
	v_mfma_f32_32x32x16_bf16 v[32:47], v[234:237], v[210:213], v[32:47]
	s_waitcnt lgkmcnt(2)
	v_mfma_f32_32x32x16_bf16 v[16:31], v[246:249], v[206:209], v[16:31]
	v_mfma_f32_32x32x16_bf16 v[0:15], v[246:249], v[210:213], v[0:15]
	v_mfma_f32_32x32x16_bf16 v[112:127], v[214:217], v[206:209], v[112:127]
	v_mfma_f32_32x32x16_bf16 v[96:111], v[214:217], v[210:213], v[96:111]
	global_load_dwordx4 v[202:205], v[134:135], off offset:384
	global_load_dwordx4 v[206:209], v[136:137], off offset:384
	s_waitcnt vmcnt(9)
	ds_write_b128 v128, v[172:175] offset:55296
	s_waitcnt vmcnt(8)
	ds_write_b128 v128, v[182:185] offset:64512
	s_waitcnt lgkmcnt(0)
	s_barrier
	ds_read_b128 v[172:175], v163 offset:36864
	ds_read_b128 v[182:185], v163 offset:36896
	ds_read_b128 v[210:213], v163 offset:41472
	ds_read_b128 v[214:217], v163 offset:41504
	ds_read_b128 v[218:221], v154
	ds_read_b128 v[222:225], v154 offset:32
	ds_read_b128 v[226:229], v154 offset:4608
	ds_read_b128 v[230:233], v154 offset:4640
	ds_read_b128 v[234:237], v154 offset:9216
	ds_read_b128 v[238:241], v154 offset:9248
	ds_read_b128 v[242:245], v154 offset:13824
	ds_read_b128 v[246:249], v154 offset:13856
	s_waitcnt lgkmcnt(5)
	v_mfma_f32_32x32x16_bf16 v[80:95], v[226:229], v[172:175], v[80:95]
	v_mfma_f32_32x32x16_bf16 v[64:79], v[226:229], v[210:213], v[64:79]
	s_waitcnt lgkmcnt(3)
	v_mfma_f32_32x32x16_bf16 v[48:63], v[234:237], v[172:175], v[48:63]
	v_mfma_f32_32x32x16_bf16 v[32:47], v[234:237], v[210:213], v[32:47]
	s_waitcnt lgkmcnt(1)
	v_mfma_f32_32x32x16_bf16 v[16:31], v[242:245], v[172:175], v[16:31]
	v_mfma_f32_32x32x16_bf16 v[0:15], v[242:245], v[210:213], v[0:15]
	v_mfma_f32_32x32x16_bf16 v[112:127], v[218:221], v[172:175], v[112:127]
	v_mfma_f32_32x32x16_bf16 v[96:111], v[218:221], v[210:213], v[96:111]
	global_load_dwordx4 v[172:175], v[148:149], off offset:512
	global_load_dwordx4 v[210:213], v[150:151], off offset:512
	s_waitcnt vmcnt(9)
	ds_write_b128 v164, v[186:189]
	s_waitcnt vmcnt(8)
	ds_write_b128 v164, v[194:197] offset:9216
	ds_read_b128 v[186:189], v163 offset:36928
	ds_read_b128 v[194:197], v163 offset:41536
	ds_read_b128 v[218:221], v154 offset:64
	ds_read_b128 v[226:229], v154 offset:4672
	ds_read_b128 v[234:237], v154 offset:9280
	ds_read_b128 v[242:245], v154 offset:13888
	v_mfma_f32_32x32x16_bf16 v[80:95], v[230:233], v[182:185], v[80:95]
	v_mfma_f32_32x32x16_bf16 v[64:79], v[230:233], v[214:217], v[64:79]
	v_mfma_f32_32x32x16_bf16 v[48:63], v[238:241], v[182:185], v[48:63]
	v_mfma_f32_32x32x16_bf16 v[32:47], v[238:241], v[214:217], v[32:47]
	s_waitcnt lgkmcnt(8)
	v_mfma_f32_32x32x16_bf16 v[16:31], v[246:249], v[182:185], v[16:31]
	v_mfma_f32_32x32x16_bf16 v[0:15], v[246:249], v[214:217], v[0:15]
	v_mfma_f32_32x32x16_bf16 v[112:127], v[222:225], v[182:185], v[112:127]
	v_mfma_f32_32x32x16_bf16 v[96:111], v[222:225], v[214:217], v[96:111]
	global_load_dwordx4 v[182:185], v[144:145], off offset:512
	global_load_dwordx4 v[214:217], v[146:147], off offset:512
	s_waitcnt vmcnt(9)
	ds_write_b128 v164, v[190:193] offset:18432
	s_waitcnt vmcnt(8)
	ds_write_b128 v164, v[198:201] offset:27648
	ds_read_b128 v[190:193], v163 offset:36960
	ds_read_b128 v[198:201], v163 offset:41568
	ds_read_b128 v[222:225], v154 offset:96
	ds_read_b128 v[230:233], v154 offset:4704
	ds_read_b128 v[238:241], v154 offset:9312
	ds_read_b128 v[246:249], v154 offset:13920
	s_waitcnt lgkmcnt(10)
	v_mfma_f32_32x32x16_bf16 v[80:95], v[226:229], v[186:189], v[80:95]
	v_mfma_f32_32x32x16_bf16 v[64:79], v[226:229], v[194:197], v[64:79]
	s_waitcnt lgkmcnt(9)
	v_mfma_f32_32x32x16_bf16 v[48:63], v[234:237], v[186:189], v[48:63]
	v_mfma_f32_32x32x16_bf16 v[32:47], v[234:237], v[194:197], v[32:47]
	s_waitcnt lgkmcnt(8)
	v_mfma_f32_32x32x16_bf16 v[16:31], v[242:245], v[186:189], v[16:31]
	v_mfma_f32_32x32x16_bf16 v[0:15], v[242:245], v[194:197], v[0:15]
	v_mfma_f32_32x32x16_bf16 v[112:127], v[218:221], v[186:189], v[112:127]
	v_mfma_f32_32x32x16_bf16 v[96:111], v[218:221], v[194:197], v[96:111]
	s_waitcnt vmcnt(7)
	ds_write_b128 v165, v[130:133]
	global_load_dwordx4 v[130:133], v[140:141], off offset:512
	s_waitcnt vmcnt(7)
	ds_write_b128 v166, v[158:161]
	global_load_dwordx4 v[158:161], v[138:139], off offset:512
	s_waitcnt lgkmcnt(4)
	v_mfma_f32_32x32x16_bf16 v[80:95], v[230:233], v[190:193], v[80:95]
	v_mfma_f32_32x32x16_bf16 v[64:79], v[230:233], v[198:201], v[64:79]
	s_waitcnt lgkmcnt(3)
	v_mfma_f32_32x32x16_bf16 v[48:63], v[238:241], v[190:193], v[48:63]
	v_mfma_f32_32x32x16_bf16 v[32:47], v[238:241], v[198:201], v[32:47]
	s_waitcnt lgkmcnt(2)
	v_mfma_f32_32x32x16_bf16 v[16:31], v[246:249], v[190:193], v[16:31]
	v_mfma_f32_32x32x16_bf16 v[0:15], v[246:249], v[198:201], v[0:15]
	v_mfma_f32_32x32x16_bf16 v[112:127], v[222:225], v[190:193], v[112:127]
	v_mfma_f32_32x32x16_bf16 v[96:111], v[222:225], v[198:201], v[96:111]
	global_load_dwordx4 v[186:189], v[134:135], off offset:512
	global_load_dwordx4 v[190:193], v[136:137], off offset:512
	s_waitcnt vmcnt(9)
	ds_write_b128 v167, v[202:205]
	s_waitcnt vmcnt(8)
	ds_write_b128 v168, v[206:209]
	s_waitcnt lgkmcnt(0)
	s_barrier
	ds_read_b128 v[194:197], v169
	ds_read_b128 v[198:201], v169 offset:32
	ds_read_b128 v[202:205], v169 offset:4608
	ds_read_b128 v[206:209], v169 offset:4640
	ds_read_b128 v[218:221], v155
	ds_read_b128 v[222:225], v155 offset:32
	ds_read_b128 v[226:229], v155 offset:4608
	ds_read_b128 v[230:233], v155 offset:4640
	ds_read_b128 v[234:237], v155 offset:9216
	ds_read_b128 v[238:241], v155 offset:9248
	ds_read_b128 v[242:245], v155 offset:13824
	ds_read_b128 v[246:249], v155 offset:13856
	s_waitcnt lgkmcnt(5)
	v_mfma_f32_32x32x16_bf16 v[80:95], v[226:229], v[194:197], v[80:95]
	v_mfma_f32_32x32x16_bf16 v[64:79], v[226:229], v[202:205], v[64:79]
	s_waitcnt lgkmcnt(3)
	v_mfma_f32_32x32x16_bf16 v[48:63], v[234:237], v[194:197], v[48:63]
	v_mfma_f32_32x32x16_bf16 v[32:47], v[234:237], v[202:205], v[32:47]
	s_waitcnt lgkmcnt(1)
	v_mfma_f32_32x32x16_bf16 v[16:31], v[242:245], v[194:197], v[16:31]
	v_mfma_f32_32x32x16_bf16 v[0:15], v[242:245], v[202:205], v[0:15]
	v_mfma_f32_32x32x16_bf16 v[112:127], v[218:221], v[194:197], v[112:127]
	v_mfma_f32_32x32x16_bf16 v[96:111], v[218:221], v[202:205], v[96:111]
	global_load_dwordx4 v[194:197], v[148:149], off offset:640
	global_load_dwordx4 v[202:205], v[150:151], off offset:640
	s_waitcnt vmcnt(9)
	ds_write_b128 v128, v[172:175]
	s_waitcnt vmcnt(8)
	ds_write_b128 v128, v[210:213] offset:9216
	ds_read_b128 v[172:175], v169 offset:64
	ds_read_b128 v[210:213], v169 offset:4672
	ds_read_b128 v[218:221], v155 offset:64
	ds_read_b128 v[226:229], v155 offset:4672
	ds_read_b128 v[234:237], v155 offset:9280
	ds_read_b128 v[242:245], v155 offset:13888
	v_mfma_f32_32x32x16_bf16 v[80:95], v[230:233], v[198:201], v[80:95]
	v_mfma_f32_32x32x16_bf16 v[64:79], v[230:233], v[206:209], v[64:79]
	v_mfma_f32_32x32x16_bf16 v[48:63], v[238:241], v[198:201], v[48:63]
	v_mfma_f32_32x32x16_bf16 v[32:47], v[238:241], v[206:209], v[32:47]
	s_waitcnt lgkmcnt(8)
	v_mfma_f32_32x32x16_bf16 v[16:31], v[246:249], v[198:201], v[16:31]
	v_mfma_f32_32x32x16_bf16 v[0:15], v[246:249], v[206:209], v[0:15]
	v_mfma_f32_32x32x16_bf16 v[112:127], v[222:225], v[198:201], v[112:127]
	v_mfma_f32_32x32x16_bf16 v[96:111], v[222:225], v[206:209], v[96:111]
	global_load_dwordx4 v[198:201], v[144:145], off offset:640
	global_load_dwordx4 v[206:209], v[146:147], off offset:640
	s_waitcnt vmcnt(9)
	ds_write_b128 v128, v[182:185] offset:18432
	s_waitcnt vmcnt(8)
	ds_write_b128 v128, v[214:217] offset:27648
	ds_read_b128 v[182:185], v169 offset:96
	ds_read_b128 v[214:217], v169 offset:4704
	ds_read_b128 v[222:225], v155 offset:96
	ds_read_b128 v[230:233], v155 offset:4704
	ds_read_b128 v[238:241], v155 offset:9312
	ds_read_b128 v[246:249], v155 offset:13920
	s_waitcnt lgkmcnt(10)
	v_mfma_f32_32x32x16_bf16 v[80:95], v[226:229], v[172:175], v[80:95]
	v_mfma_f32_32x32x16_bf16 v[64:79], v[226:229], v[210:213], v[64:79]
	s_waitcnt lgkmcnt(9)
	v_mfma_f32_32x32x16_bf16 v[48:63], v[234:237], v[172:175], v[48:63]
	v_mfma_f32_32x32x16_bf16 v[32:47], v[234:237], v[210:213], v[32:47]
	s_waitcnt lgkmcnt(8)
	v_mfma_f32_32x32x16_bf16 v[16:31], v[242:245], v[172:175], v[16:31]
	v_mfma_f32_32x32x16_bf16 v[0:15], v[242:245], v[210:213], v[0:15]
	v_mfma_f32_32x32x16_bf16 v[112:127], v[218:221], v[172:175], v[112:127]
	v_mfma_f32_32x32x16_bf16 v[96:111], v[218:221], v[210:213], v[96:111]
	s_waitcnt vmcnt(7)
	ds_write_b128 v128, v[130:133] offset:36864
	global_load_dwordx4 v[130:133], v[140:141], off offset:640
	s_waitcnt vmcnt(7)
	ds_write_b128 v128, v[158:161] offset:46080
	global_load_dwordx4 v[158:161], v[138:139], off offset:640
	s_waitcnt lgkmcnt(4)
	v_mfma_f32_32x32x16_bf16 v[80:95], v[230:233], v[182:185], v[80:95]
	v_mfma_f32_32x32x16_bf16 v[64:79], v[230:233], v[214:217], v[64:79]
	s_waitcnt lgkmcnt(3)
	v_mfma_f32_32x32x16_bf16 v[48:63], v[238:241], v[182:185], v[48:63]
	v_mfma_f32_32x32x16_bf16 v[32:47], v[238:241], v[214:217], v[32:47]
	s_waitcnt lgkmcnt(2)
	v_mfma_f32_32x32x16_bf16 v[16:31], v[246:249], v[182:185], v[16:31]
	v_mfma_f32_32x32x16_bf16 v[0:15], v[246:249], v[214:217], v[0:15]
	v_mfma_f32_32x32x16_bf16 v[112:127], v[222:225], v[182:185], v[112:127]
	v_mfma_f32_32x32x16_bf16 v[96:111], v[222:225], v[214:217], v[96:111]
	global_load_dwordx4 v[172:175], v[134:135], off offset:640
	global_load_dwordx4 v[182:185], v[136:137], off offset:640
	s_waitcnt vmcnt(9)
	ds_write_b128 v128, v[186:189] offset:55296
	s_waitcnt vmcnt(8)
	ds_write_b128 v128, v[190:193] offset:64512
	s_waitcnt lgkmcnt(0)
	s_barrier
	ds_read_b128 v[186:189], v163 offset:36864
	ds_read_b128 v[190:193], v163 offset:36896
	ds_read_b128 v[210:213], v163 offset:41472
	ds_read_b128 v[214:217], v163 offset:41504
	ds_read_b128 v[218:221], v154
	ds_read_b128 v[222:225], v154 offset:32
	ds_read_b128 v[226:229], v154 offset:4608
	ds_read_b128 v[230:233], v154 offset:4640
	ds_read_b128 v[234:237], v154 offset:9216
	ds_read_b128 v[238:241], v154 offset:9248
	ds_read_b128 v[242:245], v154 offset:13824
	ds_read_b128 v[246:249], v154 offset:13856
	s_waitcnt lgkmcnt(5)
	v_mfma_f32_32x32x16_bf16 v[80:95], v[226:229], v[186:189], v[80:95]
	v_mfma_f32_32x32x16_bf16 v[64:79], v[226:229], v[210:213], v[64:79]
	s_waitcnt lgkmcnt(3)
	v_mfma_f32_32x32x16_bf16 v[48:63], v[234:237], v[186:189], v[48:63]
	v_mfma_f32_32x32x16_bf16 v[32:47], v[234:237], v[210:213], v[32:47]
	s_waitcnt lgkmcnt(1)
	v_mfma_f32_32x32x16_bf16 v[16:31], v[242:245], v[186:189], v[16:31]
	v_mfma_f32_32x32x16_bf16 v[0:15], v[242:245], v[210:213], v[0:15]
	v_mfma_f32_32x32x16_bf16 v[112:127], v[218:221], v[186:189], v[112:127]
	v_mfma_f32_32x32x16_bf16 v[96:111], v[218:221], v[210:213], v[96:111]
	global_load_dwordx4 v[186:189], v[148:149], off offset:768
	global_load_dwordx4 v[210:213], v[150:151], off offset:768
	s_waitcnt vmcnt(9)
	ds_write_b128 v164, v[194:197]
	s_waitcnt vmcnt(8)
	ds_write_b128 v164, v[202:205] offset:9216
	ds_read_b128 v[194:197], v163 offset:36928
	ds_read_b128 v[202:205], v163 offset:41536
	ds_read_b128 v[218:221], v154 offset:64
	ds_read_b128 v[226:229], v154 offset:4672
	ds_read_b128 v[234:237], v154 offset:9280
	ds_read_b128 v[242:245], v154 offset:13888
	v_mfma_f32_32x32x16_bf16 v[80:95], v[230:233], v[190:193], v[80:95]
	v_mfma_f32_32x32x16_bf16 v[64:79], v[230:233], v[214:217], v[64:79]
	v_mfma_f32_32x32x16_bf16 v[48:63], v[238:241], v[190:193], v[48:63]
	v_mfma_f32_32x32x16_bf16 v[32:47], v[238:241], v[214:217], v[32:47]
	s_waitcnt lgkmcnt(8)
	v_mfma_f32_32x32x16_bf16 v[16:31], v[246:249], v[190:193], v[16:31]
	v_mfma_f32_32x32x16_bf16 v[0:15], v[246:249], v[214:217], v[0:15]
	v_mfma_f32_32x32x16_bf16 v[112:127], v[222:225], v[190:193], v[112:127]
	v_mfma_f32_32x32x16_bf16 v[96:111], v[222:225], v[214:217], v[96:111]
	global_load_dwordx4 v[190:193], v[144:145], off offset:768
	global_load_dwordx4 v[214:217], v[146:147], off offset:768
	s_waitcnt vmcnt(9)
	ds_write_b128 v164, v[198:201] offset:18432
	s_waitcnt vmcnt(8)
	ds_write_b128 v164, v[206:209] offset:27648
	ds_read_b128 v[198:201], v163 offset:36960
	ds_read_b128 v[206:209], v163 offset:41568
	ds_read_b128 v[222:225], v154 offset:96
	ds_read_b128 v[230:233], v154 offset:4704
	ds_read_b128 v[238:241], v154 offset:9312
	ds_read_b128 v[246:249], v154 offset:13920
	s_waitcnt lgkmcnt(10)
	v_mfma_f32_32x32x16_bf16 v[80:95], v[226:229], v[194:197], v[80:95]
	v_mfma_f32_32x32x16_bf16 v[64:79], v[226:229], v[202:205], v[64:79]
	s_waitcnt lgkmcnt(9)
	v_mfma_f32_32x32x16_bf16 v[48:63], v[234:237], v[194:197], v[48:63]
	v_mfma_f32_32x32x16_bf16 v[32:47], v[234:237], v[202:205], v[32:47]
	s_waitcnt lgkmcnt(8)
	v_mfma_f32_32x32x16_bf16 v[16:31], v[242:245], v[194:197], v[16:31]
	v_mfma_f32_32x32x16_bf16 v[0:15], v[242:245], v[202:205], v[0:15]
	v_mfma_f32_32x32x16_bf16 v[112:127], v[218:221], v[194:197], v[112:127]
	v_mfma_f32_32x32x16_bf16 v[96:111], v[218:221], v[202:205], v[96:111]
	s_waitcnt vmcnt(7)
	ds_write_b128 v165, v[130:133]
	global_load_dwordx4 v[130:133], v[140:141], off offset:768
	s_waitcnt vmcnt(7)
	ds_write_b128 v166, v[158:161]
	global_load_dwordx4 v[158:161], v[138:139], off offset:768
	s_waitcnt lgkmcnt(4)
	v_mfma_f32_32x32x16_bf16 v[80:95], v[230:233], v[198:201], v[80:95]
	v_mfma_f32_32x32x16_bf16 v[64:79], v[230:233], v[206:209], v[64:79]
	s_waitcnt lgkmcnt(3)
	v_mfma_f32_32x32x16_bf16 v[48:63], v[238:241], v[198:201], v[48:63]
	v_mfma_f32_32x32x16_bf16 v[32:47], v[238:241], v[206:209], v[32:47]
	s_waitcnt lgkmcnt(2)
	v_mfma_f32_32x32x16_bf16 v[16:31], v[246:249], v[198:201], v[16:31]
	v_mfma_f32_32x32x16_bf16 v[0:15], v[246:249], v[206:209], v[0:15]
	v_mfma_f32_32x32x16_bf16 v[112:127], v[222:225], v[198:201], v[112:127]
	v_mfma_f32_32x32x16_bf16 v[96:111], v[222:225], v[206:209], v[96:111]
	global_load_dwordx4 v[194:197], v[134:135], off offset:768
	global_load_dwordx4 v[198:201], v[136:137], off offset:768
	s_waitcnt vmcnt(9)
	ds_write_b128 v167, v[172:175]
	s_waitcnt vmcnt(8)
	ds_write_b128 v168, v[182:185]
	s_waitcnt lgkmcnt(0)
	s_barrier
	ds_read_b128 v[172:175], v169
	ds_read_b128 v[182:185], v169 offset:32
	ds_read_b128 v[202:205], v169 offset:4608
	ds_read_b128 v[206:209], v169 offset:4640
	ds_read_b128 v[218:221], v155
	ds_read_b128 v[222:225], v155 offset:32
	ds_read_b128 v[226:229], v155 offset:4608
	ds_read_b128 v[230:233], v155 offset:4640
	ds_read_b128 v[234:237], v155 offset:9216
	ds_read_b128 v[238:241], v155 offset:9248
	ds_read_b128 v[242:245], v155 offset:13824
	ds_read_b128 v[246:249], v155 offset:13856
	s_waitcnt lgkmcnt(5)
	v_mfma_f32_32x32x16_bf16 v[80:95], v[226:229], v[172:175], v[80:95]
	v_mfma_f32_32x32x16_bf16 v[64:79], v[226:229], v[202:205], v[64:79]
	s_waitcnt lgkmcnt(3)
	v_mfma_f32_32x32x16_bf16 v[48:63], v[234:237], v[172:175], v[48:63]
	v_mfma_f32_32x32x16_bf16 v[32:47], v[234:237], v[202:205], v[32:47]
	s_waitcnt lgkmcnt(1)
	v_mfma_f32_32x32x16_bf16 v[16:31], v[242:245], v[172:175], v[16:31]
	v_mfma_f32_32x32x16_bf16 v[0:15], v[242:245], v[202:205], v[0:15]
	v_mfma_f32_32x32x16_bf16 v[112:127], v[218:221], v[172:175], v[112:127]
	v_mfma_f32_32x32x16_bf16 v[96:111], v[218:221], v[202:205], v[96:111]
	global_load_dwordx4 v[172:175], v[148:149], off offset:896
	global_load_dwordx4 v[202:205], v[150:151], off offset:896
	s_waitcnt vmcnt(9)
	ds_write_b128 v128, v[186:189]
	s_waitcnt vmcnt(8)
	ds_write_b128 v128, v[210:213] offset:9216
	ds_read_b128 v[186:189], v169 offset:64
	ds_read_b128 v[210:213], v169 offset:4672
	ds_read_b128 v[218:221], v155 offset:64
	ds_read_b128 v[226:229], v155 offset:4672
	ds_read_b128 v[234:237], v155 offset:9280
	ds_read_b128 v[242:245], v155 offset:13888
	v_mfma_f32_32x32x16_bf16 v[80:95], v[230:233], v[182:185], v[80:95]
	v_mfma_f32_32x32x16_bf16 v[64:79], v[230:233], v[206:209], v[64:79]
	v_mfma_f32_32x32x16_bf16 v[48:63], v[238:241], v[182:185], v[48:63]
	v_mfma_f32_32x32x16_bf16 v[32:47], v[238:241], v[206:209], v[32:47]
	s_waitcnt lgkmcnt(8)
	v_mfma_f32_32x32x16_bf16 v[16:31], v[246:249], v[182:185], v[16:31]
	v_mfma_f32_32x32x16_bf16 v[0:15], v[246:249], v[206:209], v[0:15]
	v_mfma_f32_32x32x16_bf16 v[112:127], v[222:225], v[182:185], v[112:127]
	v_mfma_f32_32x32x16_bf16 v[96:111], v[222:225], v[206:209], v[96:111]
	global_load_dwordx4 v[182:185], v[144:145], off offset:896
	global_load_dwordx4 v[206:209], v[146:147], off offset:896
	s_waitcnt vmcnt(9)
	ds_write_b128 v128, v[190:193] offset:18432
	s_waitcnt vmcnt(8)
	ds_write_b128 v128, v[214:217] offset:27648
	ds_read_b128 v[190:193], v169 offset:96
	ds_read_b128 v[214:217], v169 offset:4704
	ds_read_b128 v[222:225], v155 offset:96
	ds_read_b128 v[230:233], v155 offset:4704
	ds_read_b128 v[238:241], v155 offset:9312
	ds_read_b128 v[246:249], v155 offset:13920
	s_waitcnt lgkmcnt(10)
	v_mfma_f32_32x32x16_bf16 v[80:95], v[226:229], v[186:189], v[80:95]
	v_mfma_f32_32x32x16_bf16 v[64:79], v[226:229], v[210:213], v[64:79]
	s_waitcnt lgkmcnt(9)
	v_mfma_f32_32x32x16_bf16 v[48:63], v[234:237], v[186:189], v[48:63]
	v_mfma_f32_32x32x16_bf16 v[32:47], v[234:237], v[210:213], v[32:47]
	s_waitcnt lgkmcnt(8)
	v_mfma_f32_32x32x16_bf16 v[16:31], v[242:245], v[186:189], v[16:31]
	v_mfma_f32_32x32x16_bf16 v[0:15], v[242:245], v[210:213], v[0:15]
	v_mfma_f32_32x32x16_bf16 v[112:127], v[218:221], v[186:189], v[112:127]
	v_mfma_f32_32x32x16_bf16 v[96:111], v[218:221], v[210:213], v[96:111]
	s_waitcnt vmcnt(7)
	ds_write_b128 v128, v[130:133] offset:36864
	global_load_dwordx4 v[130:133], v[140:141], off offset:896
	s_waitcnt vmcnt(7)
	ds_write_b128 v128, v[158:161] offset:46080
	global_load_dwordx4 v[158:161], v[138:139], off offset:896
	s_waitcnt lgkmcnt(4)
	v_mfma_f32_32x32x16_bf16 v[80:95], v[230:233], v[190:193], v[80:95]
	v_mfma_f32_32x32x16_bf16 v[64:79], v[230:233], v[214:217], v[64:79]
	s_waitcnt lgkmcnt(3)
	v_mfma_f32_32x32x16_bf16 v[48:63], v[238:241], v[190:193], v[48:63]
	v_mfma_f32_32x32x16_bf16 v[32:47], v[238:241], v[214:217], v[32:47]
	s_waitcnt lgkmcnt(2)
	v_mfma_f32_32x32x16_bf16 v[16:31], v[246:249], v[190:193], v[16:31]
	v_mfma_f32_32x32x16_bf16 v[0:15], v[246:249], v[214:217], v[0:15]
	v_mfma_f32_32x32x16_bf16 v[112:127], v[222:225], v[190:193], v[112:127]
	v_mfma_f32_32x32x16_bf16 v[96:111], v[222:225], v[214:217], v[96:111]
	global_load_dwordx4 v[186:189], v[134:135], off offset:896
	global_load_dwordx4 v[190:193], v[136:137], off offset:896
	s_waitcnt vmcnt(9)
	ds_write_b128 v128, v[194:197] offset:55296
	s_waitcnt vmcnt(8)
	ds_write_b128 v128, v[198:201] offset:64512
	s_waitcnt lgkmcnt(0)
	s_barrier
	ds_read_b128 v[194:197], v163 offset:36864
	ds_read_b128 v[198:201], v163 offset:36896
	ds_read_b128 v[210:213], v163 offset:41472
	ds_read_b128 v[214:217], v163 offset:41504
	ds_read_b128 v[218:221], v154
	ds_read_b128 v[222:225], v154 offset:32
	ds_read_b128 v[226:229], v154 offset:4608
	ds_read_b128 v[230:233], v154 offset:4640
	ds_read_b128 v[234:237], v154 offset:9216
	ds_read_b128 v[238:241], v154 offset:9248
	ds_read_b128 v[242:245], v154 offset:13824
	ds_read_b128 v[246:249], v154 offset:13856
	s_waitcnt lgkmcnt(5)
	v_mfma_f32_32x32x16_bf16 v[80:95], v[226:229], v[194:197], v[80:95]
	v_mfma_f32_32x32x16_bf16 v[64:79], v[226:229], v[210:213], v[64:79]
	s_waitcnt lgkmcnt(3)
	v_mfma_f32_32x32x16_bf16 v[48:63], v[234:237], v[194:197], v[48:63]
	v_mfma_f32_32x32x16_bf16 v[32:47], v[234:237], v[210:213], v[32:47]
	s_waitcnt lgkmcnt(1)
	v_mfma_f32_32x32x16_bf16 v[16:31], v[242:245], v[194:197], v[16:31]
	v_mfma_f32_32x32x16_bf16 v[0:15], v[242:245], v[210:213], v[0:15]
	v_mfma_f32_32x32x16_bf16 v[112:127], v[218:221], v[194:197], v[112:127]
	v_mfma_f32_32x32x16_bf16 v[96:111], v[218:221], v[210:213], v[96:111]
	global_load_dwordx4 v[194:197], v[148:149], off offset:1024
	global_load_dwordx4 v[210:213], v[150:151], off offset:1024
	s_waitcnt vmcnt(9)
	ds_write_b128 v164, v[172:175]
	s_waitcnt vmcnt(8)
	ds_write_b128 v164, v[202:205] offset:9216
	ds_read_b128 v[172:175], v163 offset:36928
	ds_read_b128 v[202:205], v163 offset:41536
	ds_read_b128 v[218:221], v154 offset:64
	ds_read_b128 v[226:229], v154 offset:4672
	ds_read_b128 v[234:237], v154 offset:9280
	ds_read_b128 v[242:245], v154 offset:13888
	v_mfma_f32_32x32x16_bf16 v[80:95], v[230:233], v[198:201], v[80:95]
	v_mfma_f32_32x32x16_bf16 v[64:79], v[230:233], v[214:217], v[64:79]
	v_mfma_f32_32x32x16_bf16 v[48:63], v[238:241], v[198:201], v[48:63]
	v_mfma_f32_32x32x16_bf16 v[32:47], v[238:241], v[214:217], v[32:47]
	s_waitcnt lgkmcnt(8)
	v_mfma_f32_32x32x16_bf16 v[16:31], v[246:249], v[198:201], v[16:31]
	v_mfma_f32_32x32x16_bf16 v[0:15], v[246:249], v[214:217], v[0:15]
	v_mfma_f32_32x32x16_bf16 v[112:127], v[222:225], v[198:201], v[112:127]
	v_mfma_f32_32x32x16_bf16 v[96:111], v[222:225], v[214:217], v[96:111]
	global_load_dwordx4 v[198:201], v[144:145], off offset:1024
	global_load_dwordx4 v[214:217], v[146:147], off offset:1024
	s_waitcnt vmcnt(9)
	ds_write_b128 v164, v[182:185] offset:18432
	s_waitcnt vmcnt(8)
	ds_write_b128 v164, v[206:209] offset:27648
	ds_read_b128 v[182:185], v163 offset:36960
	ds_read_b128 v[206:209], v163 offset:41568
	ds_read_b128 v[222:225], v154 offset:96
	ds_read_b128 v[230:233], v154 offset:4704
	ds_read_b128 v[238:241], v154 offset:9312
	ds_read_b128 v[246:249], v154 offset:13920
	s_waitcnt lgkmcnt(10)
	v_mfma_f32_32x32x16_bf16 v[80:95], v[226:229], v[172:175], v[80:95]
	v_mfma_f32_32x32x16_bf16 v[64:79], v[226:229], v[202:205], v[64:79]
	s_waitcnt lgkmcnt(9)
	v_mfma_f32_32x32x16_bf16 v[48:63], v[234:237], v[172:175], v[48:63]
	v_mfma_f32_32x32x16_bf16 v[32:47], v[234:237], v[202:205], v[32:47]
	s_waitcnt lgkmcnt(8)
	v_mfma_f32_32x32x16_bf16 v[16:31], v[242:245], v[172:175], v[16:31]
	v_mfma_f32_32x32x16_bf16 v[0:15], v[242:245], v[202:205], v[0:15]
	v_mfma_f32_32x32x16_bf16 v[112:127], v[218:221], v[172:175], v[112:127]
	v_mfma_f32_32x32x16_bf16 v[96:111], v[218:221], v[202:205], v[96:111]
	s_waitcnt vmcnt(7)
	ds_write_b128 v165, v[130:133]
	global_load_dwordx4 v[130:133], v[140:141], off offset:1024
	s_waitcnt vmcnt(7)
	ds_write_b128 v166, v[158:161]
	global_load_dwordx4 v[158:161], v[138:139], off offset:1024
	s_waitcnt lgkmcnt(4)
	v_mfma_f32_32x32x16_bf16 v[80:95], v[230:233], v[182:185], v[80:95]
	v_mfma_f32_32x32x16_bf16 v[64:79], v[230:233], v[206:209], v[64:79]
	s_waitcnt lgkmcnt(3)
	v_mfma_f32_32x32x16_bf16 v[48:63], v[238:241], v[182:185], v[48:63]
	v_mfma_f32_32x32x16_bf16 v[32:47], v[238:241], v[206:209], v[32:47]
	s_waitcnt lgkmcnt(2)
	v_mfma_f32_32x32x16_bf16 v[16:31], v[246:249], v[182:185], v[16:31]
	v_mfma_f32_32x32x16_bf16 v[0:15], v[246:249], v[206:209], v[0:15]
	v_mfma_f32_32x32x16_bf16 v[112:127], v[222:225], v[182:185], v[112:127]
	v_mfma_f32_32x32x16_bf16 v[96:111], v[222:225], v[206:209], v[96:111]
	global_load_dwordx4 v[172:175], v[134:135], off offset:1024
	global_load_dwordx4 v[182:185], v[136:137], off offset:1024
	s_waitcnt vmcnt(9)
	ds_write_b128 v167, v[186:189]
	s_waitcnt vmcnt(8)
	ds_write_b128 v168, v[190:193]
	s_waitcnt lgkmcnt(0)
	s_barrier
	ds_read_b128 v[186:189], v169
	ds_read_b128 v[190:193], v169 offset:32
	ds_read_b128 v[202:205], v169 offset:4608
	ds_read_b128 v[206:209], v169 offset:4640
	ds_read_b128 v[218:221], v155
	ds_read_b128 v[222:225], v155 offset:32
	ds_read_b128 v[226:229], v155 offset:4608
	ds_read_b128 v[230:233], v155 offset:4640
	ds_read_b128 v[234:237], v155 offset:9216
	ds_read_b128 v[238:241], v155 offset:9248
	ds_read_b128 v[242:245], v155 offset:13824
	ds_read_b128 v[246:249], v155 offset:13856
	s_waitcnt lgkmcnt(5)
	v_mfma_f32_32x32x16_bf16 v[80:95], v[226:229], v[186:189], v[80:95]
	v_mfma_f32_32x32x16_bf16 v[64:79], v[226:229], v[202:205], v[64:79]
	s_waitcnt lgkmcnt(3)
	v_mfma_f32_32x32x16_bf16 v[48:63], v[234:237], v[186:189], v[48:63]
	v_mfma_f32_32x32x16_bf16 v[32:47], v[234:237], v[202:205], v[32:47]
	s_waitcnt lgkmcnt(1)
	v_mfma_f32_32x32x16_bf16 v[16:31], v[242:245], v[186:189], v[16:31]
	v_mfma_f32_32x32x16_bf16 v[0:15], v[242:245], v[202:205], v[0:15]
	v_mfma_f32_32x32x16_bf16 v[112:127], v[218:221], v[186:189], v[112:127]
	v_mfma_f32_32x32x16_bf16 v[96:111], v[218:221], v[202:205], v[96:111]
	global_load_dwordx4 v[186:189], v[148:149], off offset:1152
	global_load_dwordx4 v[202:205], v[150:151], off offset:1152
	s_waitcnt vmcnt(9)
	ds_write_b128 v128, v[194:197]
	s_waitcnt vmcnt(8)
	ds_write_b128 v128, v[210:213] offset:9216
	ds_read_b128 v[194:197], v169 offset:64
	ds_read_b128 v[210:213], v169 offset:4672
	ds_read_b128 v[218:221], v155 offset:64
	ds_read_b128 v[226:229], v155 offset:4672
	ds_read_b128 v[234:237], v155 offset:9280
	ds_read_b128 v[242:245], v155 offset:13888
	v_mfma_f32_32x32x16_bf16 v[80:95], v[230:233], v[190:193], v[80:95]
	v_mfma_f32_32x32x16_bf16 v[64:79], v[230:233], v[206:209], v[64:79]
	v_mfma_f32_32x32x16_bf16 v[48:63], v[238:241], v[190:193], v[48:63]
	v_mfma_f32_32x32x16_bf16 v[32:47], v[238:241], v[206:209], v[32:47]
	s_waitcnt lgkmcnt(8)
	v_mfma_f32_32x32x16_bf16 v[16:31], v[246:249], v[190:193], v[16:31]
	v_mfma_f32_32x32x16_bf16 v[0:15], v[246:249], v[206:209], v[0:15]
	v_mfma_f32_32x32x16_bf16 v[112:127], v[222:225], v[190:193], v[112:127]
	v_mfma_f32_32x32x16_bf16 v[96:111], v[222:225], v[206:209], v[96:111]
	global_load_dwordx4 v[190:193], v[144:145], off offset:1152
	global_load_dwordx4 v[206:209], v[146:147], off offset:1152
	s_waitcnt vmcnt(9)
	ds_write_b128 v128, v[198:201] offset:18432
	s_waitcnt vmcnt(8)
	ds_write_b128 v128, v[214:217] offset:27648
	ds_read_b128 v[198:201], v169 offset:96
	ds_read_b128 v[214:217], v169 offset:4704
	ds_read_b128 v[222:225], v155 offset:96
	ds_read_b128 v[230:233], v155 offset:4704
	ds_read_b128 v[238:241], v155 offset:9312
	ds_read_b128 v[246:249], v155 offset:13920
	s_waitcnt lgkmcnt(10)
	v_mfma_f32_32x32x16_bf16 v[80:95], v[226:229], v[194:197], v[80:95]
	v_mfma_f32_32x32x16_bf16 v[64:79], v[226:229], v[210:213], v[64:79]
	s_waitcnt lgkmcnt(9)
	v_mfma_f32_32x32x16_bf16 v[48:63], v[234:237], v[194:197], v[48:63]
	v_mfma_f32_32x32x16_bf16 v[32:47], v[234:237], v[210:213], v[32:47]
	s_waitcnt lgkmcnt(8)
	v_mfma_f32_32x32x16_bf16 v[16:31], v[242:245], v[194:197], v[16:31]
	v_mfma_f32_32x32x16_bf16 v[0:15], v[242:245], v[210:213], v[0:15]
	v_mfma_f32_32x32x16_bf16 v[112:127], v[218:221], v[194:197], v[112:127]
	v_mfma_f32_32x32x16_bf16 v[96:111], v[218:221], v[210:213], v[96:111]
	s_waitcnt vmcnt(7)
	ds_write_b128 v128, v[130:133] offset:36864
	global_load_dwordx4 v[130:133], v[140:141], off offset:1152
	s_waitcnt vmcnt(7)
	ds_write_b128 v128, v[158:161] offset:46080
	global_load_dwordx4 v[158:161], v[138:139], off offset:1152
	s_waitcnt lgkmcnt(4)
	v_mfma_f32_32x32x16_bf16 v[80:95], v[230:233], v[198:201], v[80:95]
	v_mfma_f32_32x32x16_bf16 v[64:79], v[230:233], v[214:217], v[64:79]
	s_waitcnt lgkmcnt(3)
	v_mfma_f32_32x32x16_bf16 v[48:63], v[238:241], v[198:201], v[48:63]
	v_mfma_f32_32x32x16_bf16 v[32:47], v[238:241], v[214:217], v[32:47]
	s_waitcnt lgkmcnt(2)
	v_mfma_f32_32x32x16_bf16 v[16:31], v[246:249], v[198:201], v[16:31]
	v_mfma_f32_32x32x16_bf16 v[0:15], v[246:249], v[214:217], v[0:15]
	v_mfma_f32_32x32x16_bf16 v[112:127], v[222:225], v[198:201], v[112:127]
	v_mfma_f32_32x32x16_bf16 v[96:111], v[222:225], v[214:217], v[96:111]
	global_load_dwordx4 v[194:197], v[134:135], off offset:1152
	global_load_dwordx4 v[198:201], v[136:137], off offset:1152
	s_waitcnt vmcnt(9)
	ds_write_b128 v128, v[172:175] offset:55296
	s_waitcnt vmcnt(8)
	ds_write_b128 v128, v[182:185] offset:64512
	s_waitcnt lgkmcnt(0)
	s_barrier
	ds_read_b128 v[172:175], v163 offset:36864
	ds_read_b128 v[182:185], v163 offset:36896
	ds_read_b128 v[210:213], v163 offset:41472
	ds_read_b128 v[214:217], v163 offset:41504
	ds_read_b128 v[218:221], v154
	ds_read_b128 v[222:225], v154 offset:32
	ds_read_b128 v[226:229], v154 offset:4608
	ds_read_b128 v[230:233], v154 offset:4640
	ds_read_b128 v[234:237], v154 offset:9216
	ds_read_b128 v[238:241], v154 offset:9248
	ds_read_b128 v[242:245], v154 offset:13824
	ds_read_b128 v[246:249], v154 offset:13856
	s_waitcnt lgkmcnt(5)
	v_mfma_f32_32x32x16_bf16 v[80:95], v[226:229], v[172:175], v[80:95]
	v_mfma_f32_32x32x16_bf16 v[64:79], v[226:229], v[210:213], v[64:79]
	s_waitcnt lgkmcnt(3)
	v_mfma_f32_32x32x16_bf16 v[48:63], v[234:237], v[172:175], v[48:63]
	v_mfma_f32_32x32x16_bf16 v[32:47], v[234:237], v[210:213], v[32:47]
	s_waitcnt lgkmcnt(1)
	v_mfma_f32_32x32x16_bf16 v[16:31], v[242:245], v[172:175], v[16:31]
	v_mfma_f32_32x32x16_bf16 v[0:15], v[242:245], v[210:213], v[0:15]
	v_mfma_f32_32x32x16_bf16 v[112:127], v[218:221], v[172:175], v[112:127]
	v_mfma_f32_32x32x16_bf16 v[96:111], v[218:221], v[210:213], v[96:111]
	global_load_dwordx4 v[172:175], v[148:149], off offset:1280
	global_load_dwordx4 v[210:213], v[150:151], off offset:1280
	s_waitcnt vmcnt(9)
	ds_write_b128 v164, v[186:189]
	s_waitcnt vmcnt(8)
	ds_write_b128 v164, v[202:205] offset:9216
	ds_read_b128 v[186:189], v163 offset:36928
	ds_read_b128 v[202:205], v163 offset:41536
	ds_read_b128 v[218:221], v154 offset:64
	ds_read_b128 v[226:229], v154 offset:4672
	ds_read_b128 v[234:237], v154 offset:9280
	ds_read_b128 v[242:245], v154 offset:13888
	v_mfma_f32_32x32x16_bf16 v[80:95], v[230:233], v[182:185], v[80:95]
	v_mfma_f32_32x32x16_bf16 v[64:79], v[230:233], v[214:217], v[64:79]
	v_mfma_f32_32x32x16_bf16 v[48:63], v[238:241], v[182:185], v[48:63]
	v_mfma_f32_32x32x16_bf16 v[32:47], v[238:241], v[214:217], v[32:47]
	s_waitcnt lgkmcnt(8)
	v_mfma_f32_32x32x16_bf16 v[16:31], v[246:249], v[182:185], v[16:31]
	v_mfma_f32_32x32x16_bf16 v[0:15], v[246:249], v[214:217], v[0:15]
	v_mfma_f32_32x32x16_bf16 v[112:127], v[222:225], v[182:185], v[112:127]
	v_mfma_f32_32x32x16_bf16 v[96:111], v[222:225], v[214:217], v[96:111]
	global_load_dwordx4 v[182:185], v[144:145], off offset:1280
	global_load_dwordx4 v[214:217], v[146:147], off offset:1280
	s_waitcnt vmcnt(9)
	ds_write_b128 v164, v[190:193] offset:18432
	s_waitcnt vmcnt(8)
	ds_write_b128 v164, v[206:209] offset:27648
	ds_read_b128 v[190:193], v163 offset:36960
	ds_read_b128 v[206:209], v163 offset:41568
	ds_read_b128 v[222:225], v154 offset:96
	ds_read_b128 v[230:233], v154 offset:4704
	ds_read_b128 v[238:241], v154 offset:9312
	ds_read_b128 v[246:249], v154 offset:13920
	s_waitcnt lgkmcnt(10)
	v_mfma_f32_32x32x16_bf16 v[80:95], v[226:229], v[186:189], v[80:95]
	v_mfma_f32_32x32x16_bf16 v[64:79], v[226:229], v[202:205], v[64:79]
	s_waitcnt lgkmcnt(9)
	v_mfma_f32_32x32x16_bf16 v[48:63], v[234:237], v[186:189], v[48:63]
	v_mfma_f32_32x32x16_bf16 v[32:47], v[234:237], v[202:205], v[32:47]
	s_waitcnt lgkmcnt(8)
	v_mfma_f32_32x32x16_bf16 v[16:31], v[242:245], v[186:189], v[16:31]
	v_mfma_f32_32x32x16_bf16 v[0:15], v[242:245], v[202:205], v[0:15]
	v_mfma_f32_32x32x16_bf16 v[112:127], v[218:221], v[186:189], v[112:127]
	v_mfma_f32_32x32x16_bf16 v[96:111], v[218:221], v[202:205], v[96:111]
	s_waitcnt vmcnt(7)
	ds_write_b128 v165, v[130:133]
	global_load_dwordx4 v[130:133], v[140:141], off offset:1280
	s_waitcnt vmcnt(7)
	ds_write_b128 v166, v[158:161]
	global_load_dwordx4 v[158:161], v[138:139], off offset:1280
	s_waitcnt lgkmcnt(4)
	v_mfma_f32_32x32x16_bf16 v[80:95], v[230:233], v[190:193], v[80:95]
	v_mfma_f32_32x32x16_bf16 v[64:79], v[230:233], v[206:209], v[64:79]
	s_waitcnt lgkmcnt(3)
	v_mfma_f32_32x32x16_bf16 v[48:63], v[238:241], v[190:193], v[48:63]
	v_mfma_f32_32x32x16_bf16 v[32:47], v[238:241], v[206:209], v[32:47]
	s_waitcnt lgkmcnt(2)
	v_mfma_f32_32x32x16_bf16 v[16:31], v[246:249], v[190:193], v[16:31]
	v_mfma_f32_32x32x16_bf16 v[0:15], v[246:249], v[206:209], v[0:15]
	v_mfma_f32_32x32x16_bf16 v[112:127], v[222:225], v[190:193], v[112:127]
	v_mfma_f32_32x32x16_bf16 v[96:111], v[222:225], v[206:209], v[96:111]
	global_load_dwordx4 v[186:189], v[134:135], off offset:1280
	global_load_dwordx4 v[190:193], v[136:137], off offset:1280
	s_waitcnt vmcnt(9)
	ds_write_b128 v167, v[194:197]
	s_waitcnt vmcnt(8)
	ds_write_b128 v168, v[198:201]
	s_waitcnt lgkmcnt(0)
	s_barrier
	ds_read_b128 v[194:197], v169
	ds_read_b128 v[198:201], v169 offset:32
	ds_read_b128 v[202:205], v169 offset:4608
	ds_read_b128 v[206:209], v169 offset:4640
	ds_read_b128 v[218:221], v155
	ds_read_b128 v[222:225], v155 offset:32
	ds_read_b128 v[226:229], v155 offset:4608
	ds_read_b128 v[230:233], v155 offset:4640
	ds_read_b128 v[234:237], v155 offset:9216
	ds_read_b128 v[238:241], v155 offset:9248
	ds_read_b128 v[242:245], v155 offset:13824
	ds_read_b128 v[246:249], v155 offset:13856
	s_waitcnt lgkmcnt(5)
	v_mfma_f32_32x32x16_bf16 v[80:95], v[226:229], v[194:197], v[80:95]
	v_mfma_f32_32x32x16_bf16 v[64:79], v[226:229], v[202:205], v[64:79]
	s_waitcnt lgkmcnt(3)
	v_mfma_f32_32x32x16_bf16 v[48:63], v[234:237], v[194:197], v[48:63]
	v_mfma_f32_32x32x16_bf16 v[32:47], v[234:237], v[202:205], v[32:47]
	s_waitcnt lgkmcnt(1)
	v_mfma_f32_32x32x16_bf16 v[16:31], v[242:245], v[194:197], v[16:31]
	v_mfma_f32_32x32x16_bf16 v[0:15], v[242:245], v[202:205], v[0:15]
	v_mfma_f32_32x32x16_bf16 v[112:127], v[218:221], v[194:197], v[112:127]
	v_mfma_f32_32x32x16_bf16 v[96:111], v[218:221], v[202:205], v[96:111]
	global_load_dwordx4 v[194:197], v[148:149], off offset:1408
	global_load_dwordx4 v[202:205], v[150:151], off offset:1408
	s_waitcnt vmcnt(9)
	ds_write_b128 v128, v[172:175]
	s_waitcnt vmcnt(8)
	ds_write_b128 v128, v[210:213] offset:9216
	ds_read_b128 v[172:175], v169 offset:64
	ds_read_b128 v[210:213], v169 offset:4672
	ds_read_b128 v[218:221], v155 offset:64
	ds_read_b128 v[226:229], v155 offset:4672
	ds_read_b128 v[234:237], v155 offset:9280
	ds_read_b128 v[242:245], v155 offset:13888
	v_mfma_f32_32x32x16_bf16 v[80:95], v[230:233], v[198:201], v[80:95]
	v_mfma_f32_32x32x16_bf16 v[64:79], v[230:233], v[206:209], v[64:79]
	v_mfma_f32_32x32x16_bf16 v[48:63], v[238:241], v[198:201], v[48:63]
	v_mfma_f32_32x32x16_bf16 v[32:47], v[238:241], v[206:209], v[32:47]
	s_waitcnt lgkmcnt(8)
	v_mfma_f32_32x32x16_bf16 v[16:31], v[246:249], v[198:201], v[16:31]
	v_mfma_f32_32x32x16_bf16 v[0:15], v[246:249], v[206:209], v[0:15]
	v_mfma_f32_32x32x16_bf16 v[112:127], v[222:225], v[198:201], v[112:127]
	v_mfma_f32_32x32x16_bf16 v[96:111], v[222:225], v[206:209], v[96:111]
	global_load_dwordx4 v[198:201], v[144:145], off offset:1408
	global_load_dwordx4 v[206:209], v[146:147], off offset:1408
	s_waitcnt vmcnt(9)
	ds_write_b128 v128, v[182:185] offset:18432
	s_waitcnt vmcnt(8)
	ds_write_b128 v128, v[214:217] offset:27648
	ds_read_b128 v[182:185], v169 offset:96
	ds_read_b128 v[214:217], v169 offset:4704
	ds_read_b128 v[222:225], v155 offset:96
	ds_read_b128 v[230:233], v155 offset:4704
	ds_read_b128 v[238:241], v155 offset:9312
	ds_read_b128 v[246:249], v155 offset:13920
	s_waitcnt lgkmcnt(10)
	v_mfma_f32_32x32x16_bf16 v[80:95], v[226:229], v[172:175], v[80:95]
	v_mfma_f32_32x32x16_bf16 v[64:79], v[226:229], v[210:213], v[64:79]
	s_waitcnt lgkmcnt(9)
	v_mfma_f32_32x32x16_bf16 v[48:63], v[234:237], v[172:175], v[48:63]
	v_mfma_f32_32x32x16_bf16 v[32:47], v[234:237], v[210:213], v[32:47]
	s_waitcnt lgkmcnt(8)
	v_mfma_f32_32x32x16_bf16 v[16:31], v[242:245], v[172:175], v[16:31]
	v_mfma_f32_32x32x16_bf16 v[0:15], v[242:245], v[210:213], v[0:15]
	v_mfma_f32_32x32x16_bf16 v[112:127], v[218:221], v[172:175], v[112:127]
	v_mfma_f32_32x32x16_bf16 v[96:111], v[218:221], v[210:213], v[96:111]
	s_waitcnt vmcnt(7)
	ds_write_b128 v128, v[130:133] offset:36864
	global_load_dwordx4 v[130:133], v[140:141], off offset:1408
	s_waitcnt vmcnt(7)
	ds_write_b128 v128, v[158:161] offset:46080
	global_load_dwordx4 v[158:161], v[138:139], off offset:1408
	s_waitcnt lgkmcnt(4)
	v_mfma_f32_32x32x16_bf16 v[80:95], v[230:233], v[182:185], v[80:95]
	v_mfma_f32_32x32x16_bf16 v[64:79], v[230:233], v[214:217], v[64:79]
	s_waitcnt lgkmcnt(3)
	v_mfma_f32_32x32x16_bf16 v[48:63], v[238:241], v[182:185], v[48:63]
	v_mfma_f32_32x32x16_bf16 v[32:47], v[238:241], v[214:217], v[32:47]
	s_waitcnt lgkmcnt(2)
	v_mfma_f32_32x32x16_bf16 v[16:31], v[246:249], v[182:185], v[16:31]
	v_mfma_f32_32x32x16_bf16 v[0:15], v[246:249], v[214:217], v[0:15]
	v_mfma_f32_32x32x16_bf16 v[112:127], v[222:225], v[182:185], v[112:127]
	v_mfma_f32_32x32x16_bf16 v[96:111], v[222:225], v[214:217], v[96:111]
	global_load_dwordx4 v[172:175], v[134:135], off offset:1408
	global_load_dwordx4 v[182:185], v[136:137], off offset:1408
	s_waitcnt vmcnt(9)
	ds_write_b128 v128, v[186:189] offset:55296
	s_waitcnt vmcnt(8)
	ds_write_b128 v128, v[190:193] offset:64512
	s_waitcnt lgkmcnt(0)
	s_barrier
	ds_read_b128 v[186:189], v163 offset:36864
	ds_read_b128 v[190:193], v163 offset:36896
	ds_read_b128 v[210:213], v163 offset:41472
	ds_read_b128 v[214:217], v163 offset:41504
	ds_read_b128 v[218:221], v154
	ds_read_b128 v[222:225], v154 offset:32
	ds_read_b128 v[226:229], v154 offset:4608
	ds_read_b128 v[230:233], v154 offset:4640
	ds_read_b128 v[234:237], v154 offset:9216
	ds_read_b128 v[238:241], v154 offset:9248
	ds_read_b128 v[242:245], v154 offset:13824
	ds_read_b128 v[246:249], v154 offset:13856
	s_waitcnt lgkmcnt(5)
	v_mfma_f32_32x32x16_bf16 v[80:95], v[226:229], v[186:189], v[80:95]
	v_mfma_f32_32x32x16_bf16 v[64:79], v[226:229], v[210:213], v[64:79]
	s_waitcnt lgkmcnt(3)
	v_mfma_f32_32x32x16_bf16 v[48:63], v[234:237], v[186:189], v[48:63]
	v_mfma_f32_32x32x16_bf16 v[32:47], v[234:237], v[210:213], v[32:47]
	s_waitcnt lgkmcnt(1)
	v_mfma_f32_32x32x16_bf16 v[16:31], v[242:245], v[186:189], v[16:31]
	v_mfma_f32_32x32x16_bf16 v[0:15], v[242:245], v[210:213], v[0:15]
	v_mfma_f32_32x32x16_bf16 v[112:127], v[218:221], v[186:189], v[112:127]
	v_mfma_f32_32x32x16_bf16 v[96:111], v[218:221], v[210:213], v[96:111]
	global_load_dwordx4 v[186:189], v[148:149], off offset:1536
	global_load_dwordx4 v[210:213], v[150:151], off offset:1536
	s_waitcnt vmcnt(9)
	ds_write_b128 v164, v[194:197]
	s_waitcnt vmcnt(8)
	ds_write_b128 v164, v[202:205] offset:9216
	ds_read_b128 v[194:197], v163 offset:36928
	ds_read_b128 v[202:205], v163 offset:41536
	ds_read_b128 v[218:221], v154 offset:64
	ds_read_b128 v[226:229], v154 offset:4672
	ds_read_b128 v[234:237], v154 offset:9280
	ds_read_b128 v[242:245], v154 offset:13888
	v_mfma_f32_32x32x16_bf16 v[80:95], v[230:233], v[190:193], v[80:95]
	v_mfma_f32_32x32x16_bf16 v[64:79], v[230:233], v[214:217], v[64:79]
	v_mfma_f32_32x32x16_bf16 v[48:63], v[238:241], v[190:193], v[48:63]
	v_mfma_f32_32x32x16_bf16 v[32:47], v[238:241], v[214:217], v[32:47]
	s_waitcnt lgkmcnt(8)
	v_mfma_f32_32x32x16_bf16 v[16:31], v[246:249], v[190:193], v[16:31]
	v_mfma_f32_32x32x16_bf16 v[0:15], v[246:249], v[214:217], v[0:15]
	v_mfma_f32_32x32x16_bf16 v[112:127], v[222:225], v[190:193], v[112:127]
	v_mfma_f32_32x32x16_bf16 v[96:111], v[222:225], v[214:217], v[96:111]
	global_load_dwordx4 v[190:193], v[144:145], off offset:1536
	global_load_dwordx4 v[214:217], v[146:147], off offset:1536
	s_waitcnt vmcnt(9)
	ds_write_b128 v164, v[198:201] offset:18432
	s_waitcnt vmcnt(8)
	ds_write_b128 v164, v[206:209] offset:27648
	ds_read_b128 v[198:201], v163 offset:36960
	ds_read_b128 v[206:209], v163 offset:41568
	ds_read_b128 v[222:225], v154 offset:96
	ds_read_b128 v[230:233], v154 offset:4704
	ds_read_b128 v[238:241], v154 offset:9312
	ds_read_b128 v[246:249], v154 offset:13920
	s_waitcnt lgkmcnt(10)
	v_mfma_f32_32x32x16_bf16 v[80:95], v[226:229], v[194:197], v[80:95]
	v_mfma_f32_32x32x16_bf16 v[64:79], v[226:229], v[202:205], v[64:79]
	s_waitcnt lgkmcnt(9)
	v_mfma_f32_32x32x16_bf16 v[48:63], v[234:237], v[194:197], v[48:63]
	v_mfma_f32_32x32x16_bf16 v[32:47], v[234:237], v[202:205], v[32:47]
	s_waitcnt lgkmcnt(8)
	v_mfma_f32_32x32x16_bf16 v[16:31], v[242:245], v[194:197], v[16:31]
	v_mfma_f32_32x32x16_bf16 v[0:15], v[242:245], v[202:205], v[0:15]
	v_mfma_f32_32x32x16_bf16 v[112:127], v[218:221], v[194:197], v[112:127]
	v_mfma_f32_32x32x16_bf16 v[96:111], v[218:221], v[202:205], v[96:111]
	s_waitcnt vmcnt(7)
	ds_write_b128 v165, v[130:133]
	global_load_dwordx4 v[130:133], v[140:141], off offset:1536
	s_waitcnt vmcnt(7)
	ds_write_b128 v166, v[158:161]
	global_load_dwordx4 v[158:161], v[138:139], off offset:1536
	s_waitcnt lgkmcnt(4)
	v_mfma_f32_32x32x16_bf16 v[80:95], v[230:233], v[198:201], v[80:95]
	v_mfma_f32_32x32x16_bf16 v[64:79], v[230:233], v[206:209], v[64:79]
	s_waitcnt lgkmcnt(3)
	v_mfma_f32_32x32x16_bf16 v[48:63], v[238:241], v[198:201], v[48:63]
	v_mfma_f32_32x32x16_bf16 v[32:47], v[238:241], v[206:209], v[32:47]
	s_waitcnt lgkmcnt(2)
	v_mfma_f32_32x32x16_bf16 v[16:31], v[246:249], v[198:201], v[16:31]
	v_mfma_f32_32x32x16_bf16 v[0:15], v[246:249], v[206:209], v[0:15]
	v_mfma_f32_32x32x16_bf16 v[112:127], v[222:225], v[198:201], v[112:127]
	v_mfma_f32_32x32x16_bf16 v[96:111], v[222:225], v[206:209], v[96:111]
	global_load_dwordx4 v[194:197], v[134:135], off offset:1536
	global_load_dwordx4 v[198:201], v[136:137], off offset:1536
	s_waitcnt vmcnt(9)
	ds_write_b128 v167, v[172:175]
	s_waitcnt vmcnt(8)
	ds_write_b128 v168, v[182:185]
	s_waitcnt lgkmcnt(0)
	s_barrier
	ds_read_b128 v[172:175], v169
	ds_read_b128 v[182:185], v169 offset:32
	ds_read_b128 v[202:205], v169 offset:4608
	ds_read_b128 v[206:209], v169 offset:4640
	ds_read_b128 v[218:221], v155
	ds_read_b128 v[222:225], v155 offset:32
	ds_read_b128 v[226:229], v155 offset:4608
	ds_read_b128 v[230:233], v155 offset:4640
	ds_read_b128 v[234:237], v155 offset:9216
	ds_read_b128 v[238:241], v155 offset:9248
	ds_read_b128 v[242:245], v155 offset:13824
	ds_read_b128 v[246:249], v155 offset:13856
	s_waitcnt lgkmcnt(5)
	v_mfma_f32_32x32x16_bf16 v[80:95], v[226:229], v[172:175], v[80:95]
	v_mfma_f32_32x32x16_bf16 v[64:79], v[226:229], v[202:205], v[64:79]
	s_waitcnt lgkmcnt(3)
	v_mfma_f32_32x32x16_bf16 v[48:63], v[234:237], v[172:175], v[48:63]
	v_mfma_f32_32x32x16_bf16 v[32:47], v[234:237], v[202:205], v[32:47]
	s_waitcnt lgkmcnt(1)
	v_mfma_f32_32x32x16_bf16 v[16:31], v[242:245], v[172:175], v[16:31]
	v_mfma_f32_32x32x16_bf16 v[0:15], v[242:245], v[202:205], v[0:15]
	v_mfma_f32_32x32x16_bf16 v[112:127], v[218:221], v[172:175], v[112:127]
	v_mfma_f32_32x32x16_bf16 v[96:111], v[218:221], v[202:205], v[96:111]
	global_load_dwordx4 v[172:175], v[148:149], off offset:1664
	global_load_dwordx4 v[202:205], v[150:151], off offset:1664
	s_waitcnt vmcnt(9)
	ds_write_b128 v128, v[186:189]
	s_waitcnt vmcnt(8)
	ds_write_b128 v128, v[210:213] offset:9216
	ds_read_b128 v[186:189], v169 offset:64
	ds_read_b128 v[210:213], v169 offset:4672
	ds_read_b128 v[218:221], v155 offset:64
	ds_read_b128 v[226:229], v155 offset:4672
	ds_read_b128 v[234:237], v155 offset:9280
	ds_read_b128 v[242:245], v155 offset:13888
	v_mfma_f32_32x32x16_bf16 v[80:95], v[230:233], v[182:185], v[80:95]
	v_mfma_f32_32x32x16_bf16 v[64:79], v[230:233], v[206:209], v[64:79]
	v_mfma_f32_32x32x16_bf16 v[48:63], v[238:241], v[182:185], v[48:63]
	v_mfma_f32_32x32x16_bf16 v[32:47], v[238:241], v[206:209], v[32:47]
	s_waitcnt lgkmcnt(8)
	v_mfma_f32_32x32x16_bf16 v[16:31], v[246:249], v[182:185], v[16:31]
	v_mfma_f32_32x32x16_bf16 v[0:15], v[246:249], v[206:209], v[0:15]
	v_mfma_f32_32x32x16_bf16 v[112:127], v[222:225], v[182:185], v[112:127]
	v_mfma_f32_32x32x16_bf16 v[96:111], v[222:225], v[206:209], v[96:111]
	global_load_dwordx4 v[182:185], v[144:145], off offset:1664
	global_load_dwordx4 v[206:209], v[146:147], off offset:1664
	s_waitcnt vmcnt(9)
	ds_write_b128 v128, v[190:193] offset:18432
	s_waitcnt vmcnt(8)
	ds_write_b128 v128, v[214:217] offset:27648
	ds_read_b128 v[190:193], v169 offset:96
	ds_read_b128 v[214:217], v169 offset:4704
	ds_read_b128 v[222:225], v155 offset:96
	ds_read_b128 v[230:233], v155 offset:4704
	ds_read_b128 v[238:241], v155 offset:9312
	ds_read_b128 v[246:249], v155 offset:13920
	s_waitcnt lgkmcnt(10)
	v_mfma_f32_32x32x16_bf16 v[80:95], v[226:229], v[186:189], v[80:95]
	v_mfma_f32_32x32x16_bf16 v[64:79], v[226:229], v[210:213], v[64:79]
	s_waitcnt lgkmcnt(9)
	v_mfma_f32_32x32x16_bf16 v[48:63], v[234:237], v[186:189], v[48:63]
	v_mfma_f32_32x32x16_bf16 v[32:47], v[234:237], v[210:213], v[32:47]
	s_waitcnt lgkmcnt(8)
	v_mfma_f32_32x32x16_bf16 v[16:31], v[242:245], v[186:189], v[16:31]
	v_mfma_f32_32x32x16_bf16 v[0:15], v[242:245], v[210:213], v[0:15]
	v_mfma_f32_32x32x16_bf16 v[112:127], v[218:221], v[186:189], v[112:127]
	v_mfma_f32_32x32x16_bf16 v[96:111], v[218:221], v[210:213], v[96:111]
	s_waitcnt vmcnt(7)
	ds_write_b128 v128, v[130:133] offset:36864
	global_load_dwordx4 v[130:133], v[140:141], off offset:1664
	s_waitcnt vmcnt(7)
	ds_write_b128 v128, v[158:161] offset:46080
	global_load_dwordx4 v[158:161], v[138:139], off offset:1664
	s_waitcnt lgkmcnt(4)
	v_mfma_f32_32x32x16_bf16 v[80:95], v[230:233], v[190:193], v[80:95]
	v_mfma_f32_32x32x16_bf16 v[64:79], v[230:233], v[214:217], v[64:79]
	s_waitcnt lgkmcnt(3)
	v_mfma_f32_32x32x16_bf16 v[48:63], v[238:241], v[190:193], v[48:63]
	v_mfma_f32_32x32x16_bf16 v[32:47], v[238:241], v[214:217], v[32:47]
	s_waitcnt lgkmcnt(2)
	v_mfma_f32_32x32x16_bf16 v[16:31], v[246:249], v[190:193], v[16:31]
	v_mfma_f32_32x32x16_bf16 v[0:15], v[246:249], v[214:217], v[0:15]
	v_mfma_f32_32x32x16_bf16 v[112:127], v[222:225], v[190:193], v[112:127]
	v_mfma_f32_32x32x16_bf16 v[96:111], v[222:225], v[214:217], v[96:111]
	global_load_dwordx4 v[186:189], v[134:135], off offset:1664
	global_load_dwordx4 v[190:193], v[136:137], off offset:1664
	s_waitcnt vmcnt(9)
	ds_write_b128 v128, v[194:197] offset:55296
	s_waitcnt vmcnt(8)
	ds_write_b128 v128, v[198:201] offset:64512
	s_waitcnt lgkmcnt(0)
	s_barrier
	ds_read_b128 v[194:197], v163 offset:36864
	ds_read_b128 v[198:201], v163 offset:36896
	ds_read_b128 v[210:213], v163 offset:41472
	ds_read_b128 v[214:217], v163 offset:41504
	ds_read_b128 v[218:221], v154
	ds_read_b128 v[222:225], v154 offset:32
	ds_read_b128 v[226:229], v154 offset:4608
	ds_read_b128 v[230:233], v154 offset:4640
	ds_read_b128 v[234:237], v154 offset:9216
	ds_read_b128 v[238:241], v154 offset:9248
	ds_read_b128 v[242:245], v154 offset:13824
	ds_read_b128 v[246:249], v154 offset:13856
	s_waitcnt lgkmcnt(5)
	v_mfma_f32_32x32x16_bf16 v[80:95], v[226:229], v[194:197], v[80:95]
	v_mfma_f32_32x32x16_bf16 v[64:79], v[226:229], v[210:213], v[64:79]
	s_waitcnt lgkmcnt(3)
	v_mfma_f32_32x32x16_bf16 v[48:63], v[234:237], v[194:197], v[48:63]
	v_mfma_f32_32x32x16_bf16 v[32:47], v[234:237], v[210:213], v[32:47]
	s_waitcnt lgkmcnt(1)
	v_mfma_f32_32x32x16_bf16 v[16:31], v[242:245], v[194:197], v[16:31]
	v_mfma_f32_32x32x16_bf16 v[0:15], v[242:245], v[210:213], v[0:15]
	v_mfma_f32_32x32x16_bf16 v[112:127], v[218:221], v[194:197], v[112:127]
	v_mfma_f32_32x32x16_bf16 v[96:111], v[218:221], v[210:213], v[96:111]
	global_load_dwordx4 v[194:197], v[148:149], off offset:1792
	global_load_dwordx4 v[210:213], v[150:151], off offset:1792
	s_waitcnt vmcnt(9)
	ds_write_b128 v164, v[172:175]
	s_waitcnt vmcnt(8)
	ds_write_b128 v164, v[202:205] offset:9216
	ds_read_b128 v[172:175], v163 offset:36928
	ds_read_b128 v[202:205], v163 offset:41536
	ds_read_b128 v[218:221], v154 offset:64
	ds_read_b128 v[226:229], v154 offset:4672
	ds_read_b128 v[234:237], v154 offset:9280
	ds_read_b128 v[242:245], v154 offset:13888
	v_mfma_f32_32x32x16_bf16 v[80:95], v[230:233], v[198:201], v[80:95]
	v_mfma_f32_32x32x16_bf16 v[64:79], v[230:233], v[214:217], v[64:79]
	v_mfma_f32_32x32x16_bf16 v[48:63], v[238:241], v[198:201], v[48:63]
	v_mfma_f32_32x32x16_bf16 v[32:47], v[238:241], v[214:217], v[32:47]
	s_waitcnt lgkmcnt(8)
	v_mfma_f32_32x32x16_bf16 v[16:31], v[246:249], v[198:201], v[16:31]
	v_mfma_f32_32x32x16_bf16 v[0:15], v[246:249], v[214:217], v[0:15]
	v_mfma_f32_32x32x16_bf16 v[112:127], v[222:225], v[198:201], v[112:127]
	v_mfma_f32_32x32x16_bf16 v[96:111], v[222:225], v[214:217], v[96:111]
	global_load_dwordx4 v[198:201], v[144:145], off offset:1792
	global_load_dwordx4 v[214:217], v[146:147], off offset:1792
	s_waitcnt vmcnt(9)
	ds_write_b128 v164, v[182:185] offset:18432
	s_waitcnt vmcnt(8)
	ds_write_b128 v164, v[206:209] offset:27648
	ds_read_b128 v[182:185], v163 offset:36960
	ds_read_b128 v[206:209], v163 offset:41568
	ds_read_b128 v[222:225], v154 offset:96
	ds_read_b128 v[230:233], v154 offset:4704
	ds_read_b128 v[238:241], v154 offset:9312
	ds_read_b128 v[246:249], v154 offset:13920
	s_waitcnt lgkmcnt(10)
	v_mfma_f32_32x32x16_bf16 v[80:95], v[226:229], v[172:175], v[80:95]
	v_mfma_f32_32x32x16_bf16 v[64:79], v[226:229], v[202:205], v[64:79]
	s_waitcnt lgkmcnt(9)
	v_mfma_f32_32x32x16_bf16 v[48:63], v[234:237], v[172:175], v[48:63]
	v_mfma_f32_32x32x16_bf16 v[32:47], v[234:237], v[202:205], v[32:47]
	s_waitcnt lgkmcnt(8)
	v_mfma_f32_32x32x16_bf16 v[16:31], v[242:245], v[172:175], v[16:31]
	v_mfma_f32_32x32x16_bf16 v[0:15], v[242:245], v[202:205], v[0:15]
	v_mfma_f32_32x32x16_bf16 v[112:127], v[218:221], v[172:175], v[112:127]
	v_mfma_f32_32x32x16_bf16 v[96:111], v[218:221], v[202:205], v[96:111]
	s_waitcnt vmcnt(7)
	ds_write_b128 v165, v[130:133]
	global_load_dwordx4 v[130:133], v[140:141], off offset:1792
	s_waitcnt vmcnt(7)
	ds_write_b128 v166, v[158:161]
	global_load_dwordx4 v[158:161], v[138:139], off offset:1792
	s_waitcnt lgkmcnt(4)
	v_mfma_f32_32x32x16_bf16 v[80:95], v[230:233], v[182:185], v[80:95]
	v_mfma_f32_32x32x16_bf16 v[64:79], v[230:233], v[206:209], v[64:79]
	s_waitcnt lgkmcnt(3)
	v_mfma_f32_32x32x16_bf16 v[48:63], v[238:241], v[182:185], v[48:63]
	v_mfma_f32_32x32x16_bf16 v[32:47], v[238:241], v[206:209], v[32:47]
	s_waitcnt lgkmcnt(2)
	v_mfma_f32_32x32x16_bf16 v[16:31], v[246:249], v[182:185], v[16:31]
	v_mfma_f32_32x32x16_bf16 v[0:15], v[246:249], v[206:209], v[0:15]
	v_mfma_f32_32x32x16_bf16 v[112:127], v[222:225], v[182:185], v[112:127]
	v_mfma_f32_32x32x16_bf16 v[96:111], v[222:225], v[206:209], v[96:111]
	global_load_dwordx4 v[172:175], v[134:135], off offset:1792
	global_load_dwordx4 v[182:185], v[136:137], off offset:1792
	s_waitcnt vmcnt(9)
	ds_write_b128 v167, v[186:189]
	s_waitcnt vmcnt(8)
	ds_write_b128 v168, v[190:193]
	s_waitcnt lgkmcnt(0)
	s_barrier
	ds_read_b128 v[186:189], v169
	ds_read_b128 v[190:193], v169 offset:32
	ds_read_b128 v[202:205], v169 offset:4608
	ds_read_b128 v[206:209], v169 offset:4640
	ds_read_b128 v[218:221], v155
	ds_read_b128 v[222:225], v155 offset:32
	ds_read_b128 v[226:229], v155 offset:4608
	ds_read_b128 v[230:233], v155 offset:4640
	ds_read_b128 v[234:237], v155 offset:9216
	ds_read_b128 v[238:241], v155 offset:9248
	ds_read_b128 v[242:245], v155 offset:13824
	ds_read_b128 v[246:249], v155 offset:13856
	s_waitcnt lgkmcnt(5)
	v_mfma_f32_32x32x16_bf16 v[80:95], v[226:229], v[186:189], v[80:95]
	v_mfma_f32_32x32x16_bf16 v[64:79], v[226:229], v[202:205], v[64:79]
	s_waitcnt lgkmcnt(3)
	v_mfma_f32_32x32x16_bf16 v[48:63], v[234:237], v[186:189], v[48:63]
	v_mfma_f32_32x32x16_bf16 v[32:47], v[234:237], v[202:205], v[32:47]
	s_waitcnt lgkmcnt(1)
	v_mfma_f32_32x32x16_bf16 v[16:31], v[242:245], v[186:189], v[16:31]
	v_mfma_f32_32x32x16_bf16 v[0:15], v[242:245], v[202:205], v[0:15]
	v_mfma_f32_32x32x16_bf16 v[112:127], v[218:221], v[186:189], v[112:127]
	v_mfma_f32_32x32x16_bf16 v[96:111], v[218:221], v[202:205], v[96:111]
	global_load_dwordx4 v[186:189], v[148:149], off offset:1920
	s_nop 0
	global_load_dwordx4 v[148:151], v[150:151], off offset:1920
	s_waitcnt vmcnt(9)
	ds_write_b128 v128, v[194:197]
	s_waitcnt vmcnt(8)
	ds_write_b128 v128, v[210:213] offset:9216
	ds_read_b128 v[194:197], v169 offset:64
	ds_read_b128 v[202:205], v169 offset:4672
	ds_read_b128 v[210:213], v155 offset:64
	ds_read_b128 v[218:221], v155 offset:4672
	ds_read_b128 v[226:229], v155 offset:9280
	ds_read_b128 v[234:237], v155 offset:13888
	v_mfma_f32_32x32x16_bf16 v[80:95], v[230:233], v[190:193], v[80:95]
	v_mfma_f32_32x32x16_bf16 v[64:79], v[230:233], v[206:209], v[64:79]
	v_mfma_f32_32x32x16_bf16 v[48:63], v[238:241], v[190:193], v[48:63]
	v_mfma_f32_32x32x16_bf16 v[32:47], v[238:241], v[206:209], v[32:47]
	s_waitcnt lgkmcnt(8)
	v_mfma_f32_32x32x16_bf16 v[16:31], v[246:249], v[190:193], v[16:31]
	v_mfma_f32_32x32x16_bf16 v[0:15], v[246:249], v[206:209], v[0:15]
	v_mfma_f32_32x32x16_bf16 v[112:127], v[222:225], v[190:193], v[112:127]
	v_mfma_f32_32x32x16_bf16 v[96:111], v[222:225], v[206:209], v[96:111]
	global_load_dwordx4 v[190:193], v[144:145], off offset:1920
	s_nop 0
	global_load_dwordx4 v[144:147], v[146:147], off offset:1920
	s_waitcnt vmcnt(9)
	ds_write_b128 v128, v[198:201] offset:18432
	s_waitcnt vmcnt(8)
	ds_write_b128 v128, v[214:217] offset:27648
	ds_read_b128 v[198:201], v169 offset:96
	ds_read_b128 v[206:209], v169 offset:4704
	ds_read_b128 v[214:217], v155 offset:96
	ds_read_b128 v[222:225], v155 offset:4704
	ds_read_b128 v[230:233], v155 offset:9312
	ds_read_b128 v[238:241], v155 offset:13920
	s_waitcnt lgkmcnt(10)
	v_mfma_f32_32x32x16_bf16 v[80:95], v[218:221], v[194:197], v[80:95]
	v_mfma_f32_32x32x16_bf16 v[64:79], v[218:221], v[202:205], v[64:79]
	s_waitcnt lgkmcnt(9)
	v_mfma_f32_32x32x16_bf16 v[48:63], v[226:229], v[194:197], v[48:63]
	v_mfma_f32_32x32x16_bf16 v[32:47], v[226:229], v[202:205], v[32:47]
	s_waitcnt lgkmcnt(8)
	v_mfma_f32_32x32x16_bf16 v[16:31], v[234:237], v[194:197], v[16:31]
	v_mfma_f32_32x32x16_bf16 v[0:15], v[234:237], v[202:205], v[0:15]
	v_mfma_f32_32x32x16_bf16 v[112:127], v[210:213], v[194:197], v[112:127]
	v_mfma_f32_32x32x16_bf16 v[96:111], v[210:213], v[202:205], v[96:111]
	s_waitcnt vmcnt(7)
	ds_write_b128 v128, v[130:133] offset:36864
	global_load_dwordx4 v[130:133], v[140:141], off offset:1920
	s_waitcnt vmcnt(7)
	ds_write_b128 v128, v[158:161] offset:46080
	global_load_dwordx4 v[138:141], v[138:139], off offset:1920
	s_waitcnt lgkmcnt(4)
	v_mfma_f32_32x32x16_bf16 v[80:95], v[222:225], v[198:201], v[80:95]
	v_mfma_f32_32x32x16_bf16 v[64:79], v[222:225], v[206:209], v[64:79]
	s_waitcnt lgkmcnt(3)
	v_mfma_f32_32x32x16_bf16 v[48:63], v[230:233], v[198:201], v[48:63]
	v_mfma_f32_32x32x16_bf16 v[32:47], v[230:233], v[206:209], v[32:47]
	s_waitcnt lgkmcnt(2)
	v_mfma_f32_32x32x16_bf16 v[16:31], v[238:241], v[198:201], v[16:31]
	v_mfma_f32_32x32x16_bf16 v[0:15], v[238:241], v[206:209], v[0:15]
	v_mfma_f32_32x32x16_bf16 v[112:127], v[214:217], v[198:201], v[112:127]
	v_mfma_f32_32x32x16_bf16 v[96:111], v[214:217], v[206:209], v[96:111]
	global_load_dwordx4 v[158:161], v[134:135], off offset:1920
	s_nop 0
	global_load_dwordx4 v[134:137], v[136:137], off offset:1920
	s_waitcnt vmcnt(9)
	ds_write_b128 v128, v[172:175] offset:55296
	s_waitcnt vmcnt(8)
	ds_write_b128 v128, v[182:185] offset:64512
	s_waitcnt lgkmcnt(0)
	s_barrier
	ds_read_b128 v[172:175], v163 offset:36864
	ds_read_b128 v[182:185], v163 offset:36896
	ds_read_b128 v[194:197], v163 offset:41472
	ds_read_b128 v[198:201], v163 offset:41504
	ds_read_b128 v[202:205], v154
	ds_read_b128 v[206:209], v154 offset:32
	ds_read_b128 v[210:213], v154 offset:4608
	ds_read_b128 v[214:217], v154 offset:4640
	ds_read_b128 v[218:221], v154 offset:9216
	ds_read_b128 v[222:225], v154 offset:9248
	ds_read_b128 v[226:229], v154 offset:13824
	ds_read_b128 v[230:233], v154 offset:13856
	s_waitcnt lgkmcnt(5)
	v_mfma_f32_32x32x16_bf16 v[80:95], v[210:213], v[172:175], v[80:95]
	v_mfma_f32_32x32x16_bf16 v[64:79], v[210:213], v[194:197], v[64:79]
	s_waitcnt lgkmcnt(3)
	v_mfma_f32_32x32x16_bf16 v[48:63], v[218:221], v[172:175], v[48:63]
	v_mfma_f32_32x32x16_bf16 v[32:47], v[218:221], v[194:197], v[32:47]
	s_waitcnt lgkmcnt(1)
	v_mfma_f32_32x32x16_bf16 v[16:31], v[226:229], v[172:175], v[16:31]
	v_mfma_f32_32x32x16_bf16 v[0:15], v[226:229], v[194:197], v[0:15]
	v_mfma_f32_32x32x16_bf16 v[112:127], v[202:205], v[172:175], v[112:127]
	v_mfma_f32_32x32x16_bf16 v[96:111], v[202:205], v[194:197], v[96:111]
	s_waitcnt vmcnt(7)
	ds_write_b128 v164, v[186:189]
	s_waitcnt vmcnt(6)
	ds_write_b128 v164, v[148:151] offset:9216
	ds_read_b128 v[148:151], v163 offset:36928
	ds_read_b128 v[172:175], v163 offset:41536
	ds_read_b128 v[186:189], v154 offset:64
	ds_read_b128 v[194:197], v154 offset:4672
	ds_read_b128 v[202:205], v154 offset:9280
	ds_read_b128 v[210:213], v154 offset:13888
	v_mfma_f32_32x32x16_bf16 v[80:95], v[214:217], v[182:185], v[80:95]
	v_mfma_f32_32x32x16_bf16 v[64:79], v[214:217], v[198:201], v[64:79]
	v_mfma_f32_32x32x16_bf16 v[48:63], v[222:225], v[182:185], v[48:63]
	v_mfma_f32_32x32x16_bf16 v[32:47], v[222:225], v[198:201], v[32:47]
	s_waitcnt lgkmcnt(8)
	v_mfma_f32_32x32x16_bf16 v[16:31], v[230:233], v[182:185], v[16:31]
	v_mfma_f32_32x32x16_bf16 v[0:15], v[230:233], v[198:201], v[0:15]
	v_mfma_f32_32x32x16_bf16 v[112:127], v[206:209], v[182:185], v[112:127]
	v_mfma_f32_32x32x16_bf16 v[96:111], v[206:209], v[198:201], v[96:111]
	s_waitcnt vmcnt(5)
	ds_write_b128 v164, v[190:193] offset:18432
	s_waitcnt vmcnt(4)
	ds_write_b128 v164, v[144:147] offset:27648
	ds_read_b128 v[144:147], v163 offset:36960
	ds_read_b128 v[182:185], v163 offset:41568
	ds_read_b128 v[190:193], v154 offset:96
	ds_read_b128 v[198:201], v154 offset:4704
	ds_read_b128 v[206:209], v154 offset:9312
	ds_read_b128 v[214:217], v154 offset:13920
	s_waitcnt lgkmcnt(10)
	v_mfma_f32_32x32x16_bf16 v[80:95], v[194:197], v[148:151], v[80:95]
	v_mfma_f32_32x32x16_bf16 v[64:79], v[194:197], v[172:175], v[64:79]
	s_waitcnt lgkmcnt(9)
	v_mfma_f32_32x32x16_bf16 v[48:63], v[202:205], v[148:151], v[48:63]
	v_mfma_f32_32x32x16_bf16 v[32:47], v[202:205], v[172:175], v[32:47]
	s_waitcnt lgkmcnt(8)
	v_mfma_f32_32x32x16_bf16 v[16:31], v[210:213], v[148:151], v[16:31]
	v_mfma_f32_32x32x16_bf16 v[0:15], v[210:213], v[172:175], v[0:15]
	v_mfma_f32_32x32x16_bf16 v[112:127], v[186:189], v[148:151], v[112:127]
	v_mfma_f32_32x32x16_bf16 v[96:111], v[186:189], v[172:175], v[96:111]
	s_waitcnt vmcnt(3)
	ds_write_b128 v165, v[130:133]
	s_waitcnt vmcnt(2)
	ds_write_b128 v166, v[138:141]
	s_waitcnt lgkmcnt(4)
	v_mfma_f32_32x32x16_bf16 v[80:95], v[198:201], v[144:147], v[80:95]
	v_mfma_f32_32x32x16_bf16 v[64:79], v[198:201], v[182:185], v[64:79]
	s_waitcnt lgkmcnt(3)
	v_mfma_f32_32x32x16_bf16 v[48:63], v[206:209], v[144:147], v[48:63]
	v_mfma_f32_32x32x16_bf16 v[32:47], v[206:209], v[182:185], v[32:47]
	s_waitcnt lgkmcnt(2)
	v_mfma_f32_32x32x16_bf16 v[16:31], v[214:217], v[144:147], v[16:31]
	v_mfma_f32_32x32x16_bf16 v[0:15], v[214:217], v[182:185], v[0:15]
	v_mfma_f32_32x32x16_bf16 v[112:127], v[190:193], v[144:147], v[112:127]
	v_mfma_f32_32x32x16_bf16 v[96:111], v[190:193], v[182:185], v[96:111]
	s_waitcnt vmcnt(1)
	ds_write_b128 v167, v[158:161]
	s_waitcnt vmcnt(0)
	ds_write_b128 v168, v[134:137]
	s_waitcnt lgkmcnt(0)
	s_barrier
	ds_read_b128 v[130:133], v169
	ds_read_b128 v[134:137], v169 offset:32
	ds_read_b128 v[138:141], v169 offset:4608
	ds_read_b128 v[144:147], v169 offset:4640
	ds_read_b128 v[148:151], v155
	ds_read_b128 v[158:161], v155 offset:32
	ds_read_b128 v[172:175], v155 offset:4608
	ds_read_b128 v[182:185], v155 offset:4640
	ds_read_b128 v[186:189], v155 offset:9216
	ds_read_b128 v[190:193], v155 offset:9248
	ds_read_b128 v[194:197], v155 offset:13824
	ds_read_b128 v[198:201], v155 offset:13856
	s_waitcnt lgkmcnt(5)
	v_mfma_f32_32x32x16_bf16 v[80:95], v[172:175], v[130:133], v[80:95]
	v_mfma_f32_32x32x16_bf16 v[64:79], v[172:175], v[138:141], v[64:79]
	s_waitcnt lgkmcnt(3)
	v_mfma_f32_32x32x16_bf16 v[48:63], v[186:189], v[130:133], v[48:63]
	v_mfma_f32_32x32x16_bf16 v[32:47], v[186:189], v[138:141], v[32:47]
	s_waitcnt lgkmcnt(1)
	v_mfma_f32_32x32x16_bf16 v[16:31], v[194:197], v[130:133], v[16:31]
	v_mfma_f32_32x32x16_bf16 v[0:15], v[194:197], v[138:141], v[0:15]
	v_mfma_f32_32x32x16_bf16 v[112:127], v[148:151], v[130:133], v[112:127]
	v_mfma_f32_32x32x16_bf16 v[96:111], v[148:151], v[138:141], v[96:111]
	ds_read_b128 v[130:133], v169 offset:64
	ds_read_b128 v[138:141], v169 offset:4672
	ds_read_b128 v[148:151], v155 offset:64
	ds_read_b128 v[172:175], v155 offset:4672
	ds_read_b128 v[186:189], v155 offset:9280
	ds_read_b128 v[194:197], v155 offset:13888
	v_mfma_f32_32x32x16_bf16 v[80:95], v[182:185], v[134:137], v[80:95]
	v_mfma_f32_32x32x16_bf16 v[64:79], v[182:185], v[144:147], v[64:79]
	v_mfma_f32_32x32x16_bf16 v[48:63], v[190:193], v[134:137], v[48:63]
	v_mfma_f32_32x32x16_bf16 v[32:47], v[190:193], v[144:147], v[32:47]
	s_waitcnt lgkmcnt(6)
	v_mfma_f32_32x32x16_bf16 v[16:31], v[198:201], v[134:137], v[16:31]
	v_mfma_f32_32x32x16_bf16 v[0:15], v[198:201], v[144:147], v[0:15]
	v_mfma_f32_32x32x16_bf16 v[112:127], v[158:161], v[134:137], v[112:127]
	v_mfma_f32_32x32x16_bf16 v[96:111], v[158:161], v[144:147], v[96:111]
	ds_read_b128 v[134:137], v169 offset:96
	ds_read_b128 v[144:147], v169 offset:4704
	ds_read_b128 v[158:161], v155 offset:96
	ds_read_b128 v[182:185], v155 offset:4704
	ds_read_b128 v[190:193], v155 offset:9312
	ds_read_b128 v[198:201], v155 offset:13920
	s_waitcnt lgkmcnt(8)
	v_mfma_f32_32x32x16_bf16 v[80:95], v[172:175], v[130:133], v[80:95]
	v_mfma_f32_32x32x16_bf16 v[64:79], v[172:175], v[138:141], v[64:79]
	s_waitcnt lgkmcnt(7)
	v_mfma_f32_32x32x16_bf16 v[48:63], v[186:189], v[130:133], v[48:63]
	v_mfma_f32_32x32x16_bf16 v[32:47], v[186:189], v[138:141], v[32:47]
	s_waitcnt lgkmcnt(6)
	v_mfma_f32_32x32x16_bf16 v[16:31], v[194:197], v[130:133], v[16:31]
	v_mfma_f32_32x32x16_bf16 v[0:15], v[194:197], v[138:141], v[0:15]
	v_mfma_f32_32x32x16_bf16 v[112:127], v[148:151], v[130:133], v[112:127]
	v_mfma_f32_32x32x16_bf16 v[96:111], v[148:151], v[138:141], v[96:111]
	s_waitcnt lgkmcnt(2)
	v_mfma_f32_32x32x16_bf16 v[80:95], v[182:185], v[134:137], v[80:95]
	v_mfma_f32_32x32x16_bf16 v[64:79], v[182:185], v[144:147], v[64:79]
	s_waitcnt lgkmcnt(1)
	v_mfma_f32_32x32x16_bf16 v[48:63], v[190:193], v[134:137], v[48:63]
	v_mfma_f32_32x32x16_bf16 v[32:47], v[190:193], v[144:147], v[32:47]
	s_waitcnt lgkmcnt(0)
	v_mfma_f32_32x32x16_bf16 v[16:31], v[198:201], v[134:137], v[16:31]
	v_mfma_f32_32x32x16_bf16 v[0:15], v[198:201], v[144:147], v[0:15]
	v_mfma_f32_32x32x16_bf16 v[112:127], v[158:161], v[134:137], v[112:127]
	v_mfma_f32_32x32x16_bf16 v[96:111], v[158:161], v[144:147], v[96:111]
	s_mov_b32 s79, 0
	s_add_i32 s14, s4, s5
	s_cmp_lt_i32 s14, s6
	s_cbranch_scc0 .Lpfg_skip
	s_ashr_i32 s15, s14, 2
	s_and_b32 s16, s14, 3
	s_add_i32 s15, s15, s7
	s_lshl_b32 s15, s15, 19
	s_add_u32 s18, s82, s15
	s_addc_u32 s19, s83, 0
	s_lshl_b32 s16, s16, 19
	s_add_u32 s20, s80, s16
	s_addc_u32 s21, s81, 0
	v_lshrrev_b32_e32 v132, 3, v143
	v_lshlrev_b32_e32 v132, 11, v132
	v_and_b32_e32 v133, 7, v143
	v_lshl_add_u32 v132, v133, 4, v132
	global_load_dwordx4 v[210:213], v132, s[18:19]
	s_add_u32 s18, s18, 0x20000
	s_addc_u32 s19, s19, 0
	global_load_dwordx4 v[214:217], v132, s[18:19]
	s_add_u32 s18, s18, 0x20000
	s_addc_u32 s19, s19, 0
	global_load_dwordx4 v[218:221], v132, s[18:19]
	s_add_u32 s18, s18, 0x20000
	s_addc_u32 s19, s19, 0
	global_load_dwordx4 v[222:225], v132, s[18:19]
	global_load_dwordx4 v[226:229], v132, s[20:21]
	s_add_u32 s20, s20, 0x20000
	s_addc_u32 s21, s21, 0
	global_load_dwordx4 v[238:241], v132, s[20:21]
	s_add_u32 s20, s20, 0x20000
	s_addc_u32 s21, s21, 0
	global_load_dwordx4 v[242:245], v132, s[20:21]
	s_add_u32 s20, s20, 0x20000
	s_addc_u32 s21, s21, 0
	global_load_dwordx4 v[246:249], v132, s[20:21]
	s_mov_b32 s79, 1
.Lpfg_skip:
	v_add_u32_e32 v130, s1, v179
	s_movk_i32 s1, 0x7fff
	v_ashrrev_i32_e32 v131, 31, v130
	v_cmp_gt_i32_e32 vcc, s1, v130
	v_lshl_add_u64 v[134:135], v[130:131], 1, s[86:87]
	s_nop 5
	v_bfe_u32 v130, v112, 16, 1
	v_add3_u32 v112, v112, v130, s24
	s_barrier
	ds_write_b16_d16_hi v156, v112
	v_bfe_u32 v112, v113, 16, 1
	v_add3_u32 v112, v113, v112, s24
	ds_write_b16_d16_hi v156, v112 offset:144
	v_bfe_u32 v112, v114, 16, 1
	v_add3_u32 v112, v114, v112, s24
	ds_write_b16_d16_hi v156, v112 offset:288
	v_bfe_u32 v112, v115, 16, 1
	v_add3_u32 v112, v115, v112, s24
	ds_write_b16_d16_hi v156, v112 offset:432
	v_bfe_u32 v112, v116, 16, 1
	v_add3_u32 v112, v116, v112, s24
	ds_write_b16_d16_hi v156, v112 offset:1152
	v_bfe_u32 v112, v117, 16, 1
	v_add3_u32 v112, v117, v112, s24
	ds_write_b16_d16_hi v156, v112 offset:1296
	v_bfe_u32 v112, v118, 16, 1
	v_add3_u32 v112, v118, v112, s24
	ds_write_b16_d16_hi v156, v112 offset:1440
	v_bfe_u32 v112, v119, 16, 1
	v_add3_u32 v112, v119, v112, s24
	ds_write_b16_d16_hi v156, v112 offset:1584
	v_bfe_u32 v112, v120, 16, 1
	v_add3_u32 v112, v120, v112, s24
	ds_write_b16_d16_hi v156, v112 offset:2304
	v_bfe_u32 v112, v121, 16, 1
	v_add3_u32 v112, v121, v112, s24
	ds_write_b16_d16_hi v156, v112 offset:2448
	v_bfe_u32 v112, v122, 16, 1
	v_add3_u32 v112, v122, v112, s24
	ds_write_b16_d16_hi v156, v112 offset:2592
	v_bfe_u32 v112, v123, 16, 1
	v_add3_u32 v112, v123, v112, s24
	ds_write_b16_d16_hi v156, v112 offset:2736
	v_bfe_u32 v112, v124, 16, 1
	v_add3_u32 v112, v124, v112, s24
	ds_write_b16_d16_hi v156, v112 offset:3456
	v_bfe_u32 v112, v125, 16, 1
	v_add3_u32 v112, v125, v112, s24
	ds_write_b16_d16_hi v156, v112 offset:3600
	v_bfe_u32 v112, v126, 16, 1
	v_add3_u32 v112, v126, v112, s24
	ds_write_b16_d16_hi v156, v112 offset:3744
	v_bfe_u32 v112, v127, 16, 1
	v_add3_u32 v112, v127, v112, s24
	ds_write_b16_d16_hi v156, v112 offset:3888
	v_bfe_u32 v112, v96, 16, 1
	v_add3_u32 v96, v96, v112, s24
	ds_write_b16_d16_hi v156, v96 offset:64
	v_bfe_u32 v96, v97, 16, 1
	v_add3_u32 v96, v97, v96, s24
	ds_write_b16_d16_hi v156, v96 offset:208
	v_bfe_u32 v96, v98, 16, 1
	v_add3_u32 v96, v98, v96, s24
	ds_write_b16_d16_hi v156, v96 offset:352
	v_bfe_u32 v96, v99, 16, 1
	v_add3_u32 v96, v99, v96, s24
	ds_write_b16_d16_hi v156, v96 offset:496
	v_bfe_u32 v96, v100, 16, 1
	v_add3_u32 v96, v100, v96, s24
	ds_write_b16_d16_hi v156, v96 offset:1216
	v_bfe_u32 v96, v101, 16, 1
	v_add3_u32 v96, v101, v96, s24
	ds_write_b16_d16_hi v156, v96 offset:1360
	v_bfe_u32 v96, v102, 16, 1
	v_add3_u32 v96, v102, v96, s24
	ds_write_b16_d16_hi v156, v96 offset:1504
	v_bfe_u32 v96, v103, 16, 1
	v_add3_u32 v96, v103, v96, s24
	ds_write_b16_d16_hi v156, v96 offset:1648
	v_bfe_u32 v96, v104, 16, 1
	v_add3_u32 v96, v104, v96, s24
	ds_write_b16_d16_hi v156, v96 offset:2368
	v_bfe_u32 v96, v105, 16, 1
	v_add3_u32 v96, v105, v96, s24
	ds_write_b16_d16_hi v156, v96 offset:2512
	v_bfe_u32 v96, v106, 16, 1
	v_add3_u32 v96, v106, v96, s24
	ds_write_b16_d16_hi v156, v96 offset:2656
	v_bfe_u32 v96, v107, 16, 1
	v_add3_u32 v96, v107, v96, s24
	ds_write_b16_d16_hi v156, v96 offset:2800
	v_bfe_u32 v96, v108, 16, 1
	v_add3_u32 v96, v108, v96, s24
	ds_write_b16_d16_hi v156, v96 offset:3520
	v_bfe_u32 v96, v109, 16, 1
	v_add3_u32 v96, v109, v96, s24
	ds_write_b16_d16_hi v156, v96 offset:3664
	v_bfe_u32 v96, v110, 16, 1
	v_add3_u32 v96, v110, v96, s24
	ds_write_b16_d16_hi v156, v96 offset:3808
	v_bfe_u32 v96, v111, 16, 1
	v_add_u32_e32 v136, s0, v153
	v_add3_u32 v96, v111, v96, s24
	ds_write_b16_d16_hi v156, v96 offset:3952
	s_and_saveexec_b64 s[0:1], vcc
	s_cbranch_execz .Lgo_242
	ds_read_b128 v[96:99], v170
	v_or_b32_e32 v100, v136, v157
	v_mad_i64_i32 v[100:101], s[10:11], v100, s88, v[134:135]
	s_waitcnt lgkmcnt(0)
	global_store_dwordx4 v[100:101], v[96:99], off
	ds_read_b128 v[96:99], v170 offset:1152
	v_or_b32_e32 v100, v136, v171
	v_mad_i64_i32 v[100:101], s[10:11], v100, s88, v[134:135]
	s_waitcnt lgkmcnt(0)
	global_store_dwordx4 v[100:101], v[96:99], off
	ds_read_b128 v[96:99], v170 offset:2304
	v_or_b32_e32 v100, v136, v252
	v_mad_i64_i32 v[100:101], s[10:11], v100, s88, v[134:135]
	s_waitcnt lgkmcnt(0)
	global_store_dwordx4 v[100:101], v[96:99], off
	ds_read_b128 v[96:99], v170 offset:3456
	v_or_b32_e32 v100, v136, v181
	v_mad_i64_i32 v[100:101], s[10:11], v100, s88, v[134:135]
	s_waitcnt lgkmcnt(0)
	global_store_dwordx4 v[100:101], v[96:99], off
